# index top-256 threshold search exits once both queries have exactly 256 keys above T (exact, selection unchanged)
# speedup vs baseline: 1.0072x; 1.0072x over previous
; __device__ __forceinline__ void dsa_index_unit(const Ctx& c, int l, int b, int qb) {
;     ...
;         unsigned key[64];
; #pragma unroll
;         for (int kt = 0; kt < 64; ++kt) { const unsigned kv = sk[kt * 64 + lane]; key[kt] = (kt <= qb) ? kv : 0u; }
.Lix0_done:
	s_waitcnt vmcnt(0)
	ds_read2st64_b32 v[8:9], v67 offset1:1
	ds_read2st64_b32 v[6:7], v67 offset0:2 offset1:3
	ds_read2st64_b32 v[4:5], v67 offset0:4 offset1:5
	ds_read2st64_b32 v[2:3], v67 offset0:6 offset1:7
	ds_read2st64_b32 v[0:1], v67 offset0:8 offset1:9
	ds_read2st64_b32 v[10:11], v67 offset0:10 offset1:11
	ds_read2st64_b32 v[102:103], v67 offset0:62 offset1:63
	v_readlane_b32 s0, v250, 22
	v_readlane_b32 s1, v250, 23
	s_mov_b64 s[20:21], s[90:91]
	s_waitcnt lgkmcnt(2)
	v_cndmask_b32_e64 v101, v1, 0, s[0:1]
	v_readlane_b32 s0, v250, 16
	v_readlane_b32 s1, v250, 17
	s_waitcnt lgkmcnt(1)
	s_nop 0
	v_cndmask_b32_e64 v99, v10, 0, s[0:1]
	v_readlane_b32 s0, v250, 18
	v_readlane_b32 s1, v250, 19
	s_nop 1
	v_cndmask_b32_e64 v98, v11, 0, s[0:1]
	ds_read2st64_b32 v[10:11], v67 offset0:12 offset1:13
	v_readlane_b32 s0, v250, 26
	v_readlane_b32 s1, v250, 27
	s_waitcnt lgkmcnt(0)
	s_nop 0
	v_cndmask_b32_e64 v96, v10, 0, s[0:1]
	v_readlane_b32 s0, v250, 28
	v_readlane_b32 s1, v250, 29
	s_nop 1
	v_cndmask_b32_e64 v95, v11, 0, s[0:1]
	ds_read2st64_b32 v[10:11], v67 offset0:14 offset1:15
	v_readlane_b32 s0, v250, 30
	v_readlane_b32 s1, v250, 31
	s_waitcnt lgkmcnt(0)
	s_nop 0
	v_cndmask_b32_e64 v93, v10, 0, s[0:1]
	v_readlane_b32 s0, v250, 24
	v_readlane_b32 s1, v250, 25
	s_nop 1
	v_cndmask_b32_e64 v92, v11, 0, s[0:1]
	ds_read2st64_b32 v[10:11], v67 offset0:16 offset1:17
	v_readlane_b32 s0, v250, 40
	v_readlane_b32 s1, v250, 41
	s_waitcnt lgkmcnt(0)
	s_nop 0
	v_cndmask_b32_e64 v90, v10, 0, s[0:1]
	v_readlane_b32 s0, v250, 32
	v_readlane_b32 s1, v250, 33
	s_nop 1
	v_cndmask_b32_e64 v89, v11, 0, s[0:1]
	ds_read2st64_b32 v[10:11], v67 offset0:18 offset1:19
	v_readlane_b32 s0, v250, 10
	v_readlane_b32 s1, v250, 11
	s_waitcnt lgkmcnt(0)
	s_nop 0
	v_cndmask_b32_e64 v85, v10, 0, s[0:1]
	v_readlane_b32 s0, v250, 14
	v_readlane_b32 s1, v250, 15
	s_nop 1
	v_cndmask_b32_e64 v84, v11, 0, s[0:1]
	ds_read2st64_b32 v[10:11], v67 offset0:20 offset1:21
	v_readlane_b32 s0, v250, 34
	v_readlane_b32 s1, v250, 35
	s_waitcnt lgkmcnt(0)
	s_nop 0
	v_cndmask_b32_e64 v83, v10, 0, s[0:1]
	v_readlane_b32 s0, v250, 36
	v_readlane_b32 s1, v250, 37
	s_nop 1
	v_cndmask_b32_e64 v81, v11, 0, s[0:1]
	ds_read2st64_b32 v[10:11], v67 offset0:22 offset1:23
	v_readlane_b32 s0, v250, 38
	v_readlane_b32 s1, v250, 39
	s_waitcnt lgkmcnt(0)
	s_nop 0
	v_cndmask_b32_e64 v80, v10, 0, s[0:1]
	v_readlane_b32 s0, v252, 17
	v_readlane_b32 s1, v252, 18
	s_nop 1
	v_cndmask_b32_e64 v78, v11, 0, s[0:1]
	ds_read2st64_b32 v[10:11], v67 offset0:24 offset1:25
	v_readlane_b32 s0, v252, 19
	v_readlane_b32 s1, v252, 20
	s_waitcnt lgkmcnt(0)
	s_nop 0
	v_cndmask_b32_e64 v77, v10, 0, s[0:1]
	v_readlane_b32 s0, v252, 21
	v_readlane_b32 s1, v252, 22
	s_nop 1
	v_cndmask_b32_e64 v76, v11, 0, s[0:1]
	ds_read2st64_b32 v[10:11], v67 offset0:26 offset1:27
	v_readlane_b32 s0, v252, 23
	v_readlane_b32 s1, v252, 24
	s_waitcnt lgkmcnt(0)
	s_nop 0
	v_cndmask_b32_e64 v61, v10, 0, s[0:1]
	v_readlane_b32 s0, v252, 25
	v_readlane_b32 s1, v252, 26
	s_nop 1
	v_cndmask_b32_e64 v60, v11, 0, s[0:1]
	ds_read2st64_b32 v[10:11], v67 offset0:28 offset1:29
	v_readlane_b32 s0, v252, 27
	v_readlane_b32 s1, v252, 28
	s_waitcnt lgkmcnt(0)
	s_nop 0
	v_cndmask_b32_e64 v58, v10, 0, s[0:1]
	v_readlane_b32 s0, v252, 29
	v_readlane_b32 s1, v252, 30
	s_nop 1
	v_cndmask_b32_e64 v57, v11, 0, s[0:1]
	ds_read2st64_b32 v[10:11], v67 offset0:30 offset1:31
	v_readlane_b32 s0, v252, 31
	v_readlane_b32 s1, v252, 32
	s_waitcnt lgkmcnt(0)
	s_nop 0
	v_cndmask_b32_e64 v55, v10, 0, s[0:1]
	v_readlane_b32 s0, v252, 33
	v_readlane_b32 s1, v252, 34
	s_nop 1
	v_cndmask_b32_e64 v54, v11, 0, s[0:1]
	ds_read2st64_b32 v[10:11], v67 offset0:32 offset1:33
	v_readlane_b32 s0, v252, 35
	v_readlane_b32 s1, v252, 36
	s_waitcnt lgkmcnt(0)
	s_nop 0
	v_cndmask_b32_e64 v52, v10, 0, s[0:1]
	v_readlane_b32 s0, v252, 37
	v_readlane_b32 s1, v252, 38
	s_nop 1
	v_cndmask_b32_e64 v51, v11, 0, s[0:1]
	ds_read2st64_b32 v[10:11], v67 offset0:34 offset1:35
	v_readlane_b32 s0, v252, 39
	v_readlane_b32 s1, v252, 40
	s_waitcnt lgkmcnt(0)
	s_nop 0
	v_cndmask_b32_e64 v49, v10, 0, s[0:1]
	v_readlane_b32 s0, v252, 41
	v_readlane_b32 s1, v252, 42
	s_nop 1
	v_cndmask_b32_e64 v48, v11, 0, s[0:1]
	ds_read2st64_b32 v[10:11], v67 offset0:36 offset1:37
	v_readlane_b32 s0, v252, 43
	v_readlane_b32 s1, v252, 44
	s_waitcnt lgkmcnt(0)
	s_nop 0
	v_cndmask_b32_e64 v46, v10, 0, s[0:1]
	v_readlane_b32 s0, v252, 45
	v_readlane_b32 s1, v252, 46
	s_nop 1
	v_cndmask_b32_e64 v45, v11, 0, s[0:1]
	ds_read2st64_b32 v[10:11], v67 offset0:38 offset1:39
	v_readlane_b32 s0, v252, 47
	v_readlane_b32 s1, v252, 48
	s_waitcnt lgkmcnt(0)
	s_nop 0
	v_cndmask_b32_e64 v43, v10, 0, s[0:1]
	v_readlane_b32 s0, v252, 49
	v_readlane_b32 s1, v252, 50
	s_nop 1
	v_cndmask_b32_e64 v42, v11, 0, s[0:1]
	ds_read2st64_b32 v[10:11], v67 offset0:40 offset1:41
	v_readlane_b32 s0, v252, 51
	v_readlane_b32 s1, v252, 52
	s_waitcnt lgkmcnt(0)
	s_nop 0
	v_cndmask_b32_e64 v40, v10, 0, s[0:1]
	v_readlane_b32 s0, v252, 53
	v_readlane_b32 s1, v252, 54
	s_nop 1
	v_cndmask_b32_e64 v39, v11, 0, s[0:1]
	ds_read2st64_b32 v[10:11], v67 offset0:42 offset1:43
	v_readlane_b32 s0, v252, 55
	v_readlane_b32 s1, v252, 56
	s_waitcnt lgkmcnt(0)
	s_nop 0
	v_cndmask_b32_e64 v38, v10, 0, s[0:1]
	v_readlane_b32 s0, v252, 57
	v_readlane_b32 s1, v252, 58
	s_nop 1
	v_cndmask_b32_e64 v36, v11, 0, s[0:1]
	ds_read2st64_b32 v[10:11], v67 offset0:44 offset1:45
	v_readlane_b32 s0, v252, 59
	v_readlane_b32 s1, v252, 60
	s_waitcnt lgkmcnt(0)
; __device__ __forceinline__ int half_sum_i(int v, int hf) { v = row16_sum_i(v); const int a = __builtin_amdgcn_readlane(v, 0) + __builtin_amdgcn_readlane(v, 16), b = __builtin_amdgcn_readlane(v, 32) + __builtin_amdgcn_readlane(v, 48); return hf ? b : a; }
; __device__ __forceinline__ void dsa_index_unit(const Ctx& c, int l, int b, int qb) {
;     ...
;         for (int kt = 0; kt < 64; ++kt) { const unsigned kv = sk[kt * 64 + lane]; key[kt] = (kt <= qb) ? kv : 0u; }
;         unsigned T = 0u;
; #pragma unroll 1
;     ...
;             const unsigned cand = T | (1u << bit);
;             int cnt = 0;
; #pragma unroll
;             for (int kt = 0; kt < 64; ++kt) cnt += (key[kt] >= cand) ? 1 : 0;
;             cnt = half_sum_i(cnt, hf);
;             if (cnt >= 256) T = cand;
	s_nop 0
	v_cndmask_b32_e64 v35, v10, 0, s[0:1]
	v_readlane_b32 s0, v252, 61
	v_readlane_b32 s1, v252, 62
	s_nop 1
	v_cndmask_b32_e64 v33, v11, 0, s[0:1]
	ds_read2st64_b32 v[10:11], v67 offset0:46 offset1:47
	v_readlane_b32 s0, v252, 63
	v_readlane_b32 s1, v253, 0
	s_waitcnt lgkmcnt(0)
	s_nop 0
	v_cndmask_b32_e64 v32, v10, 0, s[0:1]
	v_readlane_b32 s0, v253, 1
	v_readlane_b32 s1, v253, 2
	s_nop 1
	v_cndmask_b32_e64 v30, v11, 0, s[0:1]
	ds_read2st64_b32 v[10:11], v67 offset0:48 offset1:49
	v_readlane_b32 s0, v253, 3
	v_readlane_b32 s1, v253, 4
	s_waitcnt lgkmcnt(0)
	s_nop 0
	v_cndmask_b32_e64 v29, v10, 0, s[0:1]
	v_readlane_b32 s0, v253, 5
	v_readlane_b32 s1, v253, 6
	s_nop 1
	v_cndmask_b32_e64 v27, v11, 0, s[0:1]
	ds_read2st64_b32 v[10:11], v67 offset0:50 offset1:51
	v_readlane_b32 s0, v253, 7
	v_readlane_b32 s1, v253, 8
	s_waitcnt lgkmcnt(0)
	s_nop 0
	v_cndmask_b32_e64 v26, v10, 0, s[0:1]
	v_readlane_b32 s0, v253, 9
	v_readlane_b32 s1, v253, 10
	s_nop 1
	v_cndmask_b32_e64 v24, v11, 0, s[0:1]
	ds_read2st64_b32 v[10:11], v67 offset0:52 offset1:53
	v_readlane_b32 s0, v253, 11
	v_readlane_b32 s1, v253, 12
	s_waitcnt lgkmcnt(0)
	s_nop 0
	v_cndmask_b32_e64 v22, v10, 0, s[0:1]
	v_readlane_b32 s0, v253, 13
	v_readlane_b32 s1, v253, 14
	s_nop 1
	v_cndmask_b32_e64 v21, v11, 0, s[0:1]
	ds_read2st64_b32 v[10:11], v67 offset0:54 offset1:55
	v_readlane_b32 s0, v253, 15
	v_readlane_b32 s1, v253, 16
	s_waitcnt lgkmcnt(0)
	s_nop 0
	v_cndmask_b32_e64 v20, v10, 0, s[0:1]
	v_readlane_b32 s0, v253, 17
	v_readlane_b32 s1, v253, 18
	s_nop 1
	v_cndmask_b32_e64 v19, v11, 0, s[0:1]
	ds_read2st64_b32 v[10:11], v67 offset0:56 offset1:57
	v_readlane_b32 s0, v253, 19
	v_readlane_b32 s1, v253, 20
	s_waitcnt lgkmcnt(0)
	s_nop 0
	v_cndmask_b32_e64 v18, v10, 0, s[0:1]
	v_readlane_b32 s0, v253, 21
	v_readlane_b32 s1, v253, 22
	s_nop 1
	v_cndmask_b32_e64 v16, v11, 0, s[0:1]
	ds_read2st64_b32 v[10:11], v67 offset0:58 offset1:59
	v_readlane_b32 s0, v253, 23
	v_readlane_b32 s1, v253, 24
	s_waitcnt lgkmcnt(0)
	s_nop 0
	v_cndmask_b32_e64 v15, v10, 0, s[0:1]
	v_readlane_b32 s0, v253, 25
	v_readlane_b32 s1, v253, 26
	s_nop 1
	v_cndmask_b32_e64 v14, v11, 0, s[0:1]
	ds_read2st64_b32 v[10:11], v67 offset0:60 offset1:61
	v_readlane_b32 s0, v253, 27
	v_readlane_b32 s1, v253, 28
	s_waitcnt lgkmcnt(0)
	s_nop 0
	v_cndmask_b32_e64 v13, v10, 0, s[0:1]
	v_readlane_b32 s0, v253, 29
	v_readlane_b32 s1, v253, 30
	v_mov_b32_e32 v10, 0
	s_nop 0
	v_cndmask_b32_e64 v12, v11, 0, s[0:1]
	v_readlane_b32 s0, v253, 31
	v_readlane_b32 s1, v253, 32
	s_nop 1
	v_cndmask_b32_e64 v11, v102, 0, s[0:1]
	v_readlane_b32 s0, v253, 33
	v_readlane_b32 s1, v253, 34
	s_nop 1
	v_cndmask_b32_e64 v1, 0, v103, s[0:1]
	s_mov_b32 s0, 31
	s_mov_b64 s[46:47], 0
.LBB0_1109:
	v_lshl_or_b32 v23, 1, s0, v10
	v_cmp_ge_u32_e32 vcc, v9, v23
	s_add_i32 s0, s0, -1
	s_nop 0
	v_cndmask_b32_e64 v25, 0, 1, vcc
	v_cmp_ge_u32_e32 vcc, v8, v23
	s_nop 1
	v_addc_co_u32_e32 v25, vcc, 0, v25, vcc
	v_cmp_ge_u32_e32 vcc, v6, v23
	s_nop 1
	v_cndmask_b32_e64 v28, 0, 1, vcc
	v_cmp_ge_u32_e32 vcc, v7, v23
	s_nop 1
	v_addc_co_u32_e32 v25, vcc, v25, v28, vcc
	v_cmp_ge_u32_e32 vcc, v4, v23
	s_nop 1
	v_cndmask_b32_e64 v28, 0, 1, vcc
	v_cmp_ge_u32_e32 vcc, v5, v23
	s_nop 1
	v_addc_co_u32_e32 v25, vcc, v25, v28, vcc
	v_cmp_ge_u32_e32 vcc, v2, v23
	s_nop 1
	v_cndmask_b32_e64 v28, 0, 1, vcc
	v_cmp_ge_u32_e32 vcc, v3, v23
	s_nop 1
	v_addc_co_u32_e32 v25, vcc, v25, v28, vcc
	v_cmp_ge_u32_e32 vcc, v0, v23
	s_nop 1
	v_cndmask_b32_e64 v28, 0, 1, vcc
	v_cmp_ge_u32_e32 vcc, v101, v23
	s_nop 1
	v_addc_co_u32_e32 v25, vcc, v25, v28, vcc
	v_cmp_ge_u32_e32 vcc, v99, v23
	s_nop 1
	v_cndmask_b32_e64 v28, 0, 1, vcc
	v_cmp_ge_u32_e32 vcc, v98, v23
	s_nop 1
	v_addc_co_u32_e32 v25, vcc, v25, v28, vcc
	v_cmp_ge_u32_e32 vcc, v96, v23
	s_nop 1
	v_cndmask_b32_e64 v28, 0, 1, vcc
	v_cmp_ge_u32_e32 vcc, v95, v23
	s_nop 1
	v_addc_co_u32_e32 v25, vcc, v25, v28, vcc
	v_cmp_ge_u32_e32 vcc, v93, v23
	s_nop 1
	v_cndmask_b32_e64 v28, 0, 1, vcc
	v_cmp_ge_u32_e32 vcc, v92, v23
	s_nop 1
	v_addc_co_u32_e32 v25, vcc, v25, v28, vcc
	v_cmp_ge_u32_e32 vcc, v90, v23
	s_nop 1
	v_cndmask_b32_e64 v28, 0, 1, vcc
	v_cmp_ge_u32_e32 vcc, v89, v23
	s_nop 1
	v_addc_co_u32_e32 v25, vcc, v25, v28, vcc
	v_cmp_ge_u32_e32 vcc, v85, v23
	s_nop 1
	v_cndmask_b32_e64 v28, 0, 1, vcc
	v_cmp_ge_u32_e32 vcc, v84, v23
	s_nop 1
	v_addc_co_u32_e32 v25, vcc, v25, v28, vcc
	v_cmp_ge_u32_e32 vcc, v83, v23
	s_nop 1
	v_cndmask_b32_e64 v28, 0, 1, vcc
	v_cmp_ge_u32_e32 vcc, v81, v23
	s_nop 1
	v_addc_co_u32_e32 v25, vcc, v25, v28, vcc
	v_cmp_ge_u32_e32 vcc, v80, v23
	s_nop 1
	v_cndmask_b32_e64 v28, 0, 1, vcc
	v_cmp_ge_u32_e32 vcc, v78, v23
	s_nop 1
	v_addc_co_u32_e32 v25, vcc, v25, v28, vcc
	v_cmp_ge_u32_e32 vcc, v77, v23
	s_nop 1
	v_cndmask_b32_e64 v28, 0, 1, vcc
	v_cmp_ge_u32_e32 vcc, v76, v23
	s_nop 1
	v_addc_co_u32_e32 v25, vcc, v25, v28, vcc
	v_cmp_ge_u32_e32 vcc, v61, v23
	s_nop 1
	v_cndmask_b32_e64 v28, 0, 1, vcc
	v_cmp_ge_u32_e32 vcc, v60, v23
	s_nop 1
	v_addc_co_u32_e32 v25, vcc, v25, v28, vcc
	v_cmp_ge_u32_e32 vcc, v58, v23
	s_nop 1
	v_cndmask_b32_e64 v28, 0, 1, vcc
	v_cmp_ge_u32_e32 vcc, v57, v23
	s_nop 1
	v_addc_co_u32_e32 v25, vcc, v25, v28, vcc
	v_cmp_ge_u32_e32 vcc, v55, v23
	s_nop 1
	v_cndmask_b32_e64 v28, 0, 1, vcc
	v_cmp_ge_u32_e32 vcc, v54, v23
	s_nop 1
	v_addc_co_u32_e32 v25, vcc, v25, v28, vcc
	v_cmp_ge_u32_e32 vcc, v52, v23
	s_nop 1
	v_cndmask_b32_e64 v28, 0, 1, vcc
	v_cmp_ge_u32_e32 vcc, v51, v23
	s_nop 1
	v_addc_co_u32_e32 v25, vcc, v25, v28, vcc
	v_cmp_ge_u32_e32 vcc, v49, v23
	s_nop 1
	v_cndmask_b32_e64 v28, 0, 1, vcc
	v_cmp_ge_u32_e32 vcc, v48, v23
	s_nop 1
	v_addc_co_u32_e32 v25, vcc, v25, v28, vcc
; __device__ __forceinline__ int half_sum_i(int v, int hf) { v = row16_sum_i(v); const int a = __builtin_amdgcn_readlane(v, 0) + __builtin_amdgcn_readlane(v, 16), b = __builtin_amdgcn_readlane(v, 32) + __builtin_amdgcn_readlane(v, 48); return hf ? b : a; }
; __device__ __forceinline__ void dsa_index_unit(const Ctx& c, int l, int b, int qb) {
;     ...
;         unsigned T = 0u;
; #pragma unroll 1
;     ...
;             const unsigned cand = T | (1u << bit);
;             int cnt = 0;
; #pragma unroll
;             for (int kt = 0; kt < 64; ++kt) cnt += (key[kt] >= cand) ? 1 : 0;
;             cnt = half_sum_i(cnt, hf);
;             if (cnt >= 256) T = cand;
;         }
;         int cg = 0;
; #pragma unroll
;         for (int kt = 0; kt < 64; ++kt) cg += (key[kt] > T) ? 1 : 0;
;         cg = half_sum_i(cg, hf);
	v_cmp_ge_u32_e32 vcc, v46, v23
	s_nop 1
	v_cndmask_b32_e64 v28, 0, 1, vcc
	v_cmp_ge_u32_e32 vcc, v45, v23
	s_nop 1
	v_addc_co_u32_e32 v25, vcc, v25, v28, vcc
	v_cmp_ge_u32_e32 vcc, v43, v23
	s_nop 1
	v_cndmask_b32_e64 v28, 0, 1, vcc
	v_cmp_ge_u32_e32 vcc, v42, v23
	s_nop 1
	v_addc_co_u32_e32 v25, vcc, v25, v28, vcc
	v_cmp_ge_u32_e32 vcc, v40, v23
	s_nop 1
	v_cndmask_b32_e64 v28, 0, 1, vcc
	v_cmp_ge_u32_e32 vcc, v39, v23
	s_nop 1
	v_addc_co_u32_e32 v25, vcc, v25, v28, vcc
	v_cmp_ge_u32_e32 vcc, v38, v23
	s_nop 1
	v_cndmask_b32_e64 v28, 0, 1, vcc
	v_cmp_ge_u32_e32 vcc, v36, v23
	s_nop 1
	v_addc_co_u32_e32 v25, vcc, v25, v28, vcc
	v_cmp_ge_u32_e32 vcc, v35, v23
	s_nop 1
	v_cndmask_b32_e64 v28, 0, 1, vcc
	v_cmp_ge_u32_e32 vcc, v33, v23
	s_nop 1
	v_addc_co_u32_e32 v25, vcc, v25, v28, vcc
	v_cmp_ge_u32_e32 vcc, v32, v23
	s_nop 1
	v_cndmask_b32_e64 v28, 0, 1, vcc
	v_cmp_ge_u32_e32 vcc, v30, v23
	s_nop 1
	v_addc_co_u32_e32 v25, vcc, v25, v28, vcc
	v_cmp_ge_u32_e32 vcc, v29, v23
	s_nop 1
	v_cndmask_b32_e64 v28, 0, 1, vcc
	v_cmp_ge_u32_e32 vcc, v27, v23
	s_nop 1
	v_addc_co_u32_e32 v25, vcc, v25, v28, vcc
	v_cmp_ge_u32_e32 vcc, v26, v23
	s_nop 1
	v_cndmask_b32_e64 v28, 0, 1, vcc
	v_cmp_ge_u32_e32 vcc, v24, v23
	s_nop 1
	v_addc_co_u32_e32 v25, vcc, v25, v28, vcc
	v_cmp_ge_u32_e32 vcc, v22, v23
	s_nop 1
	v_cndmask_b32_e64 v28, 0, 1, vcc
	v_cmp_ge_u32_e32 vcc, v21, v23
	s_nop 1
	v_addc_co_u32_e32 v25, vcc, v25, v28, vcc
	v_cmp_ge_u32_e32 vcc, v20, v23
	s_nop 1
	v_cndmask_b32_e64 v28, 0, 1, vcc
	v_cmp_ge_u32_e32 vcc, v19, v23
	s_nop 1
	v_addc_co_u32_e32 v25, vcc, v25, v28, vcc
	v_cmp_ge_u32_e32 vcc, v18, v23
	s_nop 1
	v_cndmask_b32_e64 v28, 0, 1, vcc
	v_cmp_ge_u32_e32 vcc, v16, v23
	s_nop 1
	v_addc_co_u32_e32 v25, vcc, v25, v28, vcc
	v_cmp_ge_u32_e32 vcc, v15, v23
	s_nop 1
	v_cndmask_b32_e64 v28, 0, 1, vcc
	v_cmp_ge_u32_e32 vcc, v14, v23
	s_nop 1
	v_addc_co_u32_e32 v25, vcc, v25, v28, vcc
	v_cmp_ge_u32_e32 vcc, v13, v23
	s_nop 1
	v_cndmask_b32_e64 v28, 0, 1, vcc
	v_cmp_ge_u32_e32 vcc, v12, v23
	s_nop 1
	v_addc_co_u32_e32 v25, vcc, v25, v28, vcc
	v_cmp_ge_u32_e32 vcc, v11, v23
	s_nop 1
	v_cndmask_b32_e64 v28, 0, 1, vcc
	v_cmp_ge_u32_e32 vcc, v1, v23
	s_nop 1
	v_addc_co_u32_e32 v25, vcc, v25, v28, vcc
	s_nop 1
	v_add_u32_dpp v25, v25, v25 quad_perm:[1,0,3,2] row_mask:0xf bank_mask:0xf bound_ctrl:1
	s_nop 1
	v_add_u32_dpp v25, v25, v25 quad_perm:[2,3,0,1] row_mask:0xf bank_mask:0xf bound_ctrl:1
	s_nop 1
	v_add_u32_dpp v25, v25, v25 row_half_mirror row_mask:0xf bank_mask:0xf bound_ctrl:1
	s_nop 1
	v_add_u32_dpp v25, v25, v25 row_mirror row_mask:0xf bank_mask:0xf bound_ctrl:1
	s_nop 0
	v_readlane_b32 s1, v25, 0
	v_readlane_b32 s3, v25, 16
	s_add_i32 s1, s3, s1
	v_readlane_b32 s3, v25, 32
	v_readlane_b32 s4, v25, 48
	s_add_i32 s3, s4, s3
	v_mov_b32_e32 v25, s3
	v_mov_b32_e32 v28, s1
	v_cndmask_b32_e64 v25, v25, v28, s[6:7]
	s_movk_i32 s1, 0xff
	v_cmp_lt_i32_e32 vcc, s1, v25
	s_movk_i32 s45, 0x100
	s_nop 0
	v_cndmask_b32_e32 v10, v10, v23, vcc
	v_cmp_eq_u32_e64 s[48:49], s45, v25
	s_nop 3
	s_or_b64 s[46:47], s[46:47], s[48:49]
	s_cmp_eq_u64 s[46:47], exec
	s_cbranch_scc1 .Lb0_bitdone
	s_cmp_eq_u32 s0, -1
	s_cbranch_scc0 .LBB0_1109
.Lb0_bitdone:
	v_cmp_gt_u32_e32 vcc, v9, v10
	v_cmp_gt_u32_e64 s[10:11], v8, v10
	v_cmp_gt_u32_e64 s[8:9], v7, v10
	v_cndmask_b32_e64 v113, 0, 1, vcc
	v_addc_co_u32_e64 v23, vcc, 0, v113, s[10:11]
	v_cmp_gt_u32_e32 vcc, v6, v10
	v_cmp_gt_u32_e64 s[0:1], v5, v10
	v_cmp_gt_u32_e64 s[4:5], v3, v10
	v_cndmask_b32_e64 v112, 0, 1, vcc
	v_addc_co_u32_e64 v23, vcc, v23, v112, s[8:9]
	v_cmp_gt_u32_e32 vcc, v4, v10
	v_cmp_gt_u32_e64 s[12:13], v101, v10
	v_cmp_gt_u32_e64 s[96:97], v98, v10
	v_cndmask_b32_e64 v111, 0, 1, vcc
	v_addc_co_u32_e64 v23, vcc, v23, v111, s[0:1]
	v_cmp_gt_u32_e32 vcc, v2, v10
	v_cmp_gt_u32_e64 s[94:95], v95, v10
	v_cmp_gt_u32_e64 s[92:93], v92, v10
	v_cndmask_b32_e64 v110, 0, 1, vcc
	v_addc_co_u32_e64 v23, vcc, v23, v110, s[4:5]
	v_cmp_gt_u32_e32 vcc, v0, v10
	v_cmp_gt_u32_e64 s[90:91], v89, v10
	v_cmp_gt_u32_e64 s[88:89], v84, v10
	v_cndmask_b32_e64 v109, 0, 1, vcc
	v_addc_co_u32_e64 v23, vcc, v23, v109, s[12:13]
	v_cmp_gt_u32_e32 vcc, v99, v10
	v_cmp_gt_u32_e64 s[86:87], v81, v10
	v_cmp_gt_u32_e64 s[84:85], v78, v10
	v_cndmask_b32_e64 v108, 0, 1, vcc
	v_addc_co_u32_e64 v23, vcc, v23, v108, s[96:97]
	v_cmp_gt_u32_e32 vcc, v96, v10
	v_cmp_gt_u32_e64 s[82:83], v76, v10
	v_cmp_gt_u32_e64 s[80:81], v60, v10
	v_cndmask_b32_e64 v107, 0, 1, vcc
	v_addc_co_u32_e64 v23, vcc, v23, v107, s[94:95]
	v_cmp_gt_u32_e32 vcc, v93, v10
	v_cmp_gt_u32_e64 s[78:79], v57, v10
	v_cmp_gt_u32_e64 s[76:77], v54, v10
	v_cndmask_b32_e64 v106, 0, 1, vcc
	v_addc_co_u32_e64 v23, vcc, v23, v106, s[92:93]
	v_cmp_gt_u32_e32 vcc, v90, v10
	v_cmp_gt_u32_e64 s[74:75], v51, v10
	v_cmp_gt_u32_e64 s[72:73], v48, v10
	v_cndmask_b32_e64 v105, 0, 1, vcc
	v_addc_co_u32_e64 v23, vcc, v23, v105, s[90:91]
	v_cmp_gt_u32_e32 vcc, v85, v10
	v_cmp_gt_u32_e64 s[70:71], v45, v10
	v_cmp_gt_u32_e64 s[68:69], v42, v10
	v_cndmask_b32_e64 v104, 0, 1, vcc
	v_addc_co_u32_e64 v23, vcc, v23, v104, s[88:89]
	v_cmp_gt_u32_e32 vcc, v83, v10
	v_cmp_gt_u32_e64 s[66:67], v39, v10
	v_cmp_gt_u32_e64 s[64:65], v36, v10
	v_cndmask_b32_e64 v103, 0, 1, vcc
	v_addc_co_u32_e64 v23, vcc, v23, v103, s[86:87]
	v_cmp_gt_u32_e32 vcc, v80, v10
	v_cmp_gt_u32_e64 s[62:63], v33, v10
	v_cmp_gt_u32_e64 s[60:61], v30, v10
	v_cndmask_b32_e64 v102, 0, 1, vcc
	v_addc_co_u32_e64 v23, vcc, v23, v102, s[84:85]
	v_cmp_gt_u32_e32 vcc, v77, v10
	v_cmp_gt_u32_e64 s[58:59], v27, v10
	v_cmp_gt_u32_e64 s[56:57], v24, v10
	v_cndmask_b32_e64 v100, 0, 1, vcc
	v_addc_co_u32_e64 v23, vcc, v23, v100, s[82:83]
; __device__ __forceinline__ int half_sum_i(int v, int hf) { v = row16_sum_i(v); const int a = __builtin_amdgcn_readlane(v, 0) + __builtin_amdgcn_readlane(v, 16), b = __builtin_amdgcn_readlane(v, 32) + __builtin_amdgcn_readlane(v, 48); return hf ? b : a; }
; __device__ __forceinline__ void dsa_index_unit(const Ctx& c, int l, int b, int qb) {
;     ...
;         int cg = 0;
; #pragma unroll
;         for (int kt = 0; kt < 64; ++kt) cg += (key[kt] > T) ? 1 : 0;
;         cg = half_sum_i(cg, hf);
;         const int need = 256 - cg;
;         int eqbase = 0;
;         unsigned mw0 = 0u, mw1 = 0u;
;         const unsigned below = (1u << n) - 1u;
; #pragma unroll
;         for (int kt = 0; kt < 64; ++kt) {
;             const bool gt = key[kt] > T, eq = key[kt] == T;
;             const unsigned long long em = __ballot(eq);
;             const unsigned eh = hf ? (unsigned)(em >> 32) : (unsigned)em;
;             const bool take = gt || (eq && (eqbase + __popc(eh & below) < need));
;             eqbase += __popc(eh);
;             const unsigned long long sm = __ballot(take);
;             if (lane == kt) { mw0 = (unsigned)sm; mw1 = (unsigned)(sm >> 32); }
	v_cmp_gt_u32_e32 vcc, v61, v10
	v_cmp_gt_u32_e64 s[54:55], v21, v10
	v_cmp_gt_u32_e64 s[52:53], v19, v10
	v_cndmask_b32_e64 v97, 0, 1, vcc
	v_addc_co_u32_e64 v23, vcc, v23, v97, s[80:81]
	v_cmp_gt_u32_e32 vcc, v58, v10
	v_cmp_gt_u32_e64 s[50:51], v16, v10
	v_cmp_gt_u32_e64 s[48:49], v14, v10
	v_cndmask_b32_e64 v94, 0, 1, vcc
	v_addc_co_u32_e64 v23, vcc, v23, v94, s[78:79]
	v_cmp_gt_u32_e32 vcc, v55, v10
	v_cmp_gt_u32_e64 s[46:47], v12, v10
	v_cmp_gt_u32_e64 s[44:45], v1, v10
	v_cndmask_b32_e64 v91, 0, 1, vcc
	v_addc_co_u32_e64 v23, vcc, v23, v91, s[76:77]
	v_cmp_gt_u32_e32 vcc, v52, v10
	v_cndmask_b32_e64 v115, 0, 1, s[10:11]
	v_readlane_b32 s10, v253, 37
	v_cndmask_b32_e64 v88, 0, 1, vcc
	v_addc_co_u32_e64 v23, vcc, v23, v88, s[74:75]
	v_cmp_gt_u32_e32 vcc, v49, v10
	v_readlane_b32 s11, v253, 38
	s_mov_b32 s19, 16
	v_cndmask_b32_e64 v82, 0, 1, vcc
	v_addc_co_u32_e64 v23, vcc, v23, v82, s[72:73]
	v_cmp_gt_u32_e32 vcc, v46, v10
	s_nop 1
	v_cndmask_b32_e64 v79, 0, 1, vcc
	v_addc_co_u32_e64 v23, vcc, v23, v79, s[70:71]
	v_cmp_gt_u32_e32 vcc, v43, v10
	s_nop 1
	v_cndmask_b32_e64 v67, 0, 1, vcc
	v_addc_co_u32_e64 v23, vcc, v23, v67, s[68:69]
	v_cmp_gt_u32_e32 vcc, v40, v10
	s_nop 1
	v_cndmask_b32_e64 v59, 0, 1, vcc
	v_addc_co_u32_e64 v23, vcc, v23, v59, s[66:67]
	v_cmp_gt_u32_e32 vcc, v38, v10
	s_nop 1
	v_cndmask_b32_e64 v56, 0, 1, vcc
	v_addc_co_u32_e64 v23, vcc, v23, v56, s[64:65]
	v_cmp_gt_u32_e32 vcc, v35, v10
	s_nop 1
	v_cndmask_b32_e64 v53, 0, 1, vcc
	v_addc_co_u32_e64 v23, vcc, v23, v53, s[62:63]
	v_cmp_gt_u32_e32 vcc, v32, v10
	s_nop 1
	v_cndmask_b32_e64 v50, 0, 1, vcc
	v_addc_co_u32_e64 v23, vcc, v23, v50, s[60:61]
	v_cmp_gt_u32_e32 vcc, v29, v10
	s_nop 1
	v_cndmask_b32_e64 v47, 0, 1, vcc
	v_addc_co_u32_e64 v23, vcc, v23, v47, s[58:59]
	v_cmp_gt_u32_e32 vcc, v26, v10
	s_nop 1
	v_cndmask_b32_e64 v44, 0, 1, vcc
	v_addc_co_u32_e64 v23, vcc, v23, v44, s[56:57]
	v_cmp_gt_u32_e32 vcc, v22, v10
	s_nop 1
	v_cndmask_b32_e64 v41, 0, 1, vcc
	v_addc_co_u32_e64 v23, vcc, v23, v41, s[54:55]
	v_cmp_gt_u32_e32 vcc, v20, v10
	s_nop 1
	v_cndmask_b32_e64 v37, 0, 1, vcc
	v_addc_co_u32_e64 v23, vcc, v23, v37, s[52:53]
	v_cmp_gt_u32_e32 vcc, v18, v10
	s_nop 1
	v_cndmask_b32_e64 v34, 0, 1, vcc
	v_addc_co_u32_e64 v23, vcc, v23, v34, s[50:51]
	v_cmp_gt_u32_e32 vcc, v15, v10
	s_nop 1
	v_cndmask_b32_e64 v31, 0, 1, vcc
	v_addc_co_u32_e64 v23, vcc, v23, v31, s[48:49]
	v_cmp_gt_u32_e32 vcc, v13, v10
	s_nop 1
	v_cndmask_b32_e64 v28, 0, 1, vcc
	v_addc_co_u32_e64 v23, vcc, v23, v28, s[46:47]
	v_cmp_gt_u32_e32 vcc, v11, v10
	s_nop 1
	v_cndmask_b32_e64 v25, 0, 1, vcc
	v_addc_co_u32_e64 v23, vcc, v23, v25, s[44:45]
	s_nop 1
	v_add_u32_dpp v23, v23, v23 quad_perm:[1,0,3,2] row_mask:0xf bank_mask:0xf bound_ctrl:1
	s_nop 1
	v_add_u32_dpp v23, v23, v23 quad_perm:[2,3,0,1] row_mask:0xf bank_mask:0xf bound_ctrl:1
	s_nop 1
	v_add_u32_dpp v23, v23, v23 row_half_mirror row_mask:0xf bank_mask:0xf bound_ctrl:1
	s_nop 1
	v_add_u32_dpp v23, v23, v23 row_mirror row_mask:0xf bank_mask:0xf bound_ctrl:1
	s_nop 0
	v_readlane_b32 s3, v23, 0
	v_readlane_b32 s14, v23, 16
	s_add_i32 s3, s14, s3
	v_readlane_b32 s14, v23, 32
	v_readlane_b32 s15, v23, 48
	s_add_i32 s14, s15, s14
	v_mov_b32_e32 v23, s14
	v_mov_b32_e32 v114, s3
	v_cmp_eq_u32_e64 s[14:15], v8, v10
	v_cndmask_b32_e64 v23, v23, v114, s[6:7]
	v_sub_u32_e32 v23, 0x100, v23
	v_mov_b32_e32 v8, s15
	v_mov_b32_e32 v114, s14
	v_cndmask_b32_e64 v8, v8, v114, s[6:7]
	v_and_b32_e32 v114, v8, v87
	v_bcnt_u32_b32 v114, v114, 0
	v_cmp_lt_u32_e32 vcc, v114, v23
	v_bcnt_u32_b32 v8, v8, 0
	s_ashr_i32 s3, s2, 31
	v_cndmask_b32_e64 v114, 0, 1, vcc
	v_cndmask_b32_e64 v114, v115, v114, s[14:15]
	v_and_b32_e32 v114, 1, v114
	v_cmp_ne_u32_e32 vcc, 0, v114
	s_nop 1
	v_mov_b32_e32 v114, vcc_lo
	v_mov_b32_e32 v115, vcc_hi
	v_cmp_eq_u32_e32 vcc, v9, v10
	v_cndmask_b32_e64 v114, 0, v114, s[10:11]
	v_cndmask_b32_e64 v115, 0, v115, s[10:11]
	v_mov_b32_e32 v9, vcc_hi
	v_mov_b32_e32 v116, vcc_lo
	v_cndmask_b32_e64 v9, v9, v116, s[6:7]
	v_and_b32_e32 v116, v9, v87
	v_bcnt_u32_b32 v116, v116, v8
	v_cmp_lt_u32_e64 s[10:11], v116, v23
	v_bcnt_u32_b32 v8, v9, v8
	s_nop 0
	v_cndmask_b32_e64 v116, 0, 1, s[10:11]
	v_cndmask_b32_e32 v113, v113, v116, vcc
	v_and_b32_e32 v9, 1, v113
	v_cmp_ne_u32_e32 vcc, 0, v9
	v_readlane_b32 s10, v253, 39
	v_readlane_b32 s11, v253, 40
	v_mov_b32_e32 v9, vcc_lo
	v_mov_b32_e32 v113, vcc_hi
	v_cmp_eq_u32_e32 vcc, v6, v10
	v_cndmask_b32_e64 v9, v114, v9, s[10:11]
	v_cndmask_b32_e64 v113, v115, v113, s[10:11]
	v_mov_b32_e32 v6, vcc_hi
	v_mov_b32_e32 v114, vcc_lo
	v_cndmask_b32_e64 v6, v6, v114, s[6:7]
	v_and_b32_e32 v114, v6, v87
	v_bcnt_u32_b32 v114, v114, v8
	v_cmp_lt_u32_e64 s[10:11], v114, v23
	v_bcnt_u32_b32 v6, v6, v8
	s_nop 0
	v_cndmask_b32_e64 v114, 0, 1, s[10:11]
	v_cndmask_b32_e32 v112, v112, v114, vcc
	v_and_b32_e32 v8, 1, v112
	v_cmp_ne_u32_e32 vcc, 0, v8
	v_readlane_b32 s10, v253, 41
	v_readlane_b32 s11, v253, 42
	v_mov_b32_e32 v8, vcc_lo
	s_nop 0
	v_cndmask_b32_e64 v8, v9, v8, s[10:11]
	v_mov_b32_e32 v9, vcc_hi
	v_cmp_eq_u32_e32 vcc, v7, v10
	v_cndmask_b32_e64 v9, v113, v9, s[10:11]
	v_cndmask_b32_e64 v113, 0, 1, s[8:9]
	v_mov_b32_e32 v7, vcc_hi
	v_mov_b32_e32 v112, vcc_lo
	v_cndmask_b32_e64 v7, v7, v112, s[6:7]
	v_and_b32_e32 v112, v7, v87
	v_bcnt_u32_b32 v112, v112, v6
	v_cmp_lt_u32_e64 s[10:11], v112, v23
	v_bcnt_u32_b32 v6, v7, v6
	v_readlane_b32 s8, v253, 43
	v_cndmask_b32_e64 v112, 0, 1, s[10:11]
	v_cndmask_b32_e32 v112, v113, v112, vcc
	v_and_b32_e32 v7, 1, v112
	v_cmp_ne_u32_e32 vcc, 0, v7
	v_readlane_b32 s9, v253, 44
	s_nop 0
	v_mov_b32_e32 v7, vcc_lo
	v_cndmask_b32_e64 v7, v8, v7, s[8:9]
	v_mov_b32_e32 v8, vcc_hi
; __device__ __forceinline__ void dsa_index_unit(const Ctx& c, int l, int b, int qb) {
;     ...
;         for (int kt = 0; kt < 64; ++kt) {
;             const bool gt = key[kt] > T, eq = key[kt] == T;
;             const unsigned long long em = __ballot(eq);
;             const unsigned eh = hf ? (unsigned)(em >> 32) : (unsigned)em;
;             const bool take = gt || (eq && (eqbase + __popc(eh & below) < need));
;             eqbase += __popc(eh);
;             const unsigned long long sm = __ballot(take);
;             if (lane == kt) { mw0 = (unsigned)sm; mw1 = (unsigned)(sm >> 32); }
	v_cmp_eq_u32_e32 vcc, v4, v10
	v_cndmask_b32_e64 v8, v9, v8, s[8:9]
	s_nop 0
	v_mov_b32_e32 v4, vcc_hi
	v_mov_b32_e32 v9, vcc_lo
	v_cndmask_b32_e64 v4, v4, v9, s[6:7]
	v_and_b32_e32 v9, v4, v87
	v_bcnt_u32_b32 v9, v9, v6
	v_cmp_lt_u32_e64 s[8:9], v9, v23
	v_bcnt_u32_b32 v4, v4, v6
	s_nop 0
	v_cndmask_b32_e64 v9, 0, 1, s[8:9]
	v_cndmask_b32_e32 v9, v111, v9, vcc
	v_and_b32_e32 v6, 1, v9
	v_cmp_ne_u32_e32 vcc, 0, v6
	v_readlane_b32 s8, v253, 45
	v_readlane_b32 s9, v253, 46
	v_mov_b32_e32 v6, vcc_lo
	v_cndmask_b32_e64 v9, 0, 1, s[0:1]
	v_cndmask_b32_e64 v6, v7, v6, s[8:9]
	v_mov_b32_e32 v7, vcc_hi
	v_cmp_eq_u32_e32 vcc, v5, v10
	v_cndmask_b32_e64 v7, v8, v7, s[8:9]
	v_readlane_b32 s0, v253, 47
	v_mov_b32_e32 v5, vcc_hi
	v_mov_b32_e32 v8, vcc_lo
	v_cndmask_b32_e64 v5, v5, v8, s[6:7]
	v_and_b32_e32 v8, v5, v87
	v_bcnt_u32_b32 v8, v8, v4
	v_cmp_lt_u32_e64 s[8:9], v8, v23
	v_bcnt_u32_b32 v4, v5, v4
	v_readlane_b32 s1, v253, 48
	v_cndmask_b32_e64 v8, 0, 1, s[8:9]
	v_cndmask_b32_e32 v8, v9, v8, vcc
	v_and_b32_e32 v5, 1, v8
	v_cmp_ne_u32_e32 vcc, 0, v5
	s_nop 1
	v_mov_b32_e32 v5, vcc_lo
	v_cndmask_b32_e64 v5, v6, v5, s[0:1]
	v_mov_b32_e32 v6, vcc_hi
	v_cmp_eq_u32_e32 vcc, v2, v10
	v_cndmask_b32_e64 v6, v7, v6, s[0:1]
	s_nop 0
	v_mov_b32_e32 v2, vcc_hi
	v_mov_b32_e32 v7, vcc_lo
	v_cndmask_b32_e64 v2, v2, v7, s[6:7]
	v_and_b32_e32 v7, v2, v87
	v_bcnt_u32_b32 v7, v7, v4
	v_cmp_lt_u32_e64 s[0:1], v7, v23
	v_bcnt_u32_b32 v2, v2, v4
	s_nop 0
	v_cndmask_b32_e64 v7, 0, 1, s[0:1]
	v_cndmask_b32_e32 v7, v110, v7, vcc
	v_and_b32_e32 v4, 1, v7
	v_cmp_ne_u32_e32 vcc, 0, v4
	v_readlane_b32 s0, v253, 49
	v_readlane_b32 s1, v253, 50
	v_mov_b32_e32 v4, vcc_lo
	v_cndmask_b32_e64 v7, 0, 1, s[4:5]
	v_cndmask_b32_e64 v4, v5, v4, s[0:1]
	v_mov_b32_e32 v5, vcc_hi
	v_cmp_eq_u32_e32 vcc, v3, v10
	v_cndmask_b32_e64 v5, v6, v5, s[0:1]
	s_nop 0
	v_mov_b32_e32 v3, vcc_hi
	v_mov_b32_e32 v6, vcc_lo
	v_cndmask_b32_e64 v3, v3, v6, s[6:7]
	v_and_b32_e32 v6, v3, v87
	v_bcnt_u32_b32 v6, v6, v2
	v_cmp_lt_u32_e64 s[0:1], v6, v23
	v_bcnt_u32_b32 v2, v3, v2
	s_nop 0
	v_cndmask_b32_e64 v6, 0, 1, s[0:1]
	v_cndmask_b32_e32 v6, v7, v6, vcc
	v_and_b32_e32 v3, 1, v6
	v_cmp_ne_u32_e32 vcc, 0, v3
	v_readlane_b32 s0, v253, 51
	v_readlane_b32 s1, v253, 52
	v_mov_b32_e32 v3, vcc_lo
	v_cndmask_b32_e64 v6, 0, 1, s[12:13]
	v_cndmask_b32_e64 v3, v4, v3, s[0:1]
	v_mov_b32_e32 v4, vcc_hi
	v_cmp_eq_u32_e32 vcc, v0, v10
	v_cndmask_b32_e64 v4, v5, v4, s[0:1]
	s_nop 0
	v_mov_b32_e32 v0, vcc_hi
	v_mov_b32_e32 v5, vcc_lo
	v_cndmask_b32_e64 v0, v0, v5, s[6:7]
	v_and_b32_e32 v5, v0, v87
	v_bcnt_u32_b32 v5, v5, v2
	v_cmp_lt_u32_e64 s[0:1], v5, v23
	v_bcnt_u32_b32 v0, v0, v2
	s_nop 0
	v_cndmask_b32_e64 v5, 0, 1, s[0:1]
	v_cndmask_b32_e32 v5, v109, v5, vcc
	v_and_b32_e32 v2, 1, v5
	v_cmp_ne_u32_e32 vcc, 0, v2
	v_readlane_b32 s0, v253, 53
	v_readlane_b32 s1, v253, 54
	v_mov_b32_e32 v2, vcc_lo
	s_nop 0
	v_cndmask_b32_e64 v2, v3, v2, s[0:1]
	v_mov_b32_e32 v3, vcc_hi
	v_cmp_eq_u32_e32 vcc, v101, v10
	v_cndmask_b32_e64 v3, v4, v3, s[0:1]
	s_nop 0
	v_mov_b32_e32 v4, vcc_hi
	v_mov_b32_e32 v5, vcc_lo
	v_cndmask_b32_e64 v4, v4, v5, s[6:7]
	v_and_b32_e32 v5, v4, v87
	v_bcnt_u32_b32 v5, v5, v0
	v_cmp_lt_u32_e64 s[0:1], v5, v23
	v_bcnt_u32_b32 v0, v4, v0
	s_nop 0
	v_cndmask_b32_e64 v5, 0, 1, s[0:1]
	v_cndmask_b32_e32 v5, v6, v5, vcc
	v_and_b32_e32 v4, 1, v5
	v_cmp_ne_u32_e32 vcc, 0, v4
	v_readlane_b32 s0, v253, 55
	v_readlane_b32 s1, v253, 56
	v_mov_b32_e32 v4, vcc_lo
	v_cndmask_b32_e64 v6, 0, 1, s[96:97]
	v_cndmask_b32_e64 v2, v2, v4, s[0:1]
	v_mov_b32_e32 v4, vcc_hi
	v_cmp_eq_u32_e32 vcc, v99, v10
	v_cndmask_b32_e64 v3, v3, v4, s[0:1]
	s_nop 0
	v_mov_b32_e32 v4, vcc_hi
	v_mov_b32_e32 v5, vcc_lo
	v_cndmask_b32_e64 v4, v4, v5, s[6:7]
	v_and_b32_e32 v5, v4, v87
	v_bcnt_u32_b32 v5, v5, v0
	v_cmp_lt_u32_e64 s[0:1], v5, v23
	v_bcnt_u32_b32 v0, v4, v0
	s_nop 0
	v_cndmask_b32_e64 v5, 0, 1, s[0:1]
	v_cndmask_b32_e32 v5, v108, v5, vcc
	v_and_b32_e32 v4, 1, v5
	v_cmp_ne_u32_e32 vcc, 0, v4
	v_readlane_b32 s0, v253, 57
	v_readlane_b32 s1, v253, 58
	v_mov_b32_e32 v4, vcc_lo
	s_nop 0
	v_cndmask_b32_e64 v2, v2, v4, s[0:1]
	v_mov_b32_e32 v4, vcc_hi
	v_cmp_eq_u32_e32 vcc, v98, v10
	v_cndmask_b32_e64 v3, v3, v4, s[0:1]
	s_nop 0
	v_mov_b32_e32 v4, vcc_hi
	v_mov_b32_e32 v5, vcc_lo
	v_cndmask_b32_e64 v4, v4, v5, s[6:7]
	v_and_b32_e32 v5, v4, v87
	v_bcnt_u32_b32 v5, v5, v0
	v_cmp_lt_u32_e64 s[0:1], v5, v23
	v_bcnt_u32_b32 v0, v4, v0
	s_nop 0
	v_cndmask_b32_e64 v5, 0, 1, s[0:1]
	v_cndmask_b32_e32 v5, v6, v5, vcc
	v_and_b32_e32 v4, 1, v5
	v_cmp_ne_u32_e32 vcc, 0, v4
	v_readlane_b32 s0, v253, 59
	v_readlane_b32 s1, v253, 60
	v_mov_b32_e32 v4, vcc_lo
	v_cndmask_b32_e64 v6, 0, 1, s[94:95]
	v_cndmask_b32_e64 v2, v2, v4, s[0:1]
	v_mov_b32_e32 v4, vcc_hi
	v_cmp_eq_u32_e32 vcc, v96, v10
	v_cndmask_b32_e64 v3, v3, v4, s[0:1]
	s_nop 0
	v_mov_b32_e32 v4, vcc_hi
	v_mov_b32_e32 v5, vcc_lo
	v_cndmask_b32_e64 v4, v4, v5, s[6:7]
	v_and_b32_e32 v5, v4, v87
	v_bcnt_u32_b32 v5, v5, v0
	v_cmp_lt_u32_e64 s[0:1], v5, v23
	v_bcnt_u32_b32 v0, v4, v0
	s_nop 0
	v_cndmask_b32_e64 v5, 0, 1, s[0:1]
	v_cndmask_b32_e32 v5, v107, v5, vcc
	v_and_b32_e32 v4, 1, v5
	v_cmp_ne_u32_e32 vcc, 0, v4
	v_readlane_b32 s0, v253, 61
	v_readlane_b32 s1, v253, 62
	v_mov_b32_e32 v4, vcc_lo
	s_nop 0
	v_cndmask_b32_e64 v2, v2, v4, s[0:1]
	v_mov_b32_e32 v4, vcc_hi
	v_cmp_eq_u32_e32 vcc, v95, v10
	v_cndmask_b32_e64 v3, v3, v4, s[0:1]
	s_nop 0
	v_mov_b32_e32 v4, vcc_hi
	v_mov_b32_e32 v5, vcc_lo
	v_cndmask_b32_e64 v4, v4, v5, s[6:7]
	v_and_b32_e32 v5, v4, v87
	v_bcnt_u32_b32 v5, v5, v0
	v_cmp_lt_u32_e64 s[0:1], v5, v23
	v_bcnt_u32_b32 v0, v4, v0
	s_nop 0
	v_cndmask_b32_e64 v5, 0, 1, s[0:1]
; __device__ __forceinline__ void dsa_index_unit(const Ctx& c, int l, int b, int qb) {
;     ...
;         for (int kt = 0; kt < 64; ++kt) {
;             const bool gt = key[kt] > T, eq = key[kt] == T;
;             const unsigned long long em = __ballot(eq);
;             const unsigned eh = hf ? (unsigned)(em >> 32) : (unsigned)em;
;             const bool take = gt || (eq && (eqbase + __popc(eh & below) < need));
;             eqbase += __popc(eh);
;             const unsigned long long sm = __ballot(take);
;             if (lane == kt) { mw0 = (unsigned)sm; mw1 = (unsigned)(sm >> 32); }
	v_cndmask_b32_e32 v5, v6, v5, vcc
	v_and_b32_e32 v4, 1, v5
	v_cmp_ne_u32_e32 vcc, 0, v4
	v_readlane_b32 s0, v253, 63
	v_readlane_b32 s1, v254, 0
	v_mov_b32_e32 v4, vcc_lo
	v_cndmask_b32_e64 v6, 0, 1, s[92:93]
	v_cndmask_b32_e64 v2, v2, v4, s[0:1]
	v_mov_b32_e32 v4, vcc_hi
	v_cmp_eq_u32_e32 vcc, v93, v10
	v_cndmask_b32_e64 v3, v3, v4, s[0:1]
	s_nop 0
	v_mov_b32_e32 v4, vcc_hi
	v_mov_b32_e32 v5, vcc_lo
	v_cndmask_b32_e64 v4, v4, v5, s[6:7]
	v_and_b32_e32 v5, v4, v87
	v_bcnt_u32_b32 v5, v5, v0
	v_cmp_lt_u32_e64 s[0:1], v5, v23
	v_bcnt_u32_b32 v0, v4, v0
	s_nop 0
	v_cndmask_b32_e64 v5, 0, 1, s[0:1]
	v_cndmask_b32_e32 v5, v106, v5, vcc
	v_and_b32_e32 v4, 1, v5
	v_cmp_ne_u32_e32 vcc, 0, v4
	v_readlane_b32 s0, v254, 1
	v_readlane_b32 s1, v254, 2
	v_mov_b32_e32 v4, vcc_lo
	s_nop 0
	v_cndmask_b32_e64 v2, v2, v4, s[0:1]
	v_mov_b32_e32 v4, vcc_hi
	v_cmp_eq_u32_e32 vcc, v92, v10
	v_cndmask_b32_e64 v3, v3, v4, s[0:1]
	s_nop 0
	v_mov_b32_e32 v4, vcc_hi
	v_mov_b32_e32 v5, vcc_lo
	v_cndmask_b32_e64 v4, v4, v5, s[6:7]
	v_and_b32_e32 v5, v4, v87
	v_bcnt_u32_b32 v5, v5, v0
	v_cmp_lt_u32_e64 s[0:1], v5, v23
	v_bcnt_u32_b32 v0, v4, v0
	s_nop 0
	v_cndmask_b32_e64 v5, 0, 1, s[0:1]
	v_cndmask_b32_e32 v5, v6, v5, vcc
	v_and_b32_e32 v4, 1, v5
	v_cmp_ne_u32_e32 vcc, 0, v4
	v_readlane_b32 s0, v254, 3
	v_readlane_b32 s1, v254, 4
	v_mov_b32_e32 v4, vcc_lo
	v_cndmask_b32_e64 v6, 0, 1, s[90:91]
	v_cndmask_b32_e64 v2, v2, v4, s[0:1]
	v_mov_b32_e32 v4, vcc_hi
	v_cmp_eq_u32_e32 vcc, v90, v10
	v_cndmask_b32_e64 v3, v3, v4, s[0:1]
	s_mov_b64 s[90:91], s[20:21]
	v_mov_b32_e32 v4, vcc_hi
	v_mov_b32_e32 v5, vcc_lo
	v_cndmask_b32_e64 v4, v4, v5, s[6:7]
	v_and_b32_e32 v5, v4, v87
	v_bcnt_u32_b32 v5, v5, v0
	v_cmp_lt_u32_e64 s[0:1], v5, v23
	v_bcnt_u32_b32 v0, v4, v0
	s_nop 0
	v_cndmask_b32_e64 v5, 0, 1, s[0:1]
	v_cndmask_b32_e32 v5, v105, v5, vcc
	v_and_b32_e32 v4, 1, v5
	v_cmp_ne_u32_e32 vcc, 0, v4
	v_readlane_b32 s0, v254, 5
	v_readlane_b32 s1, v254, 6
	v_mov_b32_e32 v4, vcc_lo
	s_nop 0
	v_cndmask_b32_e64 v2, v2, v4, s[0:1]
	v_mov_b32_e32 v4, vcc_hi
	v_cmp_eq_u32_e32 vcc, v89, v10
	v_cndmask_b32_e64 v3, v3, v4, s[0:1]
	s_nop 0
	v_mov_b32_e32 v4, vcc_hi
	v_mov_b32_e32 v5, vcc_lo
	v_cndmask_b32_e64 v4, v4, v5, s[6:7]
	v_and_b32_e32 v5, v4, v87
	v_bcnt_u32_b32 v5, v5, v0
	v_cmp_lt_u32_e64 s[0:1], v5, v23
	v_bcnt_u32_b32 v0, v4, v0
	s_nop 0
	v_cndmask_b32_e64 v5, 0, 1, s[0:1]
	v_cndmask_b32_e32 v5, v6, v5, vcc
	v_and_b32_e32 v4, 1, v5
	v_cmp_ne_u32_e32 vcc, 0, v4
	v_readlane_b32 s0, v254, 7
	v_readlane_b32 s1, v254, 8
	v_mov_b32_e32 v4, vcc_lo
	v_cndmask_b32_e64 v6, 0, 1, s[88:89]
	v_cndmask_b32_e64 v2, v2, v4, s[0:1]
	v_mov_b32_e32 v4, vcc_hi
	v_cmp_eq_u32_e32 vcc, v85, v10
	v_cndmask_b32_e64 v3, v3, v4, s[0:1]
	s_nop 0
	v_mov_b32_e32 v4, vcc_hi
	v_mov_b32_e32 v5, vcc_lo
	v_cndmask_b32_e64 v4, v4, v5, s[6:7]
	v_and_b32_e32 v5, v4, v87
	v_bcnt_u32_b32 v5, v5, v0
	v_cmp_lt_u32_e64 s[0:1], v5, v23
	v_bcnt_u32_b32 v0, v4, v0
	s_nop 0
	v_cndmask_b32_e64 v5, 0, 1, s[0:1]
	v_cndmask_b32_e32 v5, v104, v5, vcc
	v_and_b32_e32 v4, 1, v5
	v_cmp_ne_u32_e32 vcc, 0, v4
	v_readlane_b32 s0, v254, 9
	v_readlane_b32 s1, v254, 10
	v_mov_b32_e32 v4, vcc_lo
	s_nop 0
	v_cndmask_b32_e64 v2, v2, v4, s[0:1]
	v_mov_b32_e32 v4, vcc_hi
	v_cmp_eq_u32_e32 vcc, v84, v10
	v_cndmask_b32_e64 v3, v3, v4, s[0:1]
	s_nop 0
	v_mov_b32_e32 v4, vcc_hi
	v_mov_b32_e32 v5, vcc_lo
	v_cndmask_b32_e64 v4, v4, v5, s[6:7]
	v_and_b32_e32 v5, v4, v87
	v_bcnt_u32_b32 v5, v5, v0
	v_cmp_lt_u32_e64 s[0:1], v5, v23
	v_bcnt_u32_b32 v0, v4, v0
	s_nop 0
	v_cndmask_b32_e64 v5, 0, 1, s[0:1]
	v_cndmask_b32_e32 v5, v6, v5, vcc
	v_and_b32_e32 v4, 1, v5
	v_cmp_ne_u32_e32 vcc, 0, v4
	v_readlane_b32 s0, v254, 11
	v_readlane_b32 s1, v254, 12
	v_mov_b32_e32 v4, vcc_lo
	v_cndmask_b32_e64 v6, 0, 1, s[86:87]
	v_cndmask_b32_e64 v2, v2, v4, s[0:1]
	v_mov_b32_e32 v4, vcc_hi
	v_cmp_eq_u32_e32 vcc, v83, v10
	v_cndmask_b32_e64 v3, v3, v4, s[0:1]
	s_nop 0
	v_mov_b32_e32 v4, vcc_hi
	v_mov_b32_e32 v5, vcc_lo
	v_cndmask_b32_e64 v4, v4, v5, s[6:7]
	v_and_b32_e32 v5, v4, v87
	v_bcnt_u32_b32 v5, v5, v0
	v_cmp_lt_u32_e64 s[0:1], v5, v23
	v_bcnt_u32_b32 v0, v4, v0
	s_nop 0
	v_cndmask_b32_e64 v5, 0, 1, s[0:1]
	v_cndmask_b32_e32 v5, v103, v5, vcc
	v_and_b32_e32 v4, 1, v5
	v_cmp_ne_u32_e32 vcc, 0, v4
	v_readlane_b32 s0, v254, 13
	v_readlane_b32 s1, v254, 14
	v_mov_b32_e32 v4, vcc_lo
	s_nop 0
	v_cndmask_b32_e64 v2, v2, v4, s[0:1]
	v_mov_b32_e32 v4, vcc_hi
	v_cmp_eq_u32_e32 vcc, v81, v10
	v_cndmask_b32_e64 v3, v3, v4, s[0:1]
	s_nop 0
	v_mov_b32_e32 v4, vcc_hi
	v_mov_b32_e32 v5, vcc_lo
	v_cndmask_b32_e64 v4, v4, v5, s[6:7]
	v_and_b32_e32 v5, v4, v87
	v_bcnt_u32_b32 v5, v5, v0
	v_cmp_lt_u32_e64 s[0:1], v5, v23
	v_bcnt_u32_b32 v0, v4, v0
	s_nop 0
	v_cndmask_b32_e64 v5, 0, 1, s[0:1]
	v_cndmask_b32_e32 v5, v6, v5, vcc
	v_and_b32_e32 v4, 1, v5
	v_cmp_ne_u32_e32 vcc, 0, v4
	v_readlane_b32 s0, v254, 15
	v_readlane_b32 s1, v254, 16
	v_mov_b32_e32 v4, vcc_lo
	v_cndmask_b32_e64 v6, 0, 1, s[84:85]
	v_cndmask_b32_e64 v2, v2, v4, s[0:1]
	v_mov_b32_e32 v4, vcc_hi
	v_cmp_eq_u32_e32 vcc, v80, v10
	v_cndmask_b32_e64 v3, v3, v4, s[0:1]
	s_nop 0
	v_mov_b32_e32 v4, vcc_hi
	v_mov_b32_e32 v5, vcc_lo
	v_cndmask_b32_e64 v4, v4, v5, s[6:7]
	v_and_b32_e32 v5, v4, v87
	v_bcnt_u32_b32 v5, v5, v0
	v_cmp_lt_u32_e64 s[0:1], v5, v23
	v_bcnt_u32_b32 v0, v4, v0
	s_nop 0
	v_cndmask_b32_e64 v5, 0, 1, s[0:1]
	v_cndmask_b32_e32 v5, v102, v5, vcc
	v_and_b32_e32 v4, 1, v5
	v_cmp_ne_u32_e32 vcc, 0, v4
	v_readlane_b32 s0, v254, 17
	v_readlane_b32 s1, v254, 18
	v_mov_b32_e32 v4, vcc_lo
	s_nop 0
	v_cndmask_b32_e64 v2, v2, v4, s[0:1]
	v_mov_b32_e32 v4, vcc_hi
	v_cmp_eq_u32_e32 vcc, v78, v10
	v_cndmask_b32_e64 v3, v3, v4, s[0:1]
; __device__ __forceinline__ void dsa_index_unit(const Ctx& c, int l, int b, int qb) {
;     ...
;         for (int kt = 0; kt < 64; ++kt) {
;             const bool gt = key[kt] > T, eq = key[kt] == T;
;             const unsigned long long em = __ballot(eq);
;             const unsigned eh = hf ? (unsigned)(em >> 32) : (unsigned)em;
;             const bool take = gt || (eq && (eqbase + __popc(eh & below) < need));
;             eqbase += __popc(eh);
;             const unsigned long long sm = __ballot(take);
;             if (lane == kt) { mw0 = (unsigned)sm; mw1 = (unsigned)(sm >> 32); }
	s_nop 0
	v_mov_b32_e32 v4, vcc_hi
	v_mov_b32_e32 v5, vcc_lo
	v_cndmask_b32_e64 v4, v4, v5, s[6:7]
	v_and_b32_e32 v5, v4, v87
	v_bcnt_u32_b32 v5, v5, v0
	v_cmp_lt_u32_e64 s[0:1], v5, v23
	v_bcnt_u32_b32 v0, v4, v0
	s_nop 0
	v_cndmask_b32_e64 v5, 0, 1, s[0:1]
	v_cndmask_b32_e32 v5, v6, v5, vcc
	v_and_b32_e32 v4, 1, v5
	v_cmp_ne_u32_e32 vcc, 0, v4
	v_readlane_b32 s0, v254, 19
	v_readlane_b32 s1, v254, 20
	v_mov_b32_e32 v4, vcc_lo
	v_cndmask_b32_e64 v6, 0, 1, s[82:83]
	v_cndmask_b32_e64 v2, v2, v4, s[0:1]
	v_mov_b32_e32 v4, vcc_hi
	v_cmp_eq_u32_e32 vcc, v77, v10
	v_cndmask_b32_e64 v3, v3, v4, s[0:1]
	s_nop 0
	v_mov_b32_e32 v4, vcc_hi
	v_mov_b32_e32 v5, vcc_lo
	v_cndmask_b32_e64 v4, v4, v5, s[6:7]
	v_and_b32_e32 v5, v4, v87
	v_bcnt_u32_b32 v5, v5, v0
	v_cmp_lt_u32_e64 s[0:1], v5, v23
	v_bcnt_u32_b32 v0, v4, v0
	s_nop 0
	v_cndmask_b32_e64 v5, 0, 1, s[0:1]
	v_cndmask_b32_e32 v5, v100, v5, vcc
	v_and_b32_e32 v4, 1, v5
	v_cmp_ne_u32_e32 vcc, 0, v4
	v_readlane_b32 s0, v254, 21
	v_readlane_b32 s1, v254, 22
	v_mov_b32_e32 v4, vcc_lo
	s_nop 0
	v_cndmask_b32_e64 v2, v2, v4, s[0:1]
	v_mov_b32_e32 v4, vcc_hi
	v_cmp_eq_u32_e32 vcc, v76, v10
	v_cndmask_b32_e64 v3, v3, v4, s[0:1]
	s_nop 0
	v_mov_b32_e32 v4, vcc_hi
	v_mov_b32_e32 v5, vcc_lo
	v_cndmask_b32_e64 v4, v4, v5, s[6:7]
	v_and_b32_e32 v5, v4, v87
	v_bcnt_u32_b32 v5, v5, v0
	v_cmp_lt_u32_e64 s[0:1], v5, v23
	v_bcnt_u32_b32 v0, v4, v0
	s_nop 0
	v_cndmask_b32_e64 v5, 0, 1, s[0:1]
	v_cndmask_b32_e32 v5, v6, v5, vcc
	v_and_b32_e32 v4, 1, v5
	v_cmp_ne_u32_e32 vcc, 0, v4
	v_readlane_b32 s0, v254, 23
	v_readlane_b32 s1, v254, 24
	v_mov_b32_e32 v4, vcc_lo
	v_cndmask_b32_e64 v6, 0, 1, s[80:81]
	v_cndmask_b32_e64 v2, v2, v4, s[0:1]
	v_mov_b32_e32 v4, vcc_hi
	v_cmp_eq_u32_e32 vcc, v61, v10
	v_cndmask_b32_e64 v3, v3, v4, s[0:1]
	s_nop 0
	v_mov_b32_e32 v4, vcc_hi
	v_mov_b32_e32 v5, vcc_lo
	v_cndmask_b32_e64 v4, v4, v5, s[6:7]
	v_and_b32_e32 v5, v4, v87
	v_bcnt_u32_b32 v5, v5, v0
	v_cmp_lt_u32_e64 s[0:1], v5, v23
	v_bcnt_u32_b32 v0, v4, v0
	s_nop 0
	v_cndmask_b32_e64 v5, 0, 1, s[0:1]
	v_cndmask_b32_e32 v5, v97, v5, vcc
	v_and_b32_e32 v4, 1, v5
	v_cmp_ne_u32_e32 vcc, 0, v4
	v_readlane_b32 s0, v254, 25
	v_readlane_b32 s1, v254, 26
	v_mov_b32_e32 v4, vcc_lo
	s_nop 0
	v_cndmask_b32_e64 v2, v2, v4, s[0:1]
	v_mov_b32_e32 v4, vcc_hi
	v_cmp_eq_u32_e32 vcc, v60, v10
	v_cndmask_b32_e64 v3, v3, v4, s[0:1]
	s_nop 0
	v_mov_b32_e32 v4, vcc_hi
	v_mov_b32_e32 v5, vcc_lo
	v_cndmask_b32_e64 v4, v4, v5, s[6:7]
	v_and_b32_e32 v5, v4, v87
	v_bcnt_u32_b32 v5, v5, v0
	v_cmp_lt_u32_e64 s[0:1], v5, v23
	v_bcnt_u32_b32 v0, v4, v0
	s_nop 0
	v_cndmask_b32_e64 v5, 0, 1, s[0:1]
	v_cndmask_b32_e32 v5, v6, v5, vcc
	v_and_b32_e32 v4, 1, v5
	v_cmp_ne_u32_e32 vcc, 0, v4
	v_readlane_b32 s0, v254, 27
	v_readlane_b32 s1, v254, 28
	v_mov_b32_e32 v4, vcc_lo
	v_cndmask_b32_e64 v6, 0, 1, s[78:79]
	v_cndmask_b32_e64 v2, v2, v4, s[0:1]
	v_mov_b32_e32 v4, vcc_hi
	v_cmp_eq_u32_e32 vcc, v58, v10
	v_cndmask_b32_e64 v3, v3, v4, s[0:1]
	s_nop 0
	v_mov_b32_e32 v4, vcc_hi
	v_mov_b32_e32 v5, vcc_lo
	v_cndmask_b32_e64 v4, v4, v5, s[6:7]
	v_and_b32_e32 v5, v4, v87
	v_bcnt_u32_b32 v5, v5, v0
	v_cmp_lt_u32_e64 s[0:1], v5, v23
	v_bcnt_u32_b32 v0, v4, v0
	s_nop 0
	v_cndmask_b32_e64 v5, 0, 1, s[0:1]
	v_cndmask_b32_e32 v5, v94, v5, vcc
	v_and_b32_e32 v4, 1, v5
	v_cmp_ne_u32_e32 vcc, 0, v4
	v_readlane_b32 s0, v254, 29
	v_readlane_b32 s1, v254, 30
	v_mov_b32_e32 v4, vcc_lo
	s_nop 0
	v_cndmask_b32_e64 v2, v2, v4, s[0:1]
	v_mov_b32_e32 v4, vcc_hi
	v_cmp_eq_u32_e32 vcc, v57, v10
	v_cndmask_b32_e64 v3, v3, v4, s[0:1]
	s_nop 0
	v_mov_b32_e32 v4, vcc_hi
	v_mov_b32_e32 v5, vcc_lo
	v_cndmask_b32_e64 v4, v4, v5, s[6:7]
	v_and_b32_e32 v5, v4, v87
	v_bcnt_u32_b32 v5, v5, v0
	v_cmp_lt_u32_e64 s[0:1], v5, v23
	v_bcnt_u32_b32 v0, v4, v0
	s_nop 0
	v_cndmask_b32_e64 v5, 0, 1, s[0:1]
	v_cndmask_b32_e32 v5, v6, v5, vcc
	v_and_b32_e32 v4, 1, v5
	v_cmp_ne_u32_e32 vcc, 0, v4
	v_readlane_b32 s0, v254, 31
	v_readlane_b32 s1, v254, 32
	v_mov_b32_e32 v4, vcc_lo
	v_cndmask_b32_e64 v6, 0, 1, s[76:77]
	v_cndmask_b32_e64 v2, v2, v4, s[0:1]
	v_mov_b32_e32 v4, vcc_hi
	v_cmp_eq_u32_e32 vcc, v55, v10
	v_cndmask_b32_e64 v3, v3, v4, s[0:1]
	s_nop 0
	v_mov_b32_e32 v4, vcc_hi
	v_mov_b32_e32 v5, vcc_lo
	v_cndmask_b32_e64 v4, v4, v5, s[6:7]
	v_and_b32_e32 v5, v4, v87
	v_bcnt_u32_b32 v5, v5, v0
	v_cmp_lt_u32_e64 s[0:1], v5, v23
	v_bcnt_u32_b32 v0, v4, v0
	s_nop 0
	v_cndmask_b32_e64 v5, 0, 1, s[0:1]
	v_cndmask_b32_e32 v5, v91, v5, vcc
	v_and_b32_e32 v4, 1, v5
	v_cmp_ne_u32_e32 vcc, 0, v4
	v_readlane_b32 s0, v254, 33
	v_readlane_b32 s1, v254, 34
	v_mov_b32_e32 v4, vcc_lo
	s_nop 0
	v_cndmask_b32_e64 v2, v2, v4, s[0:1]
	v_mov_b32_e32 v4, vcc_hi
	v_cmp_eq_u32_e32 vcc, v54, v10
	v_cndmask_b32_e64 v3, v3, v4, s[0:1]
	s_nop 0
	v_mov_b32_e32 v4, vcc_hi
	v_mov_b32_e32 v5, vcc_lo
	v_cndmask_b32_e64 v4, v4, v5, s[6:7]
	v_and_b32_e32 v5, v4, v87
	v_bcnt_u32_b32 v5, v5, v0
	v_cmp_lt_u32_e64 s[0:1], v5, v23
	v_bcnt_u32_b32 v0, v4, v0
	s_nop 0
	v_cndmask_b32_e64 v5, 0, 1, s[0:1]
	v_cndmask_b32_e32 v5, v6, v5, vcc
	v_and_b32_e32 v4, 1, v5
	v_cmp_ne_u32_e32 vcc, 0, v4
	v_readlane_b32 s0, v254, 35
	v_readlane_b32 s1, v254, 36
	v_mov_b32_e32 v4, vcc_lo
	v_cndmask_b32_e64 v6, 0, 1, s[74:75]
	v_cndmask_b32_e64 v2, v2, v4, s[0:1]
	v_mov_b32_e32 v4, vcc_hi
	v_cmp_eq_u32_e32 vcc, v52, v10
	v_cndmask_b32_e64 v3, v3, v4, s[0:1]
	s_nop 0
	v_mov_b32_e32 v4, vcc_hi
	v_mov_b32_e32 v5, vcc_lo
	v_cndmask_b32_e64 v4, v4, v5, s[6:7]
	v_and_b32_e32 v5, v4, v87
	v_bcnt_u32_b32 v5, v5, v0
	v_cmp_lt_u32_e64 s[0:1], v5, v23
	v_bcnt_u32_b32 v0, v4, v0
	s_nop 0
	v_cndmask_b32_e64 v5, 0, 1, s[0:1]
	v_cndmask_b32_e32 v5, v88, v5, vcc
	v_and_b32_e32 v4, 1, v5
; __device__ __forceinline__ void dsa_index_unit(const Ctx& c, int l, int b, int qb) {
;     ...
;         for (int kt = 0; kt < 64; ++kt) {
;             const bool gt = key[kt] > T, eq = key[kt] == T;
;             const unsigned long long em = __ballot(eq);
;             const unsigned eh = hf ? (unsigned)(em >> 32) : (unsigned)em;
;             const bool take = gt || (eq && (eqbase + __popc(eh & below) < need));
;             eqbase += __popc(eh);
;             const unsigned long long sm = __ballot(take);
;             if (lane == kt) { mw0 = (unsigned)sm; mw1 = (unsigned)(sm >> 32); }
	v_cmp_ne_u32_e32 vcc, 0, v4
	v_readlane_b32 s0, v254, 37
	v_readlane_b32 s1, v254, 38
	v_mov_b32_e32 v4, vcc_lo
	s_nop 0
	v_cndmask_b32_e64 v2, v2, v4, s[0:1]
	v_mov_b32_e32 v4, vcc_hi
	v_cmp_eq_u32_e32 vcc, v51, v10
	v_cndmask_b32_e64 v3, v3, v4, s[0:1]
	s_nop 0
	v_mov_b32_e32 v4, vcc_hi
	v_mov_b32_e32 v5, vcc_lo
	v_cndmask_b32_e64 v4, v4, v5, s[6:7]
	v_and_b32_e32 v5, v4, v87
	v_bcnt_u32_b32 v5, v5, v0
	v_cmp_lt_u32_e64 s[0:1], v5, v23
	v_bcnt_u32_b32 v0, v4, v0
	s_nop 0
	v_cndmask_b32_e64 v5, 0, 1, s[0:1]
	v_cndmask_b32_e32 v5, v6, v5, vcc
	v_and_b32_e32 v4, 1, v5
	v_cmp_ne_u32_e32 vcc, 0, v4
	v_readlane_b32 s0, v254, 39
	v_readlane_b32 s1, v254, 40
	v_mov_b32_e32 v4, vcc_lo
	v_cndmask_b32_e64 v6, 0, 1, s[72:73]
	v_cndmask_b32_e64 v2, v2, v4, s[0:1]
	v_mov_b32_e32 v4, vcc_hi
	v_cmp_eq_u32_e32 vcc, v49, v10
	v_cndmask_b32_e64 v3, v3, v4, s[0:1]
	s_nop 0
	v_mov_b32_e32 v4, vcc_hi
	v_mov_b32_e32 v5, vcc_lo
	v_cndmask_b32_e64 v4, v4, v5, s[6:7]
	v_and_b32_e32 v5, v4, v87
	v_bcnt_u32_b32 v5, v5, v0
	v_cmp_lt_u32_e64 s[0:1], v5, v23
	v_bcnt_u32_b32 v0, v4, v0
	s_nop 0
	v_cndmask_b32_e64 v5, 0, 1, s[0:1]
	v_cndmask_b32_e32 v5, v82, v5, vcc
	v_and_b32_e32 v4, 1, v5
	v_cmp_ne_u32_e32 vcc, 0, v4
	v_readlane_b32 s0, v254, 41
	v_readlane_b32 s1, v254, 42
	v_mov_b32_e32 v4, vcc_lo
	s_nop 0
	v_cndmask_b32_e64 v2, v2, v4, s[0:1]
	v_mov_b32_e32 v4, vcc_hi
	v_cmp_eq_u32_e32 vcc, v48, v10
	v_cndmask_b32_e64 v3, v3, v4, s[0:1]
	s_nop 0
	v_mov_b32_e32 v4, vcc_hi
	v_mov_b32_e32 v5, vcc_lo
	v_cndmask_b32_e64 v4, v4, v5, s[6:7]
	v_and_b32_e32 v5, v4, v87
	v_bcnt_u32_b32 v5, v5, v0
	v_cmp_lt_u32_e64 s[0:1], v5, v23
	v_bcnt_u32_b32 v0, v4, v0
	s_nop 0
	v_cndmask_b32_e64 v5, 0, 1, s[0:1]
	v_cndmask_b32_e32 v5, v6, v5, vcc
	v_and_b32_e32 v4, 1, v5
	v_cmp_ne_u32_e32 vcc, 0, v4
	v_readlane_b32 s0, v254, 43
	v_readlane_b32 s1, v254, 44
	v_mov_b32_e32 v4, vcc_lo
	v_cndmask_b32_e64 v6, 0, 1, s[70:71]
	v_cndmask_b32_e64 v2, v2, v4, s[0:1]
	v_mov_b32_e32 v4, vcc_hi
	v_cmp_eq_u32_e32 vcc, v46, v10
	v_cndmask_b32_e64 v3, v3, v4, s[0:1]
	s_nop 0
	v_mov_b32_e32 v4, vcc_hi
	v_mov_b32_e32 v5, vcc_lo
	v_cndmask_b32_e64 v4, v4, v5, s[6:7]
	v_and_b32_e32 v5, v4, v87
	v_bcnt_u32_b32 v5, v5, v0
	v_cmp_lt_u32_e64 s[0:1], v5, v23
	v_bcnt_u32_b32 v0, v4, v0
	s_nop 0
	v_cndmask_b32_e64 v5, 0, 1, s[0:1]
	v_cndmask_b32_e32 v5, v79, v5, vcc
	v_and_b32_e32 v4, 1, v5
	v_cmp_ne_u32_e32 vcc, 0, v4
	v_readlane_b32 s0, v254, 45
	v_readlane_b32 s1, v254, 46
	v_mov_b32_e32 v4, vcc_lo
	s_nop 0
	v_cndmask_b32_e64 v2, v2, v4, s[0:1]
	v_mov_b32_e32 v4, vcc_hi
	v_cmp_eq_u32_e32 vcc, v45, v10
	v_cndmask_b32_e64 v3, v3, v4, s[0:1]
	s_nop 0
	v_mov_b32_e32 v4, vcc_hi
	v_mov_b32_e32 v5, vcc_lo
	v_cndmask_b32_e64 v4, v4, v5, s[6:7]
	v_and_b32_e32 v5, v4, v87
	v_bcnt_u32_b32 v5, v5, v0
	v_cmp_lt_u32_e64 s[0:1], v5, v23
	v_bcnt_u32_b32 v0, v4, v0
	s_nop 0
	v_cndmask_b32_e64 v5, 0, 1, s[0:1]
	v_cndmask_b32_e32 v5, v6, v5, vcc
	v_and_b32_e32 v4, 1, v5
	v_cmp_ne_u32_e32 vcc, 0, v4
	v_readlane_b32 s0, v254, 47
	v_readlane_b32 s1, v254, 48
	v_mov_b32_e32 v4, vcc_lo
	v_cndmask_b32_e64 v6, 0, 1, s[68:69]
	v_cndmask_b32_e64 v2, v2, v4, s[0:1]
	v_mov_b32_e32 v4, vcc_hi
	v_cmp_eq_u32_e32 vcc, v43, v10
	v_cndmask_b32_e64 v3, v3, v4, s[0:1]
	s_mov_b32 s68, 0x3d000000
	v_mov_b32_e32 v4, vcc_hi
	v_mov_b32_e32 v5, vcc_lo
	v_cndmask_b32_e64 v4, v4, v5, s[6:7]
	v_and_b32_e32 v5, v4, v87
	v_bcnt_u32_b32 v5, v5, v0
	v_cmp_lt_u32_e64 s[0:1], v5, v23
	v_bcnt_u32_b32 v0, v4, v0
	s_nop 0
	v_cndmask_b32_e64 v5, 0, 1, s[0:1]
	v_cndmask_b32_e32 v5, v67, v5, vcc
	v_and_b32_e32 v4, 1, v5
	v_cmp_ne_u32_e32 vcc, 0, v4
	v_readlane_b32 s0, v254, 49
	v_readlane_b32 s1, v254, 50
	v_mov_b32_e32 v4, vcc_lo
	s_nop 0
	v_cndmask_b32_e64 v2, v2, v4, s[0:1]
	v_mov_b32_e32 v4, vcc_hi
	v_cmp_eq_u32_e32 vcc, v42, v10
	v_cndmask_b32_e64 v3, v3, v4, s[0:1]
	s_nop 0
	v_mov_b32_e32 v4, vcc_hi
	v_mov_b32_e32 v5, vcc_lo
	v_cndmask_b32_e64 v4, v4, v5, s[6:7]
	v_and_b32_e32 v5, v4, v87
	v_bcnt_u32_b32 v5, v5, v0
	v_cmp_lt_u32_e64 s[0:1], v5, v23
	v_bcnt_u32_b32 v0, v4, v0
	s_nop 0
	v_cndmask_b32_e64 v5, 0, 1, s[0:1]
	v_cndmask_b32_e32 v5, v6, v5, vcc
	v_and_b32_e32 v4, 1, v5
	v_cmp_ne_u32_e32 vcc, 0, v4
	v_readlane_b32 s0, v254, 51
	v_readlane_b32 s1, v254, 52
	v_mov_b32_e32 v4, vcc_lo
	v_cndmask_b32_e64 v6, 0, 1, s[66:67]
	v_cndmask_b32_e64 v2, v2, v4, s[0:1]
	v_mov_b32_e32 v4, vcc_hi
	v_cmp_eq_u32_e32 vcc, v40, v10
	v_cndmask_b32_e64 v3, v3, v4, s[0:1]
	s_nop 0
	v_mov_b32_e32 v4, vcc_hi
	v_mov_b32_e32 v5, vcc_lo
	v_cndmask_b32_e64 v4, v4, v5, s[6:7]
	v_and_b32_e32 v5, v4, v87
	v_bcnt_u32_b32 v5, v5, v0
	v_cmp_lt_u32_e64 s[0:1], v5, v23
	v_bcnt_u32_b32 v0, v4, v0
	s_nop 0
	v_cndmask_b32_e64 v5, 0, 1, s[0:1]
	v_cndmask_b32_e32 v5, v59, v5, vcc
	v_and_b32_e32 v4, 1, v5
	v_cmp_ne_u32_e32 vcc, 0, v4
	v_readlane_b32 s0, v254, 53
	v_readlane_b32 s1, v254, 54
	v_mov_b32_e32 v4, vcc_lo
	s_nop 0
	v_cndmask_b32_e64 v2, v2, v4, s[0:1]
	v_mov_b32_e32 v4, vcc_hi
	v_cmp_eq_u32_e32 vcc, v39, v10
	v_cndmask_b32_e64 v3, v3, v4, s[0:1]
	s_nop 0
	v_mov_b32_e32 v4, vcc_hi
	v_mov_b32_e32 v5, vcc_lo
	v_cndmask_b32_e64 v4, v4, v5, s[6:7]
	v_and_b32_e32 v5, v4, v87
	v_bcnt_u32_b32 v5, v5, v0
	v_cmp_lt_u32_e64 s[0:1], v5, v23
	v_bcnt_u32_b32 v0, v4, v0
	s_nop 0
	v_cndmask_b32_e64 v5, 0, 1, s[0:1]
	v_cndmask_b32_e32 v5, v6, v5, vcc
	v_and_b32_e32 v4, 1, v5
	v_cmp_ne_u32_e32 vcc, 0, v4
	v_readlane_b32 s0, v254, 55
	v_readlane_b32 s1, v254, 56
	v_mov_b32_e32 v4, vcc_lo
	v_cndmask_b32_e64 v6, 0, 1, s[64:65]
	v_cndmask_b32_e64 v2, v2, v4, s[0:1]
	v_mov_b32_e32 v4, vcc_hi
	v_cmp_eq_u32_e32 vcc, v38, v10
	v_cndmask_b32_e64 v3, v3, v4, s[0:1]
	s_nop 0
	v_mov_b32_e32 v4, vcc_hi
; __device__ __forceinline__ void dsa_index_unit(const Ctx& c, int l, int b, int qb) {
;     ...
; #pragma unroll
;         for (int kt = 0; kt < 64; ++kt) {
;             const bool gt = key[kt] > T, eq = key[kt] == T;
;             const unsigned long long em = __ballot(eq);
;             const unsigned eh = hf ? (unsigned)(em >> 32) : (unsigned)em;
;             const bool take = gt || (eq && (eqbase + __popc(eh & below) < need));
;             eqbase += __popc(eh);
;             const unsigned long long sm = __ballot(take);
;             if (lane == kt) { mw0 = (unsigned)sm; mw1 = (unsigned)(sm >> 32); }
;         }
	v_mov_b32_e32 v5, vcc_lo
	v_cndmask_b32_e64 v4, v4, v5, s[6:7]
	v_and_b32_e32 v5, v4, v87
	v_bcnt_u32_b32 v5, v5, v0
	v_cmp_lt_u32_e64 s[0:1], v5, v23
	v_bcnt_u32_b32 v0, v4, v0
	s_nop 0
	v_cndmask_b32_e64 v5, 0, 1, s[0:1]
	v_cndmask_b32_e32 v5, v56, v5, vcc
	v_and_b32_e32 v4, 1, v5
	v_cmp_ne_u32_e32 vcc, 0, v4
	v_readlane_b32 s0, v254, 57
	v_readlane_b32 s1, v254, 58
	v_mov_b32_e32 v4, vcc_lo
	s_nop 0
	v_cndmask_b32_e64 v2, v2, v4, s[0:1]
	v_mov_b32_e32 v4, vcc_hi
	v_cmp_eq_u32_e32 vcc, v36, v10
	v_cndmask_b32_e64 v3, v3, v4, s[0:1]
	s_nop 0
	v_mov_b32_e32 v4, vcc_hi
	v_mov_b32_e32 v5, vcc_lo
	v_cndmask_b32_e64 v4, v4, v5, s[6:7]
	v_and_b32_e32 v5, v4, v87
	v_bcnt_u32_b32 v5, v5, v0
	v_cmp_lt_u32_e64 s[0:1], v5, v23
	v_bcnt_u32_b32 v0, v4, v0
	s_nop 0
	v_cndmask_b32_e64 v5, 0, 1, s[0:1]
	v_cndmask_b32_e32 v5, v6, v5, vcc
	v_and_b32_e32 v4, 1, v5
	v_cmp_ne_u32_e32 vcc, 0, v4
	v_readlane_b32 s0, v254, 59
	v_readlane_b32 s1, v254, 60
	v_mov_b32_e32 v4, vcc_lo
	v_cndmask_b32_e64 v6, 0, 1, s[62:63]
	v_cndmask_b32_e64 v2, v2, v4, s[0:1]
	v_mov_b32_e32 v4, vcc_hi
	v_cmp_eq_u32_e32 vcc, v35, v10
	v_cndmask_b32_e64 v3, v3, v4, s[0:1]
	s_nop 0
	v_mov_b32_e32 v4, vcc_hi
	v_mov_b32_e32 v5, vcc_lo
	v_cndmask_b32_e64 v4, v4, v5, s[6:7]
	v_and_b32_e32 v5, v4, v87
	v_bcnt_u32_b32 v5, v5, v0
	v_cmp_lt_u32_e64 s[0:1], v5, v23
	v_bcnt_u32_b32 v0, v4, v0
	s_nop 0
	v_cndmask_b32_e64 v5, 0, 1, s[0:1]
	v_cndmask_b32_e32 v5, v53, v5, vcc
	v_and_b32_e32 v4, 1, v5
	v_cmp_ne_u32_e32 vcc, 0, v4
	v_readlane_b32 s0, v254, 61
	v_readlane_b32 s1, v254, 62
	v_mov_b32_e32 v4, vcc_lo
	s_nop 0
	v_cndmask_b32_e64 v2, v2, v4, s[0:1]
	v_mov_b32_e32 v4, vcc_hi
	v_cmp_eq_u32_e32 vcc, v33, v10
	v_cndmask_b32_e64 v3, v3, v4, s[0:1]
	s_nop 0
	v_mov_b32_e32 v4, vcc_hi
	v_mov_b32_e32 v5, vcc_lo
	v_cndmask_b32_e64 v4, v4, v5, s[6:7]
	v_and_b32_e32 v5, v4, v87
	v_bcnt_u32_b32 v5, v5, v0
	v_cmp_lt_u32_e64 s[0:1], v5, v23
	v_bcnt_u32_b32 v0, v4, v0
	s_nop 0
	v_cndmask_b32_e64 v5, 0, 1, s[0:1]
	v_cndmask_b32_e32 v5, v6, v5, vcc
	v_and_b32_e32 v4, 1, v5
	v_cmp_ne_u32_e32 vcc, 0, v4
	v_readlane_b32 s0, v254, 63
	v_readlane_b32 s1, v255, 0
	v_mov_b32_e32 v4, vcc_lo
	v_cndmask_b32_e64 v6, 0, 1, s[60:61]
	v_cndmask_b32_e64 v2, v2, v4, s[0:1]
	v_mov_b32_e32 v4, vcc_hi
	v_cmp_eq_u32_e32 vcc, v32, v10
	v_cndmask_b32_e64 v3, v3, v4, s[0:1]
	s_nop 0
	v_mov_b32_e32 v4, vcc_hi
	v_mov_b32_e32 v5, vcc_lo
	v_cndmask_b32_e64 v4, v4, v5, s[6:7]
	v_and_b32_e32 v5, v4, v87
	v_bcnt_u32_b32 v5, v5, v0
	v_cmp_lt_u32_e64 s[0:1], v5, v23
	v_bcnt_u32_b32 v0, v4, v0
	s_nop 0
	v_cndmask_b32_e64 v5, 0, 1, s[0:1]
	v_cndmask_b32_e32 v5, v50, v5, vcc
	v_and_b32_e32 v4, 1, v5
	v_cmp_ne_u32_e32 vcc, 0, v4
	v_readlane_b32 s0, v255, 1
	v_readlane_b32 s1, v255, 2
	v_mov_b32_e32 v4, vcc_lo
	s_nop 0
	v_cndmask_b32_e64 v2, v2, v4, s[0:1]
	v_mov_b32_e32 v4, vcc_hi
	v_cmp_eq_u32_e32 vcc, v30, v10
	v_cndmask_b32_e64 v3, v3, v4, s[0:1]
	s_nop 0
	v_mov_b32_e32 v4, vcc_hi
	v_mov_b32_e32 v5, vcc_lo
	v_cndmask_b32_e64 v4, v4, v5, s[6:7]
	v_and_b32_e32 v5, v4, v87
	v_bcnt_u32_b32 v5, v5, v0
	v_cmp_lt_u32_e64 s[0:1], v5, v23
	v_bcnt_u32_b32 v0, v4, v0
	s_nop 0
	v_cndmask_b32_e64 v5, 0, 1, s[0:1]
	v_cndmask_b32_e32 v5, v6, v5, vcc
	v_and_b32_e32 v4, 1, v5
	v_cmp_ne_u32_e32 vcc, 0, v4
	v_readlane_b32 s0, v255, 3
	v_readlane_b32 s1, v255, 4
	v_mov_b32_e32 v4, vcc_lo
	v_cndmask_b32_e64 v6, 0, 1, s[58:59]
	v_cndmask_b32_e64 v2, v2, v4, s[0:1]
	v_mov_b32_e32 v4, vcc_hi
	v_cmp_eq_u32_e32 vcc, v29, v10
	v_cndmask_b32_e64 v3, v3, v4, s[0:1]
	s_nop 0
	v_mov_b32_e32 v4, vcc_hi
	v_mov_b32_e32 v5, vcc_lo
	v_cndmask_b32_e64 v4, v4, v5, s[6:7]
	v_and_b32_e32 v5, v4, v87
	v_bcnt_u32_b32 v5, v5, v0
	v_cmp_lt_u32_e64 s[0:1], v5, v23
	v_bcnt_u32_b32 v0, v4, v0
	s_nop 0
	v_cndmask_b32_e64 v5, 0, 1, s[0:1]
	v_cndmask_b32_e32 v5, v47, v5, vcc
	v_and_b32_e32 v4, 1, v5
	v_cmp_ne_u32_e32 vcc, 0, v4
	v_readlane_b32 s0, v255, 5
	v_readlane_b32 s1, v255, 6
	v_mov_b32_e32 v4, vcc_lo
	s_nop 0
	v_cndmask_b32_e64 v2, v2, v4, s[0:1]
	v_mov_b32_e32 v4, vcc_hi
	v_cmp_eq_u32_e32 vcc, v27, v10
	v_cndmask_b32_e64 v3, v3, v4, s[0:1]
	s_nop 0
	v_mov_b32_e32 v4, vcc_hi
	v_mov_b32_e32 v5, vcc_lo
	v_cndmask_b32_e64 v4, v4, v5, s[6:7]
	v_and_b32_e32 v5, v4, v87
	v_bcnt_u32_b32 v5, v5, v0
	v_cmp_lt_u32_e64 s[0:1], v5, v23
	v_bcnt_u32_b32 v0, v4, v0
	s_nop 0
	v_cndmask_b32_e64 v5, 0, 1, s[0:1]
	v_cndmask_b32_e32 v5, v6, v5, vcc
	v_and_b32_e32 v4, 1, v5
	v_cmp_ne_u32_e32 vcc, 0, v4
	v_readlane_b32 s0, v255, 7
	v_readlane_b32 s1, v255, 8
	v_mov_b32_e32 v4, vcc_lo
	v_cndmask_b32_e64 v6, 0, 1, s[56:57]
	v_cndmask_b32_e64 v2, v2, v4, s[0:1]
	v_mov_b32_e32 v4, vcc_hi
	v_cmp_eq_u32_e32 vcc, v26, v10
	v_cndmask_b32_e64 v3, v3, v4, s[0:1]
	s_nop 0
	v_mov_b32_e32 v4, vcc_hi
	v_mov_b32_e32 v5, vcc_lo
	v_cndmask_b32_e64 v4, v4, v5, s[6:7]
	v_and_b32_e32 v5, v4, v87
	v_bcnt_u32_b32 v5, v5, v0
	v_cmp_lt_u32_e64 s[0:1], v5, v23
	v_bcnt_u32_b32 v0, v4, v0
	s_nop 0
	v_cndmask_b32_e64 v5, 0, 1, s[0:1]
	v_cndmask_b32_e32 v5, v44, v5, vcc
	v_and_b32_e32 v4, 1, v5
	v_cmp_ne_u32_e32 vcc, 0, v4
	v_readlane_b32 s0, v255, 9
	v_readlane_b32 s1, v255, 10
	v_mov_b32_e32 v4, vcc_lo
	s_nop 0
	v_cndmask_b32_e64 v2, v2, v4, s[0:1]
	v_mov_b32_e32 v4, vcc_hi
	v_cmp_eq_u32_e32 vcc, v24, v10
	v_cndmask_b32_e64 v3, v3, v4, s[0:1]
	s_nop 0
	v_mov_b32_e32 v4, vcc_hi
	v_mov_b32_e32 v5, vcc_lo
	v_cndmask_b32_e64 v4, v4, v5, s[6:7]
	v_and_b32_e32 v5, v4, v87
	v_bcnt_u32_b32 v5, v5, v0
	v_cmp_lt_u32_e64 s[0:1], v5, v23
	v_bcnt_u32_b32 v0, v4, v0
	s_nop 0
	v_cndmask_b32_e64 v5, 0, 1, s[0:1]
	v_cndmask_b32_e32 v5, v6, v5, vcc
	v_and_b32_e32 v4, 1, v5
	v_cmp_ne_u32_e32 vcc, 0, v4
	v_readlane_b32 s0, v255, 11
; __device__ __forceinline__ void dsa_index_unit(const Ctx& c, int l, int b, int qb) {
;     ...
; #pragma unroll
;         for (int kt = 0; kt < 64; ++kt) {
;             const bool gt = key[kt] > T, eq = key[kt] == T;
;             const unsigned long long em = __ballot(eq);
;             const unsigned eh = hf ? (unsigned)(em >> 32) : (unsigned)em;
;             const bool take = gt || (eq && (eqbase + __popc(eh & below) < need));
;             eqbase += __popc(eh);
;             const unsigned long long sm = __ballot(take);
;             if (lane == kt) { mw0 = (unsigned)sm; mw1 = (unsigned)(sm >> 32); }
;         }
	v_readlane_b32 s1, v255, 12
	v_mov_b32_e32 v4, vcc_lo
	v_cndmask_b32_e64 v6, 0, 1, s[54:55]
	v_cndmask_b32_e64 v2, v2, v4, s[0:1]
	v_mov_b32_e32 v4, vcc_hi
	v_cmp_eq_u32_e32 vcc, v22, v10
	v_cndmask_b32_e64 v3, v3, v4, s[0:1]
	s_nop 0
	v_mov_b32_e32 v4, vcc_hi
	v_mov_b32_e32 v5, vcc_lo
	v_cndmask_b32_e64 v4, v4, v5, s[6:7]
	v_and_b32_e32 v5, v4, v87
	v_bcnt_u32_b32 v5, v5, v0
	v_cmp_lt_u32_e64 s[0:1], v5, v23
	v_bcnt_u32_b32 v0, v4, v0
	s_nop 0
	v_cndmask_b32_e64 v5, 0, 1, s[0:1]
	v_cndmask_b32_e32 v5, v41, v5, vcc
	v_and_b32_e32 v4, 1, v5
	v_cmp_ne_u32_e32 vcc, 0, v4
	v_readlane_b32 s0, v255, 13
	v_readlane_b32 s1, v255, 14
	v_mov_b32_e32 v4, vcc_lo
	s_nop 0
	v_cndmask_b32_e64 v2, v2, v4, s[0:1]
	v_mov_b32_e32 v4, vcc_hi
	v_cmp_eq_u32_e32 vcc, v21, v10
	v_cndmask_b32_e64 v3, v3, v4, s[0:1]
	s_nop 0
	v_mov_b32_e32 v4, vcc_hi
	v_mov_b32_e32 v5, vcc_lo
	v_cndmask_b32_e64 v4, v4, v5, s[6:7]
	v_and_b32_e32 v5, v4, v87
	v_bcnt_u32_b32 v5, v5, v0
	v_cmp_lt_u32_e64 s[0:1], v5, v23
	v_bcnt_u32_b32 v0, v4, v0
	s_nop 0
	v_cndmask_b32_e64 v5, 0, 1, s[0:1]
	v_cndmask_b32_e32 v5, v6, v5, vcc
	v_and_b32_e32 v4, 1, v5
	v_cmp_ne_u32_e32 vcc, 0, v4
	v_readlane_b32 s0, v255, 15
	v_readlane_b32 s1, v255, 16
	v_mov_b32_e32 v4, vcc_lo
	v_cndmask_b32_e64 v6, 0, 1, s[52:53]
	v_cndmask_b32_e64 v2, v2, v4, s[0:1]
	v_mov_b32_e32 v4, vcc_hi
	v_cmp_eq_u32_e32 vcc, v20, v10
	v_cndmask_b32_e64 v3, v3, v4, s[0:1]
	s_nop 0
	v_mov_b32_e32 v4, vcc_hi
	v_mov_b32_e32 v5, vcc_lo
	v_cndmask_b32_e64 v4, v4, v5, s[6:7]
	v_and_b32_e32 v5, v4, v87
	v_bcnt_u32_b32 v5, v5, v0
	v_cmp_lt_u32_e64 s[0:1], v5, v23
	v_bcnt_u32_b32 v0, v4, v0
	s_nop 0
	v_cndmask_b32_e64 v5, 0, 1, s[0:1]
	v_cndmask_b32_e32 v5, v37, v5, vcc
	v_and_b32_e32 v4, 1, v5
	v_cmp_ne_u32_e32 vcc, 0, v4
	v_readlane_b32 s0, v255, 17
	v_readlane_b32 s1, v255, 18
	v_mov_b32_e32 v4, vcc_lo
	s_nop 0
	v_cndmask_b32_e64 v2, v2, v4, s[0:1]
	v_mov_b32_e32 v4, vcc_hi
	v_cmp_eq_u32_e32 vcc, v19, v10
	v_cndmask_b32_e64 v3, v3, v4, s[0:1]
	s_nop 0
	v_mov_b32_e32 v4, vcc_hi
	v_mov_b32_e32 v5, vcc_lo
	v_cndmask_b32_e64 v4, v4, v5, s[6:7]
	v_and_b32_e32 v5, v4, v87
	v_bcnt_u32_b32 v5, v5, v0
	v_cmp_lt_u32_e64 s[0:1], v5, v23
	v_bcnt_u32_b32 v0, v4, v0
	s_nop 0
	v_cndmask_b32_e64 v5, 0, 1, s[0:1]
	v_cndmask_b32_e32 v5, v6, v5, vcc
	v_and_b32_e32 v4, 1, v5
	v_cmp_ne_u32_e32 vcc, 0, v4
	v_cndmask_b32_e64 v6, 0, 1, s[50:51]
	s_nop 0
	v_mov_b32_e32 v4, vcc_lo
	v_cndmask_b32_e64 v2, v2, v4, s[24:25]
	v_mov_b32_e32 v4, vcc_hi
	v_cmp_eq_u32_e32 vcc, v18, v10
	v_cndmask_b32_e64 v3, v3, v4, s[24:25]
	s_nop 0
	v_mov_b32_e32 v4, vcc_hi
	v_mov_b32_e32 v5, vcc_lo
	v_cndmask_b32_e64 v4, v4, v5, s[6:7]
	v_and_b32_e32 v5, v4, v87
	v_bcnt_u32_b32 v5, v5, v0
	v_cmp_lt_u32_e64 s[0:1], v5, v23
	v_bcnt_u32_b32 v0, v4, v0
	s_nop 0
	v_cndmask_b32_e64 v5, 0, 1, s[0:1]
	v_cndmask_b32_e32 v5, v34, v5, vcc
	v_and_b32_e32 v4, 1, v5
	v_cmp_ne_u32_e32 vcc, 0, v4
	s_nop 1
	v_mov_b32_e32 v4, vcc_lo
	v_cndmask_b32_e64 v2, v2, v4, s[26:27]
	v_mov_b32_e32 v4, vcc_hi
	v_cmp_eq_u32_e32 vcc, v16, v10
	v_cndmask_b32_e64 v3, v3, v4, s[26:27]
	s_nop 0
	v_mov_b32_e32 v4, vcc_hi
	v_mov_b32_e32 v5, vcc_lo
	v_cndmask_b32_e64 v4, v4, v5, s[6:7]
	v_and_b32_e32 v5, v4, v87
	v_bcnt_u32_b32 v5, v5, v0
	v_cmp_lt_u32_e64 s[0:1], v5, v23
	v_bcnt_u32_b32 v0, v4, v0
	s_nop 0
	v_cndmask_b32_e64 v5, 0, 1, s[0:1]
	v_cndmask_b32_e32 v5, v6, v5, vcc
	v_and_b32_e32 v4, 1, v5
	v_cmp_ne_u32_e32 vcc, 0, v4
	v_cndmask_b32_e64 v6, 0, 1, s[48:49]
	s_nop 0
	v_mov_b32_e32 v4, vcc_lo
	v_cndmask_b32_e64 v2, v2, v4, s[28:29]
	v_mov_b32_e32 v4, vcc_hi
	v_cmp_eq_u32_e32 vcc, v15, v10
	v_cndmask_b32_e64 v3, v3, v4, s[28:29]
	s_nop 0
	v_mov_b32_e32 v4, vcc_hi
	v_mov_b32_e32 v5, vcc_lo
	v_cndmask_b32_e64 v4, v4, v5, s[6:7]
	v_and_b32_e32 v5, v4, v87
	v_bcnt_u32_b32 v5, v5, v0
	v_cmp_lt_u32_e64 s[0:1], v5, v23
	v_bcnt_u32_b32 v0, v4, v0
	s_nop 0
	v_cndmask_b32_e64 v5, 0, 1, s[0:1]
	v_cndmask_b32_e32 v5, v31, v5, vcc
; __device__ __forceinline__ void dsa_index_unit(const Ctx& c, int l, int b, int qb) {
;     ...
; #pragma unroll
;         for (int kt = 0; kt < 64; ++kt) {
;             const bool gt = key[kt] > T, eq = key[kt] == T;
;             const unsigned long long em = __ballot(eq);
;             const unsigned eh = hf ? (unsigned)(em >> 32) : (unsigned)em;
;             const bool take = gt || (eq && (eqbase + __popc(eh & below) < need));
;             eqbase += __popc(eh);
;             const unsigned long long sm = __ballot(take);
;             if (lane == kt) { mw0 = (unsigned)sm; mw1 = (unsigned)(sm >> 32); }
;         }
;         MASKW[(size_t)(r0 + 2 * p) * 64 + lane] = mw0;
;         MASKW[(size_t)(r0 + 2 * p + 1) * 64 + lane] = mw1;
	v_and_b32_e32 v4, 1, v5
	v_cmp_ne_u32_e32 vcc, 0, v4
	s_nop 1
	v_mov_b32_e32 v4, vcc_lo
	v_cndmask_b32_e64 v2, v2, v4, s[30:31]
	v_mov_b32_e32 v4, vcc_hi
	v_cmp_eq_u32_e32 vcc, v14, v10
	v_cndmask_b32_e64 v3, v3, v4, s[30:31]
	s_nop 0
	v_mov_b32_e32 v4, vcc_hi
	v_mov_b32_e32 v5, vcc_lo
	v_cndmask_b32_e64 v4, v4, v5, s[6:7]
	v_and_b32_e32 v5, v4, v87
	v_bcnt_u32_b32 v5, v5, v0
	v_cmp_lt_u32_e64 s[0:1], v5, v23
	v_bcnt_u32_b32 v0, v4, v0
	s_nop 0
	v_cndmask_b32_e64 v5, 0, 1, s[0:1]
	v_cndmask_b32_e32 v5, v6, v5, vcc
	v_and_b32_e32 v4, 1, v5
	v_cmp_ne_u32_e32 vcc, 0, v4
	v_cndmask_b32_e64 v6, 0, 1, s[46:47]
	s_nop 0
	v_mov_b32_e32 v4, vcc_lo
	v_cndmask_b32_e64 v2, v2, v4, s[34:35]
	v_mov_b32_e32 v4, vcc_hi
	v_cmp_eq_u32_e32 vcc, v13, v10
	v_cndmask_b32_e64 v3, v3, v4, s[34:35]
	s_nop 0
	v_mov_b32_e32 v4, vcc_hi
	v_mov_b32_e32 v5, vcc_lo
	v_cndmask_b32_e64 v4, v4, v5, s[6:7]
	v_and_b32_e32 v5, v4, v87
	v_bcnt_u32_b32 v5, v5, v0
	v_cmp_lt_u32_e64 s[0:1], v5, v23
	v_bcnt_u32_b32 v0, v4, v0
	s_nop 0
	v_cndmask_b32_e64 v5, 0, 1, s[0:1]
	v_cndmask_b32_e32 v5, v28, v5, vcc
	v_and_b32_e32 v4, 1, v5
	v_cmp_ne_u32_e32 vcc, 0, v4
	s_nop 1
	v_mov_b32_e32 v4, vcc_lo
	v_cndmask_b32_e64 v2, v2, v4, s[36:37]
	v_mov_b32_e32 v4, vcc_hi
	v_cmp_eq_u32_e32 vcc, v12, v10
	v_cndmask_b32_e64 v3, v3, v4, s[36:37]
	s_nop 0
	v_mov_b32_e32 v4, vcc_hi
	v_mov_b32_e32 v5, vcc_lo
	v_cndmask_b32_e64 v4, v4, v5, s[6:7]
	v_and_b32_e32 v5, v4, v87
	v_bcnt_u32_b32 v5, v5, v0
	v_cmp_lt_u32_e64 s[0:1], v5, v23
	v_bcnt_u32_b32 v0, v4, v0
	s_nop 0
	v_cndmask_b32_e64 v5, 0, 1, s[0:1]
	v_cndmask_b32_e32 v5, v6, v5, vcc
	v_and_b32_e32 v4, 1, v5
	v_cmp_ne_u32_e32 vcc, 0, v4
	s_nop 1
	v_mov_b32_e32 v4, vcc_lo
	v_cndmask_b32_e64 v2, v2, v4, s[38:39]
	v_mov_b32_e32 v4, vcc_hi
	v_cmp_eq_u32_e32 vcc, v11, v10
	v_cndmask_b32_e64 v3, v3, v4, s[38:39]
	s_nop 0
	v_mov_b32_e32 v4, vcc_hi
	v_mov_b32_e32 v5, vcc_lo
	v_cndmask_b32_e64 v4, v4, v5, s[6:7]
	v_and_b32_e32 v5, v4, v87
	v_bcnt_u32_b32 v5, v5, v0
	v_cmp_lt_u32_e64 s[0:1], v5, v23
	v_bcnt_u32_b32 v4, v4, 0
	s_nop 0
	v_cndmask_b32_e64 v5, 0, 1, s[0:1]
	v_cndmask_b32_e32 v5, v25, v5, vcc
	v_and_b32_e32 v5, 1, v5
	v_cmp_ne_u32_e32 vcc, 0, v5
	s_nop 1
	v_mov_b32_e32 v5, vcc_lo
	v_cndmask_b32_e64 v2, v2, v5, s[40:41]
	v_mov_b32_e32 v5, vcc_hi
	v_cmp_eq_u32_e32 vcc, v1, v10
	v_cndmask_b32_e64 v3, v3, v5, s[40:41]
	s_nop 0
	v_mov_b32_e32 v1, vcc_hi
	v_mov_b32_e32 v5, vcc_lo
	v_cndmask_b32_e64 v1, v1, v5, s[6:7]
	v_and_b32_e32 v1, v1, v87
	v_bcnt_u32_b32 v1, v1, 0
	v_add3_u32 v0, v4, v0, v1
	v_cmp_lt_u32_e64 s[0:1], v0, v23
	v_cndmask_b32_e64 v1, 0, 1, s[44:45]
	s_nop 0
	v_cndmask_b32_e64 v0, 0, 1, s[0:1]
	v_cndmask_b32_e32 v0, v1, v0, vcc
	v_and_b32_e32 v0, 1, v0
	v_cmp_ne_u32_e32 vcc, 0, v0
	s_lshl_b64 s[0:1], s[2:3], 8
	s_nop 0
	v_mov_b32_e32 v0, vcc_lo
	v_cndmask_b32_e64 v4, v2, v0, s[42:43]
	v_mov_b32_e32 v0, vcc_hi
	v_cndmask_b32_e64 v2, v3, v0, s[42:43]
	v_lshl_add_u64 v[0:1], v[74:75], 0, s[0:1]
	s_or_b32 s0, s2, 1
	s_ashr_i32 s1, s0, 31
	v_readlane_b32 s2, v250, 8
	s_lshl_b64 s[0:1], s[0:1], 8
	v_readlane_b32 s3, v250, 9
	global_store_dword v[0:1], v4, off
	v_lshl_add_u64 v[0:1], v[74:75], 0, s[0:1]
	s_mov_b64 s[0:1], 0
	s_and_b64 vcc, exec, s[2:3]
	global_store_dword v[0:1], v2, off
	s_cbranch_vccz .LBB0_1106
	v_readlane_b32 s36, v250, 12
	v_readlane_b32 s37, v250, 13
	v_readlane_b32 s34, v252, 9
	v_readlane_b32 s8, v252, 15
	s_mov_b64 s[2:3], 0
	v_readlane_b32 s39, v250, 7
	v_readlane_b32 s24, v252, 8
	v_readlane_b32 s35, v252, 10
	v_readlane_b32 s25, v252, 11
	v_readlane_b32 s26, v252, 12
	s_mov_b32 s27, 0x12000
	s_mov_b32 s28, 0x800000
	s_mov_b32 s29, 0x41a00000
	s_mov_b32 s30, 0x3fb8aa3b
	s_mov_b32 s31, 0xc2ce8ed0
	s_mov_b32 s40, 0x42b17218
	s_mov_b32 s38, 0xbfb8aa3b
	s_mov_b32 s41, 0x42ce8ed0
	s_mov_b32 s42, 0xc2b17218
	s_mov_b32 s43, 0x10100
	v_readlane_b32 s37, v252, 13
	v_readlane_b32 s10, v252, 14
	v_readlane_b32 s9, v252, 16

; __device__ __forceinline__ void dsa_index_unit(const Ctx& c, int l, int b, int qb) {
;     ...
;         unsigned key[64];
; #pragma unroll
;         for (int kt = 0; kt < 64; ++kt) { const unsigned kv = sk[kt * 64 + lane]; key[kt] = (kt <= qb) ? kv : 0u; }
.Lix1_done:
	s_waitcnt vmcnt(0)
	ds_read2st64_b32 v[8:9], v67 offset1:1
	ds_read2st64_b32 v[6:7], v67 offset0:2 offset1:3
	ds_read2st64_b32 v[4:5], v67 offset0:4 offset1:5
	ds_read2st64_b32 v[2:3], v67 offset0:6 offset1:7
	ds_read2st64_b32 v[0:1], v67 offset0:8 offset1:9
	ds_read2st64_b32 v[10:11], v67 offset0:10 offset1:11
	ds_read2st64_b32 v[102:103], v67 offset0:62 offset1:63
	v_readlane_b32 s0, v250, 22
	v_readlane_b32 s1, v250, 23
	s_mov_b32 s22, s11
	s_mov_b64 s[20:21], s[90:91]
	s_waitcnt lgkmcnt(2)
	v_cndmask_b32_e64 v101, v1, 0, s[0:1]
	v_readlane_b32 s0, v250, 16
	v_readlane_b32 s1, v250, 17
	s_waitcnt lgkmcnt(1)
	s_nop 0
	v_cndmask_b32_e64 v99, v10, 0, s[0:1]
	v_readlane_b32 s0, v250, 18
	v_readlane_b32 s1, v250, 19
	s_nop 1
	v_cndmask_b32_e64 v98, v11, 0, s[0:1]
	ds_read2st64_b32 v[10:11], v67 offset0:12 offset1:13
	v_readlane_b32 s0, v250, 26
	v_readlane_b32 s1, v250, 27
	s_waitcnt lgkmcnt(0)
	s_nop 0
	v_cndmask_b32_e64 v96, v10, 0, s[0:1]
	v_readlane_b32 s0, v250, 28
	v_readlane_b32 s1, v250, 29
	s_nop 1
	v_cndmask_b32_e64 v95, v11, 0, s[0:1]
	ds_read2st64_b32 v[10:11], v67 offset0:14 offset1:15
	v_readlane_b32 s0, v250, 30
	v_readlane_b32 s1, v250, 31
	s_waitcnt lgkmcnt(0)
	s_nop 0
	v_cndmask_b32_e64 v93, v10, 0, s[0:1]
	v_readlane_b32 s0, v250, 24
	v_readlane_b32 s1, v250, 25
	s_nop 1
	v_cndmask_b32_e64 v92, v11, 0, s[0:1]
	ds_read2st64_b32 v[10:11], v67 offset0:16 offset1:17
	v_readlane_b32 s0, v250, 40
	v_readlane_b32 s1, v250, 41
	s_waitcnt lgkmcnt(0)
	s_nop 0
	v_cndmask_b32_e64 v90, v10, 0, s[0:1]
	v_readlane_b32 s0, v250, 32
	v_readlane_b32 s1, v250, 33
	s_nop 1
	v_cndmask_b32_e64 v89, v11, 0, s[0:1]
	ds_read2st64_b32 v[10:11], v67 offset0:18 offset1:19
	v_readlane_b32 s0, v250, 10
	v_readlane_b32 s1, v250, 11
	s_waitcnt lgkmcnt(0)
	s_nop 0
	v_cndmask_b32_e64 v85, v10, 0, s[0:1]
	v_readlane_b32 s0, v250, 14
	v_readlane_b32 s1, v250, 15
	s_nop 1
	v_cndmask_b32_e64 v84, v11, 0, s[0:1]
	ds_read2st64_b32 v[10:11], v67 offset0:20 offset1:21
	v_readlane_b32 s0, v250, 34
	v_readlane_b32 s1, v250, 35
	s_waitcnt lgkmcnt(0)
	s_nop 0
	v_cndmask_b32_e64 v83, v10, 0, s[0:1]
	v_readlane_b32 s0, v250, 36
	v_readlane_b32 s1, v250, 37
	s_nop 1
	v_cndmask_b32_e64 v81, v11, 0, s[0:1]
	ds_read2st64_b32 v[10:11], v67 offset0:22 offset1:23
	v_readlane_b32 s0, v250, 38
	v_readlane_b32 s1, v250, 39
	s_waitcnt lgkmcnt(0)
	s_nop 0
	v_cndmask_b32_e64 v80, v10, 0, s[0:1]
	v_readlane_b32 s0, v252, 17
	v_readlane_b32 s1, v252, 18
	s_nop 1
	v_cndmask_b32_e64 v78, v11, 0, s[0:1]
	ds_read2st64_b32 v[10:11], v67 offset0:24 offset1:25
	v_readlane_b32 s0, v252, 19
	v_readlane_b32 s1, v252, 20
	s_waitcnt lgkmcnt(0)
	s_nop 0
	v_cndmask_b32_e64 v77, v10, 0, s[0:1]
	v_readlane_b32 s0, v252, 21
	v_readlane_b32 s1, v252, 22
	s_nop 1
	v_cndmask_b32_e64 v76, v11, 0, s[0:1]
	ds_read2st64_b32 v[10:11], v67 offset0:26 offset1:27
	v_readlane_b32 s0, v252, 23
	v_readlane_b32 s1, v252, 24
	s_waitcnt lgkmcnt(0)
	s_nop 0
	v_cndmask_b32_e64 v61, v10, 0, s[0:1]
	v_readlane_b32 s0, v252, 25
	v_readlane_b32 s1, v252, 26
	s_nop 1
	v_cndmask_b32_e64 v60, v11, 0, s[0:1]
	ds_read2st64_b32 v[10:11], v67 offset0:28 offset1:29
	v_readlane_b32 s0, v252, 27
	v_readlane_b32 s1, v252, 28
	s_waitcnt lgkmcnt(0)
	s_nop 0
	v_cndmask_b32_e64 v58, v10, 0, s[0:1]
	v_readlane_b32 s0, v252, 29
	v_readlane_b32 s1, v252, 30
	s_nop 1
	v_cndmask_b32_e64 v57, v11, 0, s[0:1]
	ds_read2st64_b32 v[10:11], v67 offset0:30 offset1:31
	v_readlane_b32 s0, v252, 31
	v_readlane_b32 s1, v252, 32
	s_waitcnt lgkmcnt(0)
	s_nop 0
	v_cndmask_b32_e64 v55, v10, 0, s[0:1]
	v_readlane_b32 s0, v252, 33
	v_readlane_b32 s1, v252, 34
	s_nop 1
	v_cndmask_b32_e64 v54, v11, 0, s[0:1]
	ds_read2st64_b32 v[10:11], v67 offset0:32 offset1:33
	v_readlane_b32 s0, v252, 35
	v_readlane_b32 s1, v252, 36
	s_waitcnt lgkmcnt(0)
	s_nop 0
	v_cndmask_b32_e64 v52, v10, 0, s[0:1]
	v_readlane_b32 s0, v252, 37
	v_readlane_b32 s1, v252, 38
	s_nop 1
	v_cndmask_b32_e64 v51, v11, 0, s[0:1]
	ds_read2st64_b32 v[10:11], v67 offset0:34 offset1:35
	v_readlane_b32 s0, v252, 39
	v_readlane_b32 s1, v252, 40
	s_waitcnt lgkmcnt(0)
	s_nop 0
	v_cndmask_b32_e64 v49, v10, 0, s[0:1]
	v_readlane_b32 s0, v252, 41
	v_readlane_b32 s1, v252, 42
	s_nop 1
	v_cndmask_b32_e64 v48, v11, 0, s[0:1]
	ds_read2st64_b32 v[10:11], v67 offset0:36 offset1:37
	v_readlane_b32 s0, v252, 43
	v_readlane_b32 s1, v252, 44
	s_waitcnt lgkmcnt(0)
	s_nop 0
	v_cndmask_b32_e64 v46, v10, 0, s[0:1]
	v_readlane_b32 s0, v252, 45
	v_readlane_b32 s1, v252, 46
	s_nop 1
	v_cndmask_b32_e64 v45, v11, 0, s[0:1]
	ds_read2st64_b32 v[10:11], v67 offset0:38 offset1:39
	v_readlane_b32 s0, v252, 47
	v_readlane_b32 s1, v252, 48
	s_waitcnt lgkmcnt(0)
	s_nop 0
	v_cndmask_b32_e64 v43, v10, 0, s[0:1]
	v_readlane_b32 s0, v252, 49
	v_readlane_b32 s1, v252, 50
	s_nop 1
	v_cndmask_b32_e64 v42, v11, 0, s[0:1]
	ds_read2st64_b32 v[10:11], v67 offset0:40 offset1:41
	v_readlane_b32 s0, v252, 51
	v_readlane_b32 s1, v252, 52
	s_waitcnt lgkmcnt(0)
	s_nop 0
	v_cndmask_b32_e64 v40, v10, 0, s[0:1]
	v_readlane_b32 s0, v252, 53
	v_readlane_b32 s1, v252, 54
	s_nop 1
	v_cndmask_b32_e64 v39, v11, 0, s[0:1]
	ds_read2st64_b32 v[10:11], v67 offset0:42 offset1:43
	v_readlane_b32 s0, v252, 55
	v_readlane_b32 s1, v252, 56
	s_waitcnt lgkmcnt(0)
	s_nop 0
	v_cndmask_b32_e64 v38, v10, 0, s[0:1]
	v_readlane_b32 s0, v252, 57
	v_readlane_b32 s1, v252, 58
	s_nop 1
	v_cndmask_b32_e64 v36, v11, 0, s[0:1]
	ds_read2st64_b32 v[10:11], v67 offset0:44 offset1:45
	v_readlane_b32 s0, v252, 59
	v_readlane_b32 s1, v252, 60
	s_waitcnt lgkmcnt(0)
; __device__ __forceinline__ void dsa_index_unit(const Ctx& c, int l, int b, int qb) {
;     ...
;         for (int kt = 0; kt < 64; ++kt) { const unsigned kv = sk[kt * 64 + lane]; key[kt] = (kt <= qb) ? kv : 0u; }
;         unsigned T = 0u;
; #pragma unroll 1
;     ...
;             const unsigned cand = T | (1u << bit);
;             int cnt = 0;
; #pragma unroll
;             for (int kt = 0; kt < 64; ++kt) cnt += (key[kt] >= cand) ? 1 : 0;
	s_nop 0
	v_cndmask_b32_e64 v35, v10, 0, s[0:1]
	v_readlane_b32 s0, v252, 61
	v_readlane_b32 s1, v252, 62
	s_nop 1
	v_cndmask_b32_e64 v33, v11, 0, s[0:1]
	ds_read2st64_b32 v[10:11], v67 offset0:46 offset1:47
	v_readlane_b32 s0, v252, 63
	v_readlane_b32 s1, v253, 0
	s_waitcnt lgkmcnt(0)
	s_nop 0
	v_cndmask_b32_e64 v32, v10, 0, s[0:1]
	v_readlane_b32 s0, v253, 1
	v_readlane_b32 s1, v253, 2
	s_nop 1
	v_cndmask_b32_e64 v30, v11, 0, s[0:1]
	ds_read2st64_b32 v[10:11], v67 offset0:48 offset1:49
	v_readlane_b32 s0, v253, 3
	v_readlane_b32 s1, v253, 4
	s_waitcnt lgkmcnt(0)
	s_nop 0
	v_cndmask_b32_e64 v29, v10, 0, s[0:1]
	v_readlane_b32 s0, v253, 5
	v_readlane_b32 s1, v253, 6
	s_nop 1
	v_cndmask_b32_e64 v27, v11, 0, s[0:1]
	ds_read2st64_b32 v[10:11], v67 offset0:50 offset1:51
	v_readlane_b32 s0, v253, 7
	v_readlane_b32 s1, v253, 8
	s_waitcnt lgkmcnt(0)
	s_nop 0
	v_cndmask_b32_e64 v26, v10, 0, s[0:1]
	v_readlane_b32 s0, v253, 9
	v_readlane_b32 s1, v253, 10
	s_nop 1
	v_cndmask_b32_e64 v24, v11, 0, s[0:1]
	ds_read2st64_b32 v[10:11], v67 offset0:52 offset1:53
	v_readlane_b32 s0, v253, 11
	v_readlane_b32 s1, v253, 12
	s_waitcnt lgkmcnt(0)
	s_nop 0
	v_cndmask_b32_e64 v22, v10, 0, s[0:1]
	v_readlane_b32 s0, v253, 13
	v_readlane_b32 s1, v253, 14
	s_nop 1
	v_cndmask_b32_e64 v21, v11, 0, s[0:1]
	ds_read2st64_b32 v[10:11], v67 offset0:54 offset1:55
	v_readlane_b32 s0, v253, 15
	v_readlane_b32 s1, v253, 16
	s_waitcnt lgkmcnt(0)
	s_nop 0
	v_cndmask_b32_e64 v20, v10, 0, s[0:1]
	v_readlane_b32 s0, v253, 17
	v_readlane_b32 s1, v253, 18
	s_nop 1
	v_cndmask_b32_e64 v19, v11, 0, s[0:1]
	ds_read2st64_b32 v[10:11], v67 offset0:56 offset1:57
	v_readlane_b32 s0, v253, 19
	v_readlane_b32 s1, v253, 20
	s_waitcnt lgkmcnt(0)
	s_nop 0
	v_cndmask_b32_e64 v18, v10, 0, s[0:1]
	v_readlane_b32 s0, v253, 21
	v_readlane_b32 s1, v253, 22
	s_nop 1
	v_cndmask_b32_e64 v16, v11, 0, s[0:1]
	ds_read2st64_b32 v[10:11], v67 offset0:58 offset1:59
	v_readlane_b32 s0, v253, 23
	v_readlane_b32 s1, v253, 24
	s_waitcnt lgkmcnt(0)
	s_nop 0
	v_cndmask_b32_e64 v15, v10, 0, s[0:1]
	v_readlane_b32 s0, v253, 25
	v_readlane_b32 s1, v253, 26
	s_nop 1
	v_cndmask_b32_e64 v14, v11, 0, s[0:1]
	ds_read2st64_b32 v[10:11], v67 offset0:60 offset1:61
	v_readlane_b32 s0, v253, 27
	v_readlane_b32 s1, v253, 28
	s_waitcnt lgkmcnt(0)
	s_nop 0
	v_cndmask_b32_e64 v13, v10, 0, s[0:1]
	v_readlane_b32 s0, v253, 29
	v_readlane_b32 s1, v253, 30
	v_mov_b32_e32 v10, 0
	s_nop 0
	v_cndmask_b32_e64 v12, v11, 0, s[0:1]
	v_readlane_b32 s0, v253, 31
	v_readlane_b32 s1, v253, 32
	s_nop 1
	v_cndmask_b32_e64 v11, v102, 0, s[0:1]
	v_readlane_b32 s0, v253, 33
	v_readlane_b32 s1, v253, 34
	s_nop 1
	v_cndmask_b32_e64 v1, 0, v103, s[0:1]
	s_mov_b32 s0, 31
	s_mov_b64 s[46:47], 0
.LBB0_2632:
	v_lshl_or_b32 v23, 1, s0, v10
	v_cmp_ge_u32_e32 vcc, v9, v23
	s_add_i32 s0, s0, -1
	s_nop 0
	v_cndmask_b32_e64 v25, 0, 1, vcc
	v_cmp_ge_u32_e32 vcc, v8, v23
	s_nop 1
	v_addc_co_u32_e32 v25, vcc, 0, v25, vcc
	v_cmp_ge_u32_e32 vcc, v6, v23
	s_nop 1
	v_cndmask_b32_e64 v28, 0, 1, vcc
	v_cmp_ge_u32_e32 vcc, v7, v23
	s_nop 1
	v_addc_co_u32_e32 v25, vcc, v25, v28, vcc
	v_cmp_ge_u32_e32 vcc, v4, v23
	s_nop 1
	v_cndmask_b32_e64 v28, 0, 1, vcc
	v_cmp_ge_u32_e32 vcc, v5, v23
	s_nop 1
	v_addc_co_u32_e32 v25, vcc, v25, v28, vcc
	v_cmp_ge_u32_e32 vcc, v2, v23
	s_nop 1
	v_cndmask_b32_e64 v28, 0, 1, vcc
	v_cmp_ge_u32_e32 vcc, v3, v23
	s_nop 1
	v_addc_co_u32_e32 v25, vcc, v25, v28, vcc
	v_cmp_ge_u32_e32 vcc, v0, v23
	s_nop 1
	v_cndmask_b32_e64 v28, 0, 1, vcc
	v_cmp_ge_u32_e32 vcc, v101, v23
	s_nop 1
	v_addc_co_u32_e32 v25, vcc, v25, v28, vcc
	v_cmp_ge_u32_e32 vcc, v99, v23
	s_nop 1
	v_cndmask_b32_e64 v28, 0, 1, vcc
	v_cmp_ge_u32_e32 vcc, v98, v23
	s_nop 1
	v_addc_co_u32_e32 v25, vcc, v25, v28, vcc
	v_cmp_ge_u32_e32 vcc, v96, v23
	s_nop 1
	v_cndmask_b32_e64 v28, 0, 1, vcc
	v_cmp_ge_u32_e32 vcc, v95, v23
	s_nop 1
	v_addc_co_u32_e32 v25, vcc, v25, v28, vcc
	v_cmp_ge_u32_e32 vcc, v93, v23
	s_nop 1
	v_cndmask_b32_e64 v28, 0, 1, vcc
	v_cmp_ge_u32_e32 vcc, v92, v23
	s_nop 1
	v_addc_co_u32_e32 v25, vcc, v25, v28, vcc
	v_cmp_ge_u32_e32 vcc, v90, v23
	s_nop 1
	v_cndmask_b32_e64 v28, 0, 1, vcc
	v_cmp_ge_u32_e32 vcc, v89, v23
	s_nop 1
	v_addc_co_u32_e32 v25, vcc, v25, v28, vcc
	v_cmp_ge_u32_e32 vcc, v85, v23
	s_nop 1
	v_cndmask_b32_e64 v28, 0, 1, vcc
	v_cmp_ge_u32_e32 vcc, v84, v23
	s_nop 1
	v_addc_co_u32_e32 v25, vcc, v25, v28, vcc
	v_cmp_ge_u32_e32 vcc, v83, v23
	s_nop 1
	v_cndmask_b32_e64 v28, 0, 1, vcc
	v_cmp_ge_u32_e32 vcc, v81, v23
	s_nop 1
	v_addc_co_u32_e32 v25, vcc, v25, v28, vcc
	v_cmp_ge_u32_e32 vcc, v80, v23
	s_nop 1
	v_cndmask_b32_e64 v28, 0, 1, vcc
	v_cmp_ge_u32_e32 vcc, v78, v23
	s_nop 1
	v_addc_co_u32_e32 v25, vcc, v25, v28, vcc
	v_cmp_ge_u32_e32 vcc, v77, v23
	s_nop 1
	v_cndmask_b32_e64 v28, 0, 1, vcc
	v_cmp_ge_u32_e32 vcc, v76, v23
	s_nop 1
	v_addc_co_u32_e32 v25, vcc, v25, v28, vcc
	v_cmp_ge_u32_e32 vcc, v61, v23
	s_nop 1
	v_cndmask_b32_e64 v28, 0, 1, vcc
	v_cmp_ge_u32_e32 vcc, v60, v23
	s_nop 1
	v_addc_co_u32_e32 v25, vcc, v25, v28, vcc
	v_cmp_ge_u32_e32 vcc, v58, v23
	s_nop 1
	v_cndmask_b32_e64 v28, 0, 1, vcc
	v_cmp_ge_u32_e32 vcc, v57, v23
	s_nop 1
	v_addc_co_u32_e32 v25, vcc, v25, v28, vcc
	v_cmp_ge_u32_e32 vcc, v55, v23
	s_nop 1
	v_cndmask_b32_e64 v28, 0, 1, vcc
	v_cmp_ge_u32_e32 vcc, v54, v23
	s_nop 1
	v_addc_co_u32_e32 v25, vcc, v25, v28, vcc
	v_cmp_ge_u32_e32 vcc, v52, v23
	s_nop 1
	v_cndmask_b32_e64 v28, 0, 1, vcc
	v_cmp_ge_u32_e32 vcc, v51, v23
	s_nop 1
	v_addc_co_u32_e32 v25, vcc, v25, v28, vcc
	v_cmp_ge_u32_e32 vcc, v49, v23
	s_nop 1
	v_cndmask_b32_e64 v28, 0, 1, vcc
	v_cmp_ge_u32_e32 vcc, v48, v23
	s_nop 1
	v_addc_co_u32_e32 v25, vcc, v25, v28, vcc
; __device__ __forceinline__ int half_sum_i(int v, int hf) { v = row16_sum_i(v); const int a = __builtin_amdgcn_readlane(v, 0) + __builtin_amdgcn_readlane(v, 16), b = __builtin_amdgcn_readlane(v, 32) + __builtin_amdgcn_readlane(v, 48); return hf ? b : a; }
; __device__ __forceinline__ void dsa_index_unit(const Ctx& c, int l, int b, int qb) {
;     ...
; #pragma unroll 1
;     ...
;             const unsigned cand = T | (1u << bit);
;             int cnt = 0;
; #pragma unroll
;             for (int kt = 0; kt < 64; ++kt) cnt += (key[kt] >= cand) ? 1 : 0;
;             cnt = half_sum_i(cnt, hf);
;             if (cnt >= 256) T = cand;
;         }
;         int cg = 0;
; #pragma unroll
;         for (int kt = 0; kt < 64; ++kt) cg += (key[kt] > T) ? 1 : 0;
;         cg = half_sum_i(cg, hf);
	v_cmp_ge_u32_e32 vcc, v46, v23
	s_nop 1
	v_cndmask_b32_e64 v28, 0, 1, vcc
	v_cmp_ge_u32_e32 vcc, v45, v23
	s_nop 1
	v_addc_co_u32_e32 v25, vcc, v25, v28, vcc
	v_cmp_ge_u32_e32 vcc, v43, v23
	s_nop 1
	v_cndmask_b32_e64 v28, 0, 1, vcc
	v_cmp_ge_u32_e32 vcc, v42, v23
	s_nop 1
	v_addc_co_u32_e32 v25, vcc, v25, v28, vcc
	v_cmp_ge_u32_e32 vcc, v40, v23
	s_nop 1
	v_cndmask_b32_e64 v28, 0, 1, vcc
	v_cmp_ge_u32_e32 vcc, v39, v23
	s_nop 1
	v_addc_co_u32_e32 v25, vcc, v25, v28, vcc
	v_cmp_ge_u32_e32 vcc, v38, v23
	s_nop 1
	v_cndmask_b32_e64 v28, 0, 1, vcc
	v_cmp_ge_u32_e32 vcc, v36, v23
	s_nop 1
	v_addc_co_u32_e32 v25, vcc, v25, v28, vcc
	v_cmp_ge_u32_e32 vcc, v35, v23
	s_nop 1
	v_cndmask_b32_e64 v28, 0, 1, vcc
	v_cmp_ge_u32_e32 vcc, v33, v23
	s_nop 1
	v_addc_co_u32_e32 v25, vcc, v25, v28, vcc
	v_cmp_ge_u32_e32 vcc, v32, v23
	s_nop 1
	v_cndmask_b32_e64 v28, 0, 1, vcc
	v_cmp_ge_u32_e32 vcc, v30, v23
	s_nop 1
	v_addc_co_u32_e32 v25, vcc, v25, v28, vcc
	v_cmp_ge_u32_e32 vcc, v29, v23
	s_nop 1
	v_cndmask_b32_e64 v28, 0, 1, vcc
	v_cmp_ge_u32_e32 vcc, v27, v23
	s_nop 1
	v_addc_co_u32_e32 v25, vcc, v25, v28, vcc
	v_cmp_ge_u32_e32 vcc, v26, v23
	s_nop 1
	v_cndmask_b32_e64 v28, 0, 1, vcc
	v_cmp_ge_u32_e32 vcc, v24, v23
	s_nop 1
	v_addc_co_u32_e32 v25, vcc, v25, v28, vcc
	v_cmp_ge_u32_e32 vcc, v22, v23
	s_nop 1
	v_cndmask_b32_e64 v28, 0, 1, vcc
	v_cmp_ge_u32_e32 vcc, v21, v23
	s_nop 1
	v_addc_co_u32_e32 v25, vcc, v25, v28, vcc
	v_cmp_ge_u32_e32 vcc, v20, v23
	s_nop 1
	v_cndmask_b32_e64 v28, 0, 1, vcc
	v_cmp_ge_u32_e32 vcc, v19, v23
	s_nop 1
	v_addc_co_u32_e32 v25, vcc, v25, v28, vcc
	v_cmp_ge_u32_e32 vcc, v18, v23
	s_nop 1
	v_cndmask_b32_e64 v28, 0, 1, vcc
	v_cmp_ge_u32_e32 vcc, v16, v23
	s_nop 1
	v_addc_co_u32_e32 v25, vcc, v25, v28, vcc
	v_cmp_ge_u32_e32 vcc, v15, v23
	s_nop 1
	v_cndmask_b32_e64 v28, 0, 1, vcc
	v_cmp_ge_u32_e32 vcc, v14, v23
	s_nop 1
	v_addc_co_u32_e32 v25, vcc, v25, v28, vcc
	v_cmp_ge_u32_e32 vcc, v13, v23
	s_nop 1
	v_cndmask_b32_e64 v28, 0, 1, vcc
	v_cmp_ge_u32_e32 vcc, v12, v23
	s_nop 1
	v_addc_co_u32_e32 v25, vcc, v25, v28, vcc
	v_cmp_ge_u32_e32 vcc, v11, v23
	s_nop 1
	v_cndmask_b32_e64 v28, 0, 1, vcc
	v_cmp_ge_u32_e32 vcc, v1, v23
	s_nop 1
	v_addc_co_u32_e32 v25, vcc, v25, v28, vcc
	s_nop 1
	v_add_u32_dpp v25, v25, v25 quad_perm:[1,0,3,2] row_mask:0xf bank_mask:0xf bound_ctrl:1
	s_nop 1
	v_add_u32_dpp v25, v25, v25 quad_perm:[2,3,0,1] row_mask:0xf bank_mask:0xf bound_ctrl:1
	s_nop 1
	v_add_u32_dpp v25, v25, v25 row_half_mirror row_mask:0xf bank_mask:0xf bound_ctrl:1
	s_nop 1
	v_add_u32_dpp v25, v25, v25 row_mirror row_mask:0xf bank_mask:0xf bound_ctrl:1
	s_nop 0
	v_readlane_b32 s1, v25, 0
	v_readlane_b32 s2, v25, 16
	s_add_i32 s1, s2, s1
	v_readlane_b32 s2, v25, 32
	v_readlane_b32 s3, v25, 48
	s_add_i32 s2, s3, s2
	v_mov_b32_e32 v25, s2
	v_mov_b32_e32 v28, s1
	v_cndmask_b32_e64 v25, v25, v28, s[6:7]
	s_movk_i32 s1, 0xff
	v_cmp_lt_i32_e32 vcc, s1, v25
	s_movk_i32 s45, 0x100
	s_nop 0
	v_cndmask_b32_e32 v10, v10, v23, vcc
	v_cmp_eq_u32_e64 s[48:49], s45, v25
	s_nop 3
	s_or_b64 s[46:47], s[46:47], s[48:49]
	s_cmp_eq_u64 s[46:47], exec
	s_cbranch_scc1 .Lb1_bitdone
	s_cmp_eq_u32 s0, -1
	s_cbranch_scc0 .LBB0_2632
.Lb1_bitdone:
	v_cmp_gt_u32_e32 vcc, v9, v10
	v_cmp_gt_u32_e64 s[10:11], v8, v10
	v_cmp_gt_u32_e64 s[8:9], v7, v10
	v_cndmask_b32_e64 v113, 0, 1, vcc
	v_addc_co_u32_e64 v23, vcc, 0, v113, s[10:11]
	v_cmp_gt_u32_e32 vcc, v6, v10
	v_cmp_gt_u32_e64 s[4:5], v5, v10
	v_cmp_gt_u32_e64 s[0:1], v3, v10
	v_cndmask_b32_e64 v112, 0, 1, vcc
	v_addc_co_u32_e64 v23, vcc, v23, v112, s[8:9]
	v_cmp_gt_u32_e32 vcc, v4, v10
	v_cmp_gt_u32_e64 s[12:13], v101, v10
	v_cmp_gt_u32_e64 s[96:97], v98, v10
	v_cndmask_b32_e64 v111, 0, 1, vcc
	v_addc_co_u32_e64 v23, vcc, v23, v111, s[4:5]
	v_cmp_gt_u32_e32 vcc, v2, v10
	v_cmp_gt_u32_e64 s[94:95], v95, v10
	v_cmp_gt_u32_e64 s[92:93], v92, v10
	v_cndmask_b32_e64 v110, 0, 1, vcc
	v_addc_co_u32_e64 v23, vcc, v23, v110, s[0:1]
	v_cmp_gt_u32_e32 vcc, v0, v10
	v_cmp_gt_u32_e64 s[90:91], v89, v10
	v_cmp_gt_u32_e64 s[88:89], v84, v10
	v_cndmask_b32_e64 v109, 0, 1, vcc
	v_addc_co_u32_e64 v23, vcc, v23, v109, s[12:13]
	v_cmp_gt_u32_e32 vcc, v99, v10
	v_cmp_gt_u32_e64 s[86:87], v81, v10
	v_cmp_gt_u32_e64 s[84:85], v78, v10
	v_cndmask_b32_e64 v108, 0, 1, vcc
	v_addc_co_u32_e64 v23, vcc, v23, v108, s[96:97]
	v_cmp_gt_u32_e32 vcc, v96, v10
	v_cmp_gt_u32_e64 s[82:83], v76, v10
	v_cmp_gt_u32_e64 s[80:81], v60, v10
	v_cndmask_b32_e64 v107, 0, 1, vcc
	v_addc_co_u32_e64 v23, vcc, v23, v107, s[94:95]
	v_cmp_gt_u32_e32 vcc, v93, v10
	v_cmp_gt_u32_e64 s[78:79], v57, v10
	v_cmp_gt_u32_e64 s[76:77], v54, v10
	v_cndmask_b32_e64 v106, 0, 1, vcc
	v_addc_co_u32_e64 v23, vcc, v23, v106, s[92:93]
	v_cmp_gt_u32_e32 vcc, v90, v10
	v_cmp_gt_u32_e64 s[74:75], v51, v10
	v_cmp_gt_u32_e64 s[72:73], v48, v10
	v_cndmask_b32_e64 v105, 0, 1, vcc
	v_addc_co_u32_e64 v23, vcc, v23, v105, s[90:91]
	v_cmp_gt_u32_e32 vcc, v85, v10
	v_cmp_gt_u32_e64 s[70:71], v45, v10
	v_cmp_gt_u32_e64 s[68:69], v42, v10
	v_cndmask_b32_e64 v104, 0, 1, vcc
	v_addc_co_u32_e64 v23, vcc, v23, v104, s[88:89]
	v_cmp_gt_u32_e32 vcc, v83, v10
	v_cmp_gt_u32_e64 s[66:67], v39, v10
	v_cmp_gt_u32_e64 s[64:65], v36, v10
	v_cndmask_b32_e64 v103, 0, 1, vcc
	v_addc_co_u32_e64 v23, vcc, v23, v103, s[86:87]
	v_cmp_gt_u32_e32 vcc, v80, v10
	v_cmp_gt_u32_e64 s[62:63], v33, v10
	v_cmp_gt_u32_e64 s[60:61], v30, v10
	v_cndmask_b32_e64 v102, 0, 1, vcc
	v_addc_co_u32_e64 v23, vcc, v23, v102, s[84:85]
	v_cmp_gt_u32_e32 vcc, v77, v10
	v_cmp_gt_u32_e64 s[58:59], v27, v10
	v_cmp_gt_u32_e64 s[56:57], v24, v10
	v_cndmask_b32_e64 v100, 0, 1, vcc
	v_addc_co_u32_e64 v23, vcc, v23, v100, s[82:83]
; __device__ __forceinline__ int half_sum_i(int v, int hf) { v = row16_sum_i(v); const int a = __builtin_amdgcn_readlane(v, 0) + __builtin_amdgcn_readlane(v, 16), b = __builtin_amdgcn_readlane(v, 32) + __builtin_amdgcn_readlane(v, 48); return hf ? b : a; }
; __device__ __forceinline__ void dsa_index_unit(const Ctx& c, int l, int b, int qb) {
;     ...
;         int cg = 0;
; #pragma unroll
;         for (int kt = 0; kt < 64; ++kt) cg += (key[kt] > T) ? 1 : 0;
;         cg = half_sum_i(cg, hf);
;         const int need = 256 - cg;
;         int eqbase = 0;
;         unsigned mw0 = 0u, mw1 = 0u;
;         const unsigned below = (1u << n) - 1u;
; #pragma unroll
;         for (int kt = 0; kt < 64; ++kt) {
;             const bool gt = key[kt] > T, eq = key[kt] == T;
;             const unsigned long long em = __ballot(eq);
;             const unsigned eh = hf ? (unsigned)(em >> 32) : (unsigned)em;
;             const bool take = gt || (eq && (eqbase + __popc(eh & below) < need));
;             eqbase += __popc(eh);
;             const unsigned long long sm = __ballot(take);
;             if (lane == kt) { mw0 = (unsigned)sm; mw1 = (unsigned)(sm >> 32); }
	v_cmp_gt_u32_e32 vcc, v61, v10
	v_cmp_gt_u32_e64 s[54:55], v21, v10
	v_cmp_gt_u32_e64 s[52:53], v19, v10
	v_cndmask_b32_e64 v97, 0, 1, vcc
	v_addc_co_u32_e64 v23, vcc, v23, v97, s[80:81]
	v_cmp_gt_u32_e32 vcc, v58, v10
	v_cmp_gt_u32_e64 s[50:51], v16, v10
	v_cmp_gt_u32_e64 s[48:49], v14, v10
	v_cndmask_b32_e64 v94, 0, 1, vcc
	v_addc_co_u32_e64 v23, vcc, v23, v94, s[78:79]
	v_cmp_gt_u32_e32 vcc, v55, v10
	v_cmp_gt_u32_e64 s[46:47], v12, v10
	v_cmp_gt_u32_e64 s[44:45], v1, v10
	v_cndmask_b32_e64 v91, 0, 1, vcc
	v_addc_co_u32_e64 v23, vcc, v23, v91, s[76:77]
	v_cmp_gt_u32_e32 vcc, v52, v10
	v_cndmask_b32_e64 v115, 0, 1, s[10:11]
	s_mov_b32 s19, 16
	v_cndmask_b32_e64 v88, 0, 1, vcc
	v_addc_co_u32_e64 v23, vcc, v23, v88, s[74:75]
	v_cmp_gt_u32_e32 vcc, v49, v10
	s_mov_b32 s11, s22
	s_nop 0
	v_cndmask_b32_e64 v82, 0, 1, vcc
	v_addc_co_u32_e64 v23, vcc, v23, v82, s[72:73]
	v_cmp_gt_u32_e32 vcc, v46, v10
	s_nop 1
	v_cndmask_b32_e64 v79, 0, 1, vcc
	v_addc_co_u32_e64 v23, vcc, v23, v79, s[70:71]
	v_cmp_gt_u32_e32 vcc, v43, v10
	s_nop 1
	v_cndmask_b32_e64 v67, 0, 1, vcc
	v_addc_co_u32_e64 v23, vcc, v23, v67, s[68:69]
	v_cmp_gt_u32_e32 vcc, v40, v10
	s_nop 1
	v_cndmask_b32_e64 v59, 0, 1, vcc
	v_addc_co_u32_e64 v23, vcc, v23, v59, s[66:67]
	v_cmp_gt_u32_e32 vcc, v38, v10
	s_nop 1
	v_cndmask_b32_e64 v56, 0, 1, vcc
	v_addc_co_u32_e64 v23, vcc, v23, v56, s[64:65]
	v_cmp_gt_u32_e32 vcc, v35, v10
	s_nop 1
	v_cndmask_b32_e64 v53, 0, 1, vcc
	v_addc_co_u32_e64 v23, vcc, v23, v53, s[62:63]
	v_cmp_gt_u32_e32 vcc, v32, v10
	s_nop 1
	v_cndmask_b32_e64 v50, 0, 1, vcc
	v_addc_co_u32_e64 v23, vcc, v23, v50, s[60:61]
	v_cmp_gt_u32_e32 vcc, v29, v10
	s_nop 1
	v_cndmask_b32_e64 v47, 0, 1, vcc
	v_addc_co_u32_e64 v23, vcc, v23, v47, s[58:59]
	v_cmp_gt_u32_e32 vcc, v26, v10
	s_nop 1
	v_cndmask_b32_e64 v44, 0, 1, vcc
	v_addc_co_u32_e64 v23, vcc, v23, v44, s[56:57]
	v_cmp_gt_u32_e32 vcc, v22, v10
	s_nop 1
	v_cndmask_b32_e64 v41, 0, 1, vcc
	v_addc_co_u32_e64 v23, vcc, v23, v41, s[54:55]
	v_cmp_gt_u32_e32 vcc, v20, v10
	s_nop 1
	v_cndmask_b32_e64 v37, 0, 1, vcc
	v_addc_co_u32_e64 v23, vcc, v23, v37, s[52:53]
	v_cmp_gt_u32_e32 vcc, v18, v10
	s_nop 1
	v_cndmask_b32_e64 v34, 0, 1, vcc
	v_addc_co_u32_e64 v23, vcc, v23, v34, s[50:51]
	v_cmp_gt_u32_e32 vcc, v15, v10
	s_nop 1
	v_cndmask_b32_e64 v31, 0, 1, vcc
	v_addc_co_u32_e64 v23, vcc, v23, v31, s[48:49]
	v_cmp_gt_u32_e32 vcc, v13, v10
	s_nop 1
	v_cndmask_b32_e64 v28, 0, 1, vcc
	v_addc_co_u32_e64 v23, vcc, v23, v28, s[46:47]
	v_cmp_gt_u32_e32 vcc, v11, v10
	s_nop 1
	v_cndmask_b32_e64 v25, 0, 1, vcc
	v_addc_co_u32_e64 v23, vcc, v23, v25, s[44:45]
	v_cmp_eq_u32_e32 vcc, v8, v10
	s_nop 0
	v_add_u32_dpp v23, v23, v23 quad_perm:[1,0,3,2] row_mask:0xf bank_mask:0xf bound_ctrl:1
	v_mov_b32_e32 v8, vcc_hi
	s_nop 0
	v_add_u32_dpp v23, v23, v23 quad_perm:[2,3,0,1] row_mask:0xf bank_mask:0xf bound_ctrl:1
	s_nop 1
	v_add_u32_dpp v23, v23, v23 row_half_mirror row_mask:0xf bank_mask:0xf bound_ctrl:1
	s_nop 1
	v_add_u32_dpp v23, v23, v23 row_mirror row_mask:0xf bank_mask:0xf bound_ctrl:1
	s_nop 0
	v_readlane_b32 s2, v23, 0
	v_readlane_b32 s3, v23, 16
	s_add_i32 s2, s3, s2
	v_readlane_b32 s3, v23, 32
	v_readlane_b32 s17, v23, 48
	s_add_i32 s3, s17, s3
	v_mov_b32_e32 v23, s3
	v_mov_b32_e32 v114, s2
	v_cndmask_b32_e64 v23, v23, v114, s[6:7]
	v_mov_b32_e32 v114, vcc_lo
	v_cndmask_b32_e64 v8, v8, v114, s[6:7]
	v_and_b32_e32 v114, v8, v87
	v_sub_u32_e32 v23, 0x100, v23
	v_bcnt_u32_b32 v114, v114, 0
	v_cmp_lt_u32_e64 s[2:3], v114, v23
	v_bcnt_u32_b32 v8, v8, 0
	s_ashr_i32 s17, s16, 31
	v_cndmask_b32_e64 v114, 0, 1, s[2:3]
	v_cndmask_b32_e32 v114, v115, v114, vcc
	v_and_b32_e32 v114, 1, v114
	v_cmp_ne_u32_e32 vcc, 0, v114
	v_readlane_b32 s2, v253, 37
	v_readlane_b32 s3, v253, 38
	v_mov_b32_e32 v114, vcc_lo
	v_mov_b32_e32 v115, vcc_hi
	v_cmp_eq_u32_e32 vcc, v9, v10
	v_cndmask_b32_e64 v114, 0, v114, s[2:3]
	v_cndmask_b32_e64 v115, 0, v115, s[2:3]
	v_mov_b32_e32 v9, vcc_hi
	v_mov_b32_e32 v116, vcc_lo
	v_cndmask_b32_e64 v9, v9, v116, s[6:7]
	v_and_b32_e32 v116, v9, v87
	v_bcnt_u32_b32 v116, v116, v8
	v_cmp_lt_u32_e64 s[2:3], v116, v23
	v_bcnt_u32_b32 v8, v9, v8
	s_nop 0
	v_cndmask_b32_e64 v116, 0, 1, s[2:3]
	v_cndmask_b32_e32 v113, v113, v116, vcc
	v_and_b32_e32 v9, 1, v113
	v_cmp_ne_u32_e32 vcc, 0, v9
	v_readlane_b32 s2, v253, 39
	v_readlane_b32 s3, v253, 40
	v_mov_b32_e32 v9, vcc_lo
	v_mov_b32_e32 v113, vcc_hi
	v_cmp_eq_u32_e32 vcc, v6, v10
	v_cndmask_b32_e64 v9, v114, v9, s[2:3]
	v_cndmask_b32_e64 v113, v115, v113, s[2:3]
	v_mov_b32_e32 v6, vcc_hi
	v_mov_b32_e32 v114, vcc_lo
	v_cndmask_b32_e64 v6, v6, v114, s[6:7]
	v_and_b32_e32 v114, v6, v87
	v_bcnt_u32_b32 v114, v114, v8
	v_cmp_lt_u32_e64 s[2:3], v114, v23
	v_bcnt_u32_b32 v6, v6, v8
	s_nop 0
	v_cndmask_b32_e64 v114, 0, 1, s[2:3]
	v_cndmask_b32_e32 v112, v112, v114, vcc
	v_and_b32_e32 v8, 1, v112
	v_cmp_ne_u32_e32 vcc, 0, v8
	v_readlane_b32 s2, v253, 41
	v_readlane_b32 s3, v253, 42
	v_mov_b32_e32 v8, vcc_lo
	s_nop 0
	v_cndmask_b32_e64 v8, v9, v8, s[2:3]
	v_mov_b32_e32 v9, vcc_hi
	v_cmp_eq_u32_e32 vcc, v7, v10
	v_cndmask_b32_e64 v9, v113, v9, s[2:3]
	v_cndmask_b32_e64 v113, 0, 1, s[8:9]
	v_mov_b32_e32 v7, vcc_hi
	v_mov_b32_e32 v112, vcc_lo
	v_cndmask_b32_e64 v7, v7, v112, s[6:7]
	v_and_b32_e32 v112, v7, v87
	v_bcnt_u32_b32 v112, v112, v6
	v_cmp_lt_u32_e64 s[2:3], v112, v23
	v_bcnt_u32_b32 v6, v7, v6
	s_nop 0
	v_cndmask_b32_e64 v112, 0, 1, s[2:3]
	v_cndmask_b32_e32 v112, v113, v112, vcc
	v_and_b32_e32 v7, 1, v112
	v_cmp_ne_u32_e32 vcc, 0, v7
	v_readlane_b32 s2, v253, 43
	v_readlane_b32 s3, v253, 44
	v_mov_b32_e32 v7, vcc_lo
	s_nop 0
	v_cndmask_b32_e64 v7, v8, v7, s[2:3]
	v_mov_b32_e32 v8, vcc_hi
; __device__ __forceinline__ void dsa_index_unit(const Ctx& c, int l, int b, int qb) {
;     ...
; #pragma unroll
;         for (int kt = 0; kt < 64; ++kt) {
;             const bool gt = key[kt] > T, eq = key[kt] == T;
;             const unsigned long long em = __ballot(eq);
;             const unsigned eh = hf ? (unsigned)(em >> 32) : (unsigned)em;
;             const bool take = gt || (eq && (eqbase + __popc(eh & below) < need));
;             eqbase += __popc(eh);
;             const unsigned long long sm = __ballot(take);
;             if (lane == kt) { mw0 = (unsigned)sm; mw1 = (unsigned)(sm >> 32); }
;         }
	v_cmp_eq_u32_e32 vcc, v4, v10
	v_cndmask_b32_e64 v8, v9, v8, s[2:3]
	s_nop 0
	v_mov_b32_e32 v4, vcc_hi
	v_mov_b32_e32 v9, vcc_lo
	v_cndmask_b32_e64 v4, v4, v9, s[6:7]
	v_and_b32_e32 v9, v4, v87
	v_bcnt_u32_b32 v9, v9, v6
	v_cmp_lt_u32_e64 s[2:3], v9, v23
	v_bcnt_u32_b32 v4, v4, v6
	s_nop 0
	v_cndmask_b32_e64 v9, 0, 1, s[2:3]
	v_cndmask_b32_e32 v9, v111, v9, vcc
	v_and_b32_e32 v6, 1, v9
	v_cmp_ne_u32_e32 vcc, 0, v6
	v_readlane_b32 s2, v253, 45
	v_readlane_b32 s3, v253, 46
	v_mov_b32_e32 v6, vcc_lo
	v_cndmask_b32_e64 v9, 0, 1, s[4:5]
	v_cndmask_b32_e64 v6, v7, v6, s[2:3]
	v_mov_b32_e32 v7, vcc_hi
	v_cmp_eq_u32_e32 vcc, v5, v10
	v_cndmask_b32_e64 v7, v8, v7, s[2:3]
	s_nop 0
	v_mov_b32_e32 v5, vcc_hi
	v_mov_b32_e32 v8, vcc_lo
	v_cndmask_b32_e64 v5, v5, v8, s[6:7]
	v_and_b32_e32 v8, v5, v87
	v_bcnt_u32_b32 v8, v8, v4
	v_cmp_lt_u32_e64 s[2:3], v8, v23
	v_bcnt_u32_b32 v4, v5, v4
	s_nop 0
	v_cndmask_b32_e64 v8, 0, 1, s[2:3]
	v_cndmask_b32_e32 v8, v9, v8, vcc
	v_and_b32_e32 v5, 1, v8
	v_cmp_ne_u32_e32 vcc, 0, v5
	v_readlane_b32 s2, v253, 47
	v_readlane_b32 s3, v253, 48
	v_mov_b32_e32 v5, vcc_lo
	s_nop 0
	v_cndmask_b32_e64 v5, v6, v5, s[2:3]
	v_mov_b32_e32 v6, vcc_hi
	v_cmp_eq_u32_e32 vcc, v2, v10
	v_cndmask_b32_e64 v6, v7, v6, s[2:3]
	s_nop 0
	v_mov_b32_e32 v2, vcc_hi
	v_mov_b32_e32 v7, vcc_lo
	v_cndmask_b32_e64 v2, v2, v7, s[6:7]
	v_and_b32_e32 v7, v2, v87
	v_bcnt_u32_b32 v7, v7, v4
	v_cmp_lt_u32_e64 s[2:3], v7, v23
	v_bcnt_u32_b32 v2, v2, v4
	s_nop 0
	v_cndmask_b32_e64 v7, 0, 1, s[2:3]
	v_cndmask_b32_e32 v7, v110, v7, vcc
	v_and_b32_e32 v4, 1, v7
	v_cmp_ne_u32_e32 vcc, 0, v4
	v_readlane_b32 s2, v253, 49
	v_readlane_b32 s3, v253, 50
	v_mov_b32_e32 v4, vcc_lo
	v_cndmask_b32_e64 v7, 0, 1, s[0:1]
	v_cndmask_b32_e64 v4, v5, v4, s[2:3]
	v_mov_b32_e32 v5, vcc_hi
	v_cmp_eq_u32_e32 vcc, v3, v10
	v_cndmask_b32_e64 v5, v6, v5, s[2:3]
	v_readlane_b32 s0, v253, 51
	v_mov_b32_e32 v3, vcc_hi
	v_mov_b32_e32 v6, vcc_lo
	v_cndmask_b32_e64 v3, v3, v6, s[6:7]
	v_and_b32_e32 v6, v3, v87
	v_bcnt_u32_b32 v6, v6, v2
	v_cmp_lt_u32_e64 s[2:3], v6, v23
	v_bcnt_u32_b32 v2, v3, v2
	v_readlane_b32 s1, v253, 52
	v_cndmask_b32_e64 v6, 0, 1, s[2:3]
	v_cndmask_b32_e32 v6, v7, v6, vcc
	v_and_b32_e32 v3, 1, v6
	v_cmp_ne_u32_e32 vcc, 0, v3
	v_cndmask_b32_e64 v6, 0, 1, s[12:13]
	v_readlane_b32 s2, v250, 8
	v_mov_b32_e32 v3, vcc_lo
	v_cndmask_b32_e64 v3, v4, v3, s[0:1]
	v_mov_b32_e32 v4, vcc_hi
	v_cmp_eq_u32_e32 vcc, v0, v10
	v_cndmask_b32_e64 v4, v5, v4, s[0:1]
	v_readlane_b32 s3, v250, 9
	v_mov_b32_e32 v0, vcc_hi
	v_mov_b32_e32 v5, vcc_lo
	v_cndmask_b32_e64 v0, v0, v5, s[6:7]
	v_and_b32_e32 v5, v0, v87
	v_bcnt_u32_b32 v5, v5, v2
	v_cmp_lt_u32_e64 s[0:1], v5, v23
	v_bcnt_u32_b32 v0, v0, v2
	s_nop 0
	v_cndmask_b32_e64 v5, 0, 1, s[0:1]
	v_cndmask_b32_e32 v5, v109, v5, vcc
	v_and_b32_e32 v2, 1, v5
	v_cmp_ne_u32_e32 vcc, 0, v2
	v_readlane_b32 s0, v253, 53
	v_readlane_b32 s1, v253, 54
	v_mov_b32_e32 v2, vcc_lo
	s_nop 0
	v_cndmask_b32_e64 v2, v3, v2, s[0:1]
	v_mov_b32_e32 v3, vcc_hi
	v_cmp_eq_u32_e32 vcc, v101, v10
	v_cndmask_b32_e64 v3, v4, v3, s[0:1]
	s_nop 0
	v_mov_b32_e32 v4, vcc_hi
	v_mov_b32_e32 v5, vcc_lo
	v_cndmask_b32_e64 v4, v4, v5, s[6:7]
	v_and_b32_e32 v5, v4, v87
	v_bcnt_u32_b32 v5, v5, v0
	v_cmp_lt_u32_e64 s[0:1], v5, v23
	v_bcnt_u32_b32 v0, v4, v0
	s_nop 0
	v_cndmask_b32_e64 v5, 0, 1, s[0:1]
	v_cndmask_b32_e32 v5, v6, v5, vcc
	v_and_b32_e32 v4, 1, v5
	v_cmp_ne_u32_e32 vcc, 0, v4
	v_readlane_b32 s0, v253, 55
	v_readlane_b32 s1, v253, 56
	v_mov_b32_e32 v4, vcc_lo
	v_cndmask_b32_e64 v6, 0, 1, s[96:97]
	v_cndmask_b32_e64 v2, v2, v4, s[0:1]
	v_mov_b32_e32 v4, vcc_hi
	v_cmp_eq_u32_e32 vcc, v99, v10
	v_cndmask_b32_e64 v3, v3, v4, s[0:1]
	s_nop 0
	v_mov_b32_e32 v4, vcc_hi
	v_mov_b32_e32 v5, vcc_lo
	v_cndmask_b32_e64 v4, v4, v5, s[6:7]
	v_and_b32_e32 v5, v4, v87
	v_bcnt_u32_b32 v5, v5, v0
	v_cmp_lt_u32_e64 s[0:1], v5, v23
	v_bcnt_u32_b32 v0, v4, v0
	s_nop 0
	v_cndmask_b32_e64 v5, 0, 1, s[0:1]
	v_cndmask_b32_e32 v5, v108, v5, vcc
	v_and_b32_e32 v4, 1, v5
	v_cmp_ne_u32_e32 vcc, 0, v4
	v_readlane_b32 s0, v253, 57
	v_readlane_b32 s1, v253, 58
	v_mov_b32_e32 v4, vcc_lo
	s_nop 0
	v_cndmask_b32_e64 v2, v2, v4, s[0:1]
	v_mov_b32_e32 v4, vcc_hi
	v_cmp_eq_u32_e32 vcc, v98, v10
	v_cndmask_b32_e64 v3, v3, v4, s[0:1]
	s_nop 0
	v_mov_b32_e32 v4, vcc_hi
	v_mov_b32_e32 v5, vcc_lo
	v_cndmask_b32_e64 v4, v4, v5, s[6:7]
	v_and_b32_e32 v5, v4, v87
	v_bcnt_u32_b32 v5, v5, v0
	v_cmp_lt_u32_e64 s[0:1], v5, v23
	v_bcnt_u32_b32 v0, v4, v0
	s_nop 0
	v_cndmask_b32_e64 v5, 0, 1, s[0:1]
	v_cndmask_b32_e32 v5, v6, v5, vcc
	v_and_b32_e32 v4, 1, v5
	v_cmp_ne_u32_e32 vcc, 0, v4
	v_readlane_b32 s0, v253, 59
	v_readlane_b32 s1, v253, 60
	v_mov_b32_e32 v4, vcc_lo
	v_cndmask_b32_e64 v6, 0, 1, s[94:95]
	v_cndmask_b32_e64 v2, v2, v4, s[0:1]
	v_mov_b32_e32 v4, vcc_hi
	v_cmp_eq_u32_e32 vcc, v96, v10
	v_cndmask_b32_e64 v3, v3, v4, s[0:1]
	s_nop 0
	v_mov_b32_e32 v4, vcc_hi
	v_mov_b32_e32 v5, vcc_lo
	v_cndmask_b32_e64 v4, v4, v5, s[6:7]
	v_and_b32_e32 v5, v4, v87
	v_bcnt_u32_b32 v5, v5, v0
	v_cmp_lt_u32_e64 s[0:1], v5, v23
	v_bcnt_u32_b32 v0, v4, v0
	s_nop 0
	v_cndmask_b32_e64 v5, 0, 1, s[0:1]
	v_cndmask_b32_e32 v5, v107, v5, vcc
	v_and_b32_e32 v4, 1, v5
	v_cmp_ne_u32_e32 vcc, 0, v4
	v_readlane_b32 s0, v253, 61
	v_readlane_b32 s1, v253, 62
	v_mov_b32_e32 v4, vcc_lo
	s_nop 0
	v_cndmask_b32_e64 v2, v2, v4, s[0:1]
	v_mov_b32_e32 v4, vcc_hi
	v_cmp_eq_u32_e32 vcc, v95, v10
	v_cndmask_b32_e64 v3, v3, v4, s[0:1]
	s_nop 0
	v_mov_b32_e32 v4, vcc_hi
	v_mov_b32_e32 v5, vcc_lo
	v_cndmask_b32_e64 v4, v4, v5, s[6:7]
	v_and_b32_e32 v5, v4, v87
	v_bcnt_u32_b32 v5, v5, v0
	v_cmp_lt_u32_e64 s[0:1], v5, v23
	v_bcnt_u32_b32 v0, v4, v0
	s_nop 0
; __device__ __forceinline__ void dsa_index_unit(const Ctx& c, int l, int b, int qb) {
;     ...
; #pragma unroll
;         for (int kt = 0; kt < 64; ++kt) {
;             const bool gt = key[kt] > T, eq = key[kt] == T;
;             const unsigned long long em = __ballot(eq);
;             const unsigned eh = hf ? (unsigned)(em >> 32) : (unsigned)em;
;             const bool take = gt || (eq && (eqbase + __popc(eh & below) < need));
;             eqbase += __popc(eh);
;             const unsigned long long sm = __ballot(take);
;             if (lane == kt) { mw0 = (unsigned)sm; mw1 = (unsigned)(sm >> 32); }
;         }
	v_cndmask_b32_e64 v5, 0, 1, s[0:1]
	v_cndmask_b32_e32 v5, v6, v5, vcc
	v_and_b32_e32 v4, 1, v5
	v_cmp_ne_u32_e32 vcc, 0, v4
	v_readlane_b32 s0, v253, 63
	v_readlane_b32 s1, v254, 0
	v_mov_b32_e32 v4, vcc_lo
	v_cndmask_b32_e64 v6, 0, 1, s[92:93]
	v_cndmask_b32_e64 v2, v2, v4, s[0:1]
	v_mov_b32_e32 v4, vcc_hi
	v_cmp_eq_u32_e32 vcc, v93, v10
	v_cndmask_b32_e64 v3, v3, v4, s[0:1]
	s_nop 0
	v_mov_b32_e32 v4, vcc_hi
	v_mov_b32_e32 v5, vcc_lo
	v_cndmask_b32_e64 v4, v4, v5, s[6:7]
	v_and_b32_e32 v5, v4, v87
	v_bcnt_u32_b32 v5, v5, v0
	v_cmp_lt_u32_e64 s[0:1], v5, v23
	v_bcnt_u32_b32 v0, v4, v0
	s_nop 0
	v_cndmask_b32_e64 v5, 0, 1, s[0:1]
	v_cndmask_b32_e32 v5, v106, v5, vcc
	v_and_b32_e32 v4, 1, v5
	v_cmp_ne_u32_e32 vcc, 0, v4
	v_readlane_b32 s0, v254, 1
	v_readlane_b32 s1, v254, 2
	v_mov_b32_e32 v4, vcc_lo
	s_nop 0
	v_cndmask_b32_e64 v2, v2, v4, s[0:1]
	v_mov_b32_e32 v4, vcc_hi
	v_cmp_eq_u32_e32 vcc, v92, v10
	v_cndmask_b32_e64 v3, v3, v4, s[0:1]
	s_nop 0
	v_mov_b32_e32 v4, vcc_hi
	v_mov_b32_e32 v5, vcc_lo
	v_cndmask_b32_e64 v4, v4, v5, s[6:7]
	v_and_b32_e32 v5, v4, v87
	v_bcnt_u32_b32 v5, v5, v0
	v_cmp_lt_u32_e64 s[0:1], v5, v23
	v_bcnt_u32_b32 v0, v4, v0
	s_nop 0
	v_cndmask_b32_e64 v5, 0, 1, s[0:1]
	v_cndmask_b32_e32 v5, v6, v5, vcc
	v_and_b32_e32 v4, 1, v5
	v_cmp_ne_u32_e32 vcc, 0, v4
	v_readlane_b32 s0, v254, 3
	v_readlane_b32 s1, v254, 4
	v_mov_b32_e32 v4, vcc_lo
	v_cndmask_b32_e64 v6, 0, 1, s[90:91]
	v_cndmask_b32_e64 v2, v2, v4, s[0:1]
	v_mov_b32_e32 v4, vcc_hi
	v_cmp_eq_u32_e32 vcc, v90, v10
	v_cndmask_b32_e64 v3, v3, v4, s[0:1]
	s_mov_b64 s[90:91], s[20:21]
	v_mov_b32_e32 v4, vcc_hi
	v_mov_b32_e32 v5, vcc_lo
	v_cndmask_b32_e64 v4, v4, v5, s[6:7]
	v_and_b32_e32 v5, v4, v87
	v_bcnt_u32_b32 v5, v5, v0
	v_cmp_lt_u32_e64 s[0:1], v5, v23
	v_bcnt_u32_b32 v0, v4, v0
	s_nop 0
	v_cndmask_b32_e64 v5, 0, 1, s[0:1]
	v_cndmask_b32_e32 v5, v105, v5, vcc
	v_and_b32_e32 v4, 1, v5
	v_cmp_ne_u32_e32 vcc, 0, v4
	v_readlane_b32 s0, v254, 5
	v_readlane_b32 s1, v254, 6
	v_mov_b32_e32 v4, vcc_lo
	s_nop 0
	v_cndmask_b32_e64 v2, v2, v4, s[0:1]
	v_mov_b32_e32 v4, vcc_hi
	v_cmp_eq_u32_e32 vcc, v89, v10
	v_cndmask_b32_e64 v3, v3, v4, s[0:1]
	s_nop 0
	v_mov_b32_e32 v4, vcc_hi
	v_mov_b32_e32 v5, vcc_lo
	v_cndmask_b32_e64 v4, v4, v5, s[6:7]
	v_and_b32_e32 v5, v4, v87
	v_bcnt_u32_b32 v5, v5, v0
	v_cmp_lt_u32_e64 s[0:1], v5, v23
	v_bcnt_u32_b32 v0, v4, v0
	s_nop 0
	v_cndmask_b32_e64 v5, 0, 1, s[0:1]
	v_cndmask_b32_e32 v5, v6, v5, vcc
	v_and_b32_e32 v4, 1, v5
	v_cmp_ne_u32_e32 vcc, 0, v4
	v_readlane_b32 s0, v254, 7
	v_readlane_b32 s1, v254, 8
	v_mov_b32_e32 v4, vcc_lo
	v_cndmask_b32_e64 v6, 0, 1, s[88:89]
	v_cndmask_b32_e64 v2, v2, v4, s[0:1]
	v_mov_b32_e32 v4, vcc_hi
	v_cmp_eq_u32_e32 vcc, v85, v10
	v_cndmask_b32_e64 v3, v3, v4, s[0:1]
	s_nop 0
	v_mov_b32_e32 v4, vcc_hi
	v_mov_b32_e32 v5, vcc_lo
	v_cndmask_b32_e64 v4, v4, v5, s[6:7]
	v_and_b32_e32 v5, v4, v87
	v_bcnt_u32_b32 v5, v5, v0
	v_cmp_lt_u32_e64 s[0:1], v5, v23
	v_bcnt_u32_b32 v0, v4, v0
	s_nop 0
	v_cndmask_b32_e64 v5, 0, 1, s[0:1]
	v_cndmask_b32_e32 v5, v104, v5, vcc
	v_and_b32_e32 v4, 1, v5
	v_cmp_ne_u32_e32 vcc, 0, v4
	v_readlane_b32 s0, v254, 9
	v_readlane_b32 s1, v254, 10
	v_mov_b32_e32 v4, vcc_lo
	s_nop 0
	v_cndmask_b32_e64 v2, v2, v4, s[0:1]
	v_mov_b32_e32 v4, vcc_hi
	v_cmp_eq_u32_e32 vcc, v84, v10
	v_cndmask_b32_e64 v3, v3, v4, s[0:1]
	s_nop 0
	v_mov_b32_e32 v4, vcc_hi
	v_mov_b32_e32 v5, vcc_lo
	v_cndmask_b32_e64 v4, v4, v5, s[6:7]
	v_and_b32_e32 v5, v4, v87
	v_bcnt_u32_b32 v5, v5, v0
	v_cmp_lt_u32_e64 s[0:1], v5, v23
	v_bcnt_u32_b32 v0, v4, v0
	s_nop 0
	v_cndmask_b32_e64 v5, 0, 1, s[0:1]
	v_cndmask_b32_e32 v5, v6, v5, vcc
	v_and_b32_e32 v4, 1, v5
	v_cmp_ne_u32_e32 vcc, 0, v4
	v_readlane_b32 s0, v254, 11
	v_readlane_b32 s1, v254, 12
	v_mov_b32_e32 v4, vcc_lo
	v_cndmask_b32_e64 v6, 0, 1, s[86:87]
	v_cndmask_b32_e64 v2, v2, v4, s[0:1]
	v_mov_b32_e32 v4, vcc_hi
	v_cmp_eq_u32_e32 vcc, v83, v10
	v_cndmask_b32_e64 v3, v3, v4, s[0:1]
	s_nop 0
	v_mov_b32_e32 v4, vcc_hi
	v_mov_b32_e32 v5, vcc_lo
	v_cndmask_b32_e64 v4, v4, v5, s[6:7]
	v_and_b32_e32 v5, v4, v87
	v_bcnt_u32_b32 v5, v5, v0
	v_cmp_lt_u32_e64 s[0:1], v5, v23
	v_bcnt_u32_b32 v0, v4, v0
	s_nop 0
	v_cndmask_b32_e64 v5, 0, 1, s[0:1]
	v_cndmask_b32_e32 v5, v103, v5, vcc
	v_and_b32_e32 v4, 1, v5
	v_cmp_ne_u32_e32 vcc, 0, v4
	v_readlane_b32 s0, v254, 13
	v_readlane_b32 s1, v254, 14
	v_mov_b32_e32 v4, vcc_lo
	s_nop 0
	v_cndmask_b32_e64 v2, v2, v4, s[0:1]
	v_mov_b32_e32 v4, vcc_hi
	v_cmp_eq_u32_e32 vcc, v81, v10
	v_cndmask_b32_e64 v3, v3, v4, s[0:1]
	s_nop 0
	v_mov_b32_e32 v4, vcc_hi
	v_mov_b32_e32 v5, vcc_lo
	v_cndmask_b32_e64 v4, v4, v5, s[6:7]
	v_and_b32_e32 v5, v4, v87
	v_bcnt_u32_b32 v5, v5, v0
	v_cmp_lt_u32_e64 s[0:1], v5, v23
	v_bcnt_u32_b32 v0, v4, v0
	s_nop 0
	v_cndmask_b32_e64 v5, 0, 1, s[0:1]
	v_cndmask_b32_e32 v5, v6, v5, vcc
	v_and_b32_e32 v4, 1, v5
	v_cmp_ne_u32_e32 vcc, 0, v4
	v_readlane_b32 s0, v254, 15
	v_readlane_b32 s1, v254, 16
	v_mov_b32_e32 v4, vcc_lo
	v_cndmask_b32_e64 v6, 0, 1, s[84:85]
	v_cndmask_b32_e64 v2, v2, v4, s[0:1]
	v_mov_b32_e32 v4, vcc_hi
	v_cmp_eq_u32_e32 vcc, v80, v10
	v_cndmask_b32_e64 v3, v3, v4, s[0:1]
	s_nop 0
	v_mov_b32_e32 v4, vcc_hi
	v_mov_b32_e32 v5, vcc_lo
	v_cndmask_b32_e64 v4, v4, v5, s[6:7]
	v_and_b32_e32 v5, v4, v87
	v_bcnt_u32_b32 v5, v5, v0
	v_cmp_lt_u32_e64 s[0:1], v5, v23
	v_bcnt_u32_b32 v0, v4, v0
	s_nop 0
	v_cndmask_b32_e64 v5, 0, 1, s[0:1]
	v_cndmask_b32_e32 v5, v102, v5, vcc
	v_and_b32_e32 v4, 1, v5
	v_cmp_ne_u32_e32 vcc, 0, v4
	v_readlane_b32 s0, v254, 17
	v_readlane_b32 s1, v254, 18
	v_mov_b32_e32 v4, vcc_lo
	s_nop 0
	v_cndmask_b32_e64 v2, v2, v4, s[0:1]
	v_mov_b32_e32 v4, vcc_hi
	v_cmp_eq_u32_e32 vcc, v78, v10
; __device__ __forceinline__ void dsa_index_unit(const Ctx& c, int l, int b, int qb) {
;     ...
; #pragma unroll
;         for (int kt = 0; kt < 64; ++kt) {
;             const bool gt = key[kt] > T, eq = key[kt] == T;
;             const unsigned long long em = __ballot(eq);
;             const unsigned eh = hf ? (unsigned)(em >> 32) : (unsigned)em;
;             const bool take = gt || (eq && (eqbase + __popc(eh & below) < need));
;             eqbase += __popc(eh);
;             const unsigned long long sm = __ballot(take);
;             if (lane == kt) { mw0 = (unsigned)sm; mw1 = (unsigned)(sm >> 32); }
;         }
	v_cndmask_b32_e64 v3, v3, v4, s[0:1]
	s_nop 0
	v_mov_b32_e32 v4, vcc_hi
	v_mov_b32_e32 v5, vcc_lo
	v_cndmask_b32_e64 v4, v4, v5, s[6:7]
	v_and_b32_e32 v5, v4, v87
	v_bcnt_u32_b32 v5, v5, v0
	v_cmp_lt_u32_e64 s[0:1], v5, v23
	v_bcnt_u32_b32 v0, v4, v0
	s_nop 0
	v_cndmask_b32_e64 v5, 0, 1, s[0:1]
	v_cndmask_b32_e32 v5, v6, v5, vcc
	v_and_b32_e32 v4, 1, v5
	v_cmp_ne_u32_e32 vcc, 0, v4
	v_readlane_b32 s0, v254, 19
	v_readlane_b32 s1, v254, 20
	v_mov_b32_e32 v4, vcc_lo
	v_cndmask_b32_e64 v6, 0, 1, s[82:83]
	v_cndmask_b32_e64 v2, v2, v4, s[0:1]
	v_mov_b32_e32 v4, vcc_hi
	v_cmp_eq_u32_e32 vcc, v77, v10
	v_cndmask_b32_e64 v3, v3, v4, s[0:1]
	s_nop 0
	v_mov_b32_e32 v4, vcc_hi
	v_mov_b32_e32 v5, vcc_lo
	v_cndmask_b32_e64 v4, v4, v5, s[6:7]
	v_and_b32_e32 v5, v4, v87
	v_bcnt_u32_b32 v5, v5, v0
	v_cmp_lt_u32_e64 s[0:1], v5, v23
	v_bcnt_u32_b32 v0, v4, v0
	s_nop 0
	v_cndmask_b32_e64 v5, 0, 1, s[0:1]
	v_cndmask_b32_e32 v5, v100, v5, vcc
	v_and_b32_e32 v4, 1, v5
	v_cmp_ne_u32_e32 vcc, 0, v4
	v_readlane_b32 s0, v254, 21
	v_readlane_b32 s1, v254, 22
	v_mov_b32_e32 v4, vcc_lo
	s_nop 0
	v_cndmask_b32_e64 v2, v2, v4, s[0:1]
	v_mov_b32_e32 v4, vcc_hi
	v_cmp_eq_u32_e32 vcc, v76, v10
	v_cndmask_b32_e64 v3, v3, v4, s[0:1]
	s_nop 0
	v_mov_b32_e32 v4, vcc_hi
	v_mov_b32_e32 v5, vcc_lo
	v_cndmask_b32_e64 v4, v4, v5, s[6:7]
	v_and_b32_e32 v5, v4, v87
	v_bcnt_u32_b32 v5, v5, v0
	v_cmp_lt_u32_e64 s[0:1], v5, v23
	v_bcnt_u32_b32 v0, v4, v0
	s_nop 0
	v_cndmask_b32_e64 v5, 0, 1, s[0:1]
	v_cndmask_b32_e32 v5, v6, v5, vcc
	v_and_b32_e32 v4, 1, v5
	v_cmp_ne_u32_e32 vcc, 0, v4
	v_readlane_b32 s0, v254, 23
	v_readlane_b32 s1, v254, 24
	v_mov_b32_e32 v4, vcc_lo
	v_cndmask_b32_e64 v6, 0, 1, s[80:81]
	v_cndmask_b32_e64 v2, v2, v4, s[0:1]
	v_mov_b32_e32 v4, vcc_hi
	v_cmp_eq_u32_e32 vcc, v61, v10
	v_cndmask_b32_e64 v3, v3, v4, s[0:1]
	s_nop 0
	v_mov_b32_e32 v4, vcc_hi
	v_mov_b32_e32 v5, vcc_lo
	v_cndmask_b32_e64 v4, v4, v5, s[6:7]
	v_and_b32_e32 v5, v4, v87
	v_bcnt_u32_b32 v5, v5, v0
	v_cmp_lt_u32_e64 s[0:1], v5, v23
	v_bcnt_u32_b32 v0, v4, v0
	s_nop 0
	v_cndmask_b32_e64 v5, 0, 1, s[0:1]
	v_cndmask_b32_e32 v5, v97, v5, vcc
	v_and_b32_e32 v4, 1, v5
	v_cmp_ne_u32_e32 vcc, 0, v4
	v_readlane_b32 s0, v254, 25
	v_readlane_b32 s1, v254, 26
	v_mov_b32_e32 v4, vcc_lo
	s_nop 0
	v_cndmask_b32_e64 v2, v2, v4, s[0:1]
	v_mov_b32_e32 v4, vcc_hi
	v_cmp_eq_u32_e32 vcc, v60, v10
	v_cndmask_b32_e64 v3, v3, v4, s[0:1]
	s_nop 0
	v_mov_b32_e32 v4, vcc_hi
	v_mov_b32_e32 v5, vcc_lo
	v_cndmask_b32_e64 v4, v4, v5, s[6:7]
	v_and_b32_e32 v5, v4, v87
	v_bcnt_u32_b32 v5, v5, v0
	v_cmp_lt_u32_e64 s[0:1], v5, v23
	v_bcnt_u32_b32 v0, v4, v0
	s_nop 0
	v_cndmask_b32_e64 v5, 0, 1, s[0:1]
	v_cndmask_b32_e32 v5, v6, v5, vcc
	v_and_b32_e32 v4, 1, v5
	v_cmp_ne_u32_e32 vcc, 0, v4
	v_readlane_b32 s0, v254, 27
	v_readlane_b32 s1, v254, 28
	v_mov_b32_e32 v4, vcc_lo
	v_cndmask_b32_e64 v6, 0, 1, s[78:79]
	v_cndmask_b32_e64 v2, v2, v4, s[0:1]
	v_mov_b32_e32 v4, vcc_hi
	v_cmp_eq_u32_e32 vcc, v58, v10
	v_cndmask_b32_e64 v3, v3, v4, s[0:1]
	s_nop 0
	v_mov_b32_e32 v4, vcc_hi
	v_mov_b32_e32 v5, vcc_lo
	v_cndmask_b32_e64 v4, v4, v5, s[6:7]
	v_and_b32_e32 v5, v4, v87
	v_bcnt_u32_b32 v5, v5, v0
	v_cmp_lt_u32_e64 s[0:1], v5, v23
	v_bcnt_u32_b32 v0, v4, v0
	s_nop 0
	v_cndmask_b32_e64 v5, 0, 1, s[0:1]
	v_cndmask_b32_e32 v5, v94, v5, vcc
	v_and_b32_e32 v4, 1, v5
	v_cmp_ne_u32_e32 vcc, 0, v4
	v_readlane_b32 s0, v254, 29
	v_readlane_b32 s1, v254, 30
	v_mov_b32_e32 v4, vcc_lo
	s_nop 0
	v_cndmask_b32_e64 v2, v2, v4, s[0:1]
	v_mov_b32_e32 v4, vcc_hi
	v_cmp_eq_u32_e32 vcc, v57, v10
	v_cndmask_b32_e64 v3, v3, v4, s[0:1]
	s_nop 0
	v_mov_b32_e32 v4, vcc_hi
	v_mov_b32_e32 v5, vcc_lo
	v_cndmask_b32_e64 v4, v4, v5, s[6:7]
	v_and_b32_e32 v5, v4, v87
	v_bcnt_u32_b32 v5, v5, v0
	v_cmp_lt_u32_e64 s[0:1], v5, v23
	v_bcnt_u32_b32 v0, v4, v0
	s_nop 0
	v_cndmask_b32_e64 v5, 0, 1, s[0:1]
	v_cndmask_b32_e32 v5, v6, v5, vcc
	v_and_b32_e32 v4, 1, v5
	v_cmp_ne_u32_e32 vcc, 0, v4
	v_readlane_b32 s0, v254, 31
	v_readlane_b32 s1, v254, 32
	v_mov_b32_e32 v4, vcc_lo
	v_cndmask_b32_e64 v6, 0, 1, s[76:77]
	v_cndmask_b32_e64 v2, v2, v4, s[0:1]
	v_mov_b32_e32 v4, vcc_hi
	v_cmp_eq_u32_e32 vcc, v55, v10
	v_cndmask_b32_e64 v3, v3, v4, s[0:1]
	s_nop 0
	v_mov_b32_e32 v4, vcc_hi
	v_mov_b32_e32 v5, vcc_lo
	v_cndmask_b32_e64 v4, v4, v5, s[6:7]
	v_and_b32_e32 v5, v4, v87
	v_bcnt_u32_b32 v5, v5, v0
	v_cmp_lt_u32_e64 s[0:1], v5, v23
	v_bcnt_u32_b32 v0, v4, v0
	s_nop 0
	v_cndmask_b32_e64 v5, 0, 1, s[0:1]
	v_cndmask_b32_e32 v5, v91, v5, vcc
	v_and_b32_e32 v4, 1, v5
	v_cmp_ne_u32_e32 vcc, 0, v4
	v_readlane_b32 s0, v254, 33
	v_readlane_b32 s1, v254, 34
	v_mov_b32_e32 v4, vcc_lo
	s_nop 0
	v_cndmask_b32_e64 v2, v2, v4, s[0:1]
	v_mov_b32_e32 v4, vcc_hi
	v_cmp_eq_u32_e32 vcc, v54, v10
	v_cndmask_b32_e64 v3, v3, v4, s[0:1]
	s_nop 0
	v_mov_b32_e32 v4, vcc_hi
	v_mov_b32_e32 v5, vcc_lo
	v_cndmask_b32_e64 v4, v4, v5, s[6:7]
	v_and_b32_e32 v5, v4, v87
	v_bcnt_u32_b32 v5, v5, v0
	v_cmp_lt_u32_e64 s[0:1], v5, v23
	v_bcnt_u32_b32 v0, v4, v0
	s_nop 0
	v_cndmask_b32_e64 v5, 0, 1, s[0:1]
	v_cndmask_b32_e32 v5, v6, v5, vcc
	v_and_b32_e32 v4, 1, v5
	v_cmp_ne_u32_e32 vcc, 0, v4
	v_readlane_b32 s0, v254, 35
	v_readlane_b32 s1, v254, 36
	v_mov_b32_e32 v4, vcc_lo
	v_cndmask_b32_e64 v6, 0, 1, s[74:75]
	v_cndmask_b32_e64 v2, v2, v4, s[0:1]
	v_mov_b32_e32 v4, vcc_hi
	v_cmp_eq_u32_e32 vcc, v52, v10
	v_cndmask_b32_e64 v3, v3, v4, s[0:1]
	s_nop 0
	v_mov_b32_e32 v4, vcc_hi
	v_mov_b32_e32 v5, vcc_lo
	v_cndmask_b32_e64 v4, v4, v5, s[6:7]
	v_and_b32_e32 v5, v4, v87
	v_bcnt_u32_b32 v5, v5, v0
	v_cmp_lt_u32_e64 s[0:1], v5, v23
	v_bcnt_u32_b32 v0, v4, v0
	s_nop 0
	v_cndmask_b32_e64 v5, 0, 1, s[0:1]
; __device__ __forceinline__ void dsa_index_unit(const Ctx& c, int l, int b, int qb) {
;     ...
; #pragma unroll
;         for (int kt = 0; kt < 64; ++kt) {
;             const bool gt = key[kt] > T, eq = key[kt] == T;
;             const unsigned long long em = __ballot(eq);
;             const unsigned eh = hf ? (unsigned)(em >> 32) : (unsigned)em;
;             const bool take = gt || (eq && (eqbase + __popc(eh & below) < need));
;             eqbase += __popc(eh);
;             const unsigned long long sm = __ballot(take);
;             if (lane == kt) { mw0 = (unsigned)sm; mw1 = (unsigned)(sm >> 32); }
;         }
	v_cndmask_b32_e32 v5, v88, v5, vcc
	v_and_b32_e32 v4, 1, v5
	v_cmp_ne_u32_e32 vcc, 0, v4
	v_readlane_b32 s0, v254, 37
	v_readlane_b32 s1, v254, 38
	v_mov_b32_e32 v4, vcc_lo
	s_nop 0
	v_cndmask_b32_e64 v2, v2, v4, s[0:1]
	v_mov_b32_e32 v4, vcc_hi
	v_cmp_eq_u32_e32 vcc, v51, v10
	v_cndmask_b32_e64 v3, v3, v4, s[0:1]
	s_nop 0
	v_mov_b32_e32 v4, vcc_hi
	v_mov_b32_e32 v5, vcc_lo
	v_cndmask_b32_e64 v4, v4, v5, s[6:7]
	v_and_b32_e32 v5, v4, v87
	v_bcnt_u32_b32 v5, v5, v0
	v_cmp_lt_u32_e64 s[0:1], v5, v23
	v_bcnt_u32_b32 v0, v4, v0
	s_nop 0
	v_cndmask_b32_e64 v5, 0, 1, s[0:1]
	v_cndmask_b32_e32 v5, v6, v5, vcc
	v_and_b32_e32 v4, 1, v5
	v_cmp_ne_u32_e32 vcc, 0, v4
	v_readlane_b32 s0, v254, 39
	v_readlane_b32 s1, v254, 40
	v_mov_b32_e32 v4, vcc_lo
	v_cndmask_b32_e64 v6, 0, 1, s[72:73]
	v_cndmask_b32_e64 v2, v2, v4, s[0:1]
	v_mov_b32_e32 v4, vcc_hi
	v_cmp_eq_u32_e32 vcc, v49, v10
	v_cndmask_b32_e64 v3, v3, v4, s[0:1]
	s_nop 0
	v_mov_b32_e32 v4, vcc_hi
	v_mov_b32_e32 v5, vcc_lo
	v_cndmask_b32_e64 v4, v4, v5, s[6:7]
	v_and_b32_e32 v5, v4, v87
	v_bcnt_u32_b32 v5, v5, v0
	v_cmp_lt_u32_e64 s[0:1], v5, v23
	v_bcnt_u32_b32 v0, v4, v0
	s_nop 0
	v_cndmask_b32_e64 v5, 0, 1, s[0:1]
	v_cndmask_b32_e32 v5, v82, v5, vcc
	v_and_b32_e32 v4, 1, v5
	v_cmp_ne_u32_e32 vcc, 0, v4
	v_readlane_b32 s0, v254, 41
	v_readlane_b32 s1, v254, 42
	v_mov_b32_e32 v4, vcc_lo
	s_nop 0
	v_cndmask_b32_e64 v2, v2, v4, s[0:1]
	v_mov_b32_e32 v4, vcc_hi
	v_cmp_eq_u32_e32 vcc, v48, v10
	v_cndmask_b32_e64 v3, v3, v4, s[0:1]
	s_nop 0
	v_mov_b32_e32 v4, vcc_hi
	v_mov_b32_e32 v5, vcc_lo
	v_cndmask_b32_e64 v4, v4, v5, s[6:7]
	v_and_b32_e32 v5, v4, v87
	v_bcnt_u32_b32 v5, v5, v0
	v_cmp_lt_u32_e64 s[0:1], v5, v23
	v_bcnt_u32_b32 v0, v4, v0
	s_nop 0
	v_cndmask_b32_e64 v5, 0, 1, s[0:1]
	v_cndmask_b32_e32 v5, v6, v5, vcc
	v_and_b32_e32 v4, 1, v5
	v_cmp_ne_u32_e32 vcc, 0, v4
	v_readlane_b32 s0, v254, 43
	v_readlane_b32 s1, v254, 44
	v_mov_b32_e32 v4, vcc_lo
	v_cndmask_b32_e64 v6, 0, 1, s[70:71]
	v_cndmask_b32_e64 v2, v2, v4, s[0:1]
	v_mov_b32_e32 v4, vcc_hi
	v_cmp_eq_u32_e32 vcc, v46, v10
	v_cndmask_b32_e64 v3, v3, v4, s[0:1]
	s_nop 0
	v_mov_b32_e32 v4, vcc_hi
	v_mov_b32_e32 v5, vcc_lo
	v_cndmask_b32_e64 v4, v4, v5, s[6:7]
	v_and_b32_e32 v5, v4, v87
	v_bcnt_u32_b32 v5, v5, v0
	v_cmp_lt_u32_e64 s[0:1], v5, v23
	v_bcnt_u32_b32 v0, v4, v0
	s_nop 0
	v_cndmask_b32_e64 v5, 0, 1, s[0:1]
	v_cndmask_b32_e32 v5, v79, v5, vcc
	v_and_b32_e32 v4, 1, v5
	v_cmp_ne_u32_e32 vcc, 0, v4
	v_readlane_b32 s0, v254, 45
	v_readlane_b32 s1, v254, 46
	v_mov_b32_e32 v4, vcc_lo
	s_nop 0
	v_cndmask_b32_e64 v2, v2, v4, s[0:1]
	v_mov_b32_e32 v4, vcc_hi
	v_cmp_eq_u32_e32 vcc, v45, v10
	v_cndmask_b32_e64 v3, v3, v4, s[0:1]
	s_nop 0
	v_mov_b32_e32 v4, vcc_hi
	v_mov_b32_e32 v5, vcc_lo
	v_cndmask_b32_e64 v4, v4, v5, s[6:7]
	v_and_b32_e32 v5, v4, v87
	v_bcnt_u32_b32 v5, v5, v0
	v_cmp_lt_u32_e64 s[0:1], v5, v23
	v_bcnt_u32_b32 v0, v4, v0
	s_nop 0
	v_cndmask_b32_e64 v5, 0, 1, s[0:1]
	v_cndmask_b32_e32 v5, v6, v5, vcc
	v_and_b32_e32 v4, 1, v5
	v_cmp_ne_u32_e32 vcc, 0, v4
	v_readlane_b32 s0, v254, 47
	v_readlane_b32 s1, v254, 48
	v_mov_b32_e32 v4, vcc_lo
	v_cndmask_b32_e64 v6, 0, 1, s[68:69]
	v_cndmask_b32_e64 v2, v2, v4, s[0:1]
	v_mov_b32_e32 v4, vcc_hi
	v_cmp_eq_u32_e32 vcc, v43, v10
	v_cndmask_b32_e64 v3, v3, v4, s[0:1]
	s_mov_b32 s68, 0x3d000000
	v_mov_b32_e32 v4, vcc_hi
	v_mov_b32_e32 v5, vcc_lo
	v_cndmask_b32_e64 v4, v4, v5, s[6:7]
	v_and_b32_e32 v5, v4, v87
	v_bcnt_u32_b32 v5, v5, v0
	v_cmp_lt_u32_e64 s[0:1], v5, v23
	v_bcnt_u32_b32 v0, v4, v0
	s_nop 0
	v_cndmask_b32_e64 v5, 0, 1, s[0:1]
	v_cndmask_b32_e32 v5, v67, v5, vcc
	v_and_b32_e32 v4, 1, v5
	v_cmp_ne_u32_e32 vcc, 0, v4
	v_readlane_b32 s0, v254, 49
	v_readlane_b32 s1, v254, 50
	v_mov_b32_e32 v4, vcc_lo
	s_nop 0
	v_cndmask_b32_e64 v2, v2, v4, s[0:1]
	v_mov_b32_e32 v4, vcc_hi
	v_cmp_eq_u32_e32 vcc, v42, v10
	v_cndmask_b32_e64 v3, v3, v4, s[0:1]
	s_nop 0
	v_mov_b32_e32 v4, vcc_hi
	v_mov_b32_e32 v5, vcc_lo
	v_cndmask_b32_e64 v4, v4, v5, s[6:7]
	v_and_b32_e32 v5, v4, v87
	v_bcnt_u32_b32 v5, v5, v0
	v_cmp_lt_u32_e64 s[0:1], v5, v23
	v_bcnt_u32_b32 v0, v4, v0
	s_nop 0
	v_cndmask_b32_e64 v5, 0, 1, s[0:1]
	v_cndmask_b32_e32 v5, v6, v5, vcc
	v_and_b32_e32 v4, 1, v5
	v_cmp_ne_u32_e32 vcc, 0, v4
	v_readlane_b32 s0, v254, 51
	v_readlane_b32 s1, v254, 52
	v_mov_b32_e32 v4, vcc_lo
	v_cndmask_b32_e64 v6, 0, 1, s[66:67]
	v_cndmask_b32_e64 v2, v2, v4, s[0:1]
	v_mov_b32_e32 v4, vcc_hi
	v_cmp_eq_u32_e32 vcc, v40, v10
	v_cndmask_b32_e64 v3, v3, v4, s[0:1]
	s_nop 0
	v_mov_b32_e32 v4, vcc_hi
	v_mov_b32_e32 v5, vcc_lo
	v_cndmask_b32_e64 v4, v4, v5, s[6:7]
	v_and_b32_e32 v5, v4, v87
	v_bcnt_u32_b32 v5, v5, v0
	v_cmp_lt_u32_e64 s[0:1], v5, v23
	v_bcnt_u32_b32 v0, v4, v0
	s_nop 0
	v_cndmask_b32_e64 v5, 0, 1, s[0:1]
	v_cndmask_b32_e32 v5, v59, v5, vcc
	v_and_b32_e32 v4, 1, v5
	v_cmp_ne_u32_e32 vcc, 0, v4
	v_readlane_b32 s0, v254, 53
	v_readlane_b32 s1, v254, 54
	v_mov_b32_e32 v4, vcc_lo
	s_nop 0
	v_cndmask_b32_e64 v2, v2, v4, s[0:1]
	v_mov_b32_e32 v4, vcc_hi
	v_cmp_eq_u32_e32 vcc, v39, v10
	v_cndmask_b32_e64 v3, v3, v4, s[0:1]
	s_nop 0
	v_mov_b32_e32 v4, vcc_hi
	v_mov_b32_e32 v5, vcc_lo
	v_cndmask_b32_e64 v4, v4, v5, s[6:7]
	v_and_b32_e32 v5, v4, v87
	v_bcnt_u32_b32 v5, v5, v0
	v_cmp_lt_u32_e64 s[0:1], v5, v23
	v_bcnt_u32_b32 v0, v4, v0
	s_nop 0
	v_cndmask_b32_e64 v5, 0, 1, s[0:1]
	v_cndmask_b32_e32 v5, v6, v5, vcc
	v_and_b32_e32 v4, 1, v5
	v_cmp_ne_u32_e32 vcc, 0, v4
	v_readlane_b32 s0, v254, 55
	v_readlane_b32 s1, v254, 56
	v_mov_b32_e32 v4, vcc_lo
	v_cndmask_b32_e64 v6, 0, 1, s[64:65]
	v_cndmask_b32_e64 v2, v2, v4, s[0:1]
	v_mov_b32_e32 v4, vcc_hi
	v_cmp_eq_u32_e32 vcc, v38, v10
; __device__ __forceinline__ void dsa_index_unit(const Ctx& c, int l, int b, int qb) {
;     ...
; #pragma unroll
;         for (int kt = 0; kt < 64; ++kt) {
;             const bool gt = key[kt] > T, eq = key[kt] == T;
;             const unsigned long long em = __ballot(eq);
;             const unsigned eh = hf ? (unsigned)(em >> 32) : (unsigned)em;
;             const bool take = gt || (eq && (eqbase + __popc(eh & below) < need));
;             eqbase += __popc(eh);
;             const unsigned long long sm = __ballot(take);
;             if (lane == kt) { mw0 = (unsigned)sm; mw1 = (unsigned)(sm >> 32); }
;         }
	v_cndmask_b32_e64 v3, v3, v4, s[0:1]
	s_nop 0
	v_mov_b32_e32 v4, vcc_hi
	v_mov_b32_e32 v5, vcc_lo
	v_cndmask_b32_e64 v4, v4, v5, s[6:7]
	v_and_b32_e32 v5, v4, v87
	v_bcnt_u32_b32 v5, v5, v0
	v_cmp_lt_u32_e64 s[0:1], v5, v23
	v_bcnt_u32_b32 v0, v4, v0
	s_nop 0
	v_cndmask_b32_e64 v5, 0, 1, s[0:1]
	v_cndmask_b32_e32 v5, v56, v5, vcc
	v_and_b32_e32 v4, 1, v5
	v_cmp_ne_u32_e32 vcc, 0, v4
	v_readlane_b32 s0, v254, 57
	v_readlane_b32 s1, v254, 58
	v_mov_b32_e32 v4, vcc_lo
	s_nop 0
	v_cndmask_b32_e64 v2, v2, v4, s[0:1]
	v_mov_b32_e32 v4, vcc_hi
	v_cmp_eq_u32_e32 vcc, v36, v10
	v_cndmask_b32_e64 v3, v3, v4, s[0:1]
	s_nop 0
	v_mov_b32_e32 v4, vcc_hi
	v_mov_b32_e32 v5, vcc_lo
	v_cndmask_b32_e64 v4, v4, v5, s[6:7]
	v_and_b32_e32 v5, v4, v87
	v_bcnt_u32_b32 v5, v5, v0
	v_cmp_lt_u32_e64 s[0:1], v5, v23
	v_bcnt_u32_b32 v0, v4, v0
	s_nop 0
	v_cndmask_b32_e64 v5, 0, 1, s[0:1]
	v_cndmask_b32_e32 v5, v6, v5, vcc
	v_and_b32_e32 v4, 1, v5
	v_cmp_ne_u32_e32 vcc, 0, v4
	v_readlane_b32 s0, v254, 59
	v_readlane_b32 s1, v254, 60
	v_mov_b32_e32 v4, vcc_lo
	v_cndmask_b32_e64 v6, 0, 1, s[62:63]
	v_cndmask_b32_e64 v2, v2, v4, s[0:1]
	v_mov_b32_e32 v4, vcc_hi
	v_cmp_eq_u32_e32 vcc, v35, v10
	v_cndmask_b32_e64 v3, v3, v4, s[0:1]
	s_nop 0
	v_mov_b32_e32 v4, vcc_hi
	v_mov_b32_e32 v5, vcc_lo
	v_cndmask_b32_e64 v4, v4, v5, s[6:7]
	v_and_b32_e32 v5, v4, v87
	v_bcnt_u32_b32 v5, v5, v0
	v_cmp_lt_u32_e64 s[0:1], v5, v23
	v_bcnt_u32_b32 v0, v4, v0
	s_nop 0
	v_cndmask_b32_e64 v5, 0, 1, s[0:1]
	v_cndmask_b32_e32 v5, v53, v5, vcc
	v_and_b32_e32 v4, 1, v5
	v_cmp_ne_u32_e32 vcc, 0, v4
	v_readlane_b32 s0, v254, 61
	v_readlane_b32 s1, v254, 62
	v_mov_b32_e32 v4, vcc_lo
	s_nop 0
	v_cndmask_b32_e64 v2, v2, v4, s[0:1]
	v_mov_b32_e32 v4, vcc_hi
	v_cmp_eq_u32_e32 vcc, v33, v10
	v_cndmask_b32_e64 v3, v3, v4, s[0:1]
	s_nop 0
	v_mov_b32_e32 v4, vcc_hi
	v_mov_b32_e32 v5, vcc_lo
	v_cndmask_b32_e64 v4, v4, v5, s[6:7]
	v_and_b32_e32 v5, v4, v87
	v_bcnt_u32_b32 v5, v5, v0
	v_cmp_lt_u32_e64 s[0:1], v5, v23
	v_bcnt_u32_b32 v0, v4, v0
	s_nop 0
	v_cndmask_b32_e64 v5, 0, 1, s[0:1]
	v_cndmask_b32_e32 v5, v6, v5, vcc
	v_and_b32_e32 v4, 1, v5
	v_cmp_ne_u32_e32 vcc, 0, v4
	v_readlane_b32 s0, v254, 63
	v_readlane_b32 s1, v255, 0
	v_mov_b32_e32 v4, vcc_lo
	v_cndmask_b32_e64 v6, 0, 1, s[60:61]
	v_cndmask_b32_e64 v2, v2, v4, s[0:1]
	v_mov_b32_e32 v4, vcc_hi
	v_cmp_eq_u32_e32 vcc, v32, v10
	v_cndmask_b32_e64 v3, v3, v4, s[0:1]
	s_nop 0
	v_mov_b32_e32 v4, vcc_hi
	v_mov_b32_e32 v5, vcc_lo
	v_cndmask_b32_e64 v4, v4, v5, s[6:7]
	v_and_b32_e32 v5, v4, v87
	v_bcnt_u32_b32 v5, v5, v0
	v_cmp_lt_u32_e64 s[0:1], v5, v23
	v_bcnt_u32_b32 v0, v4, v0
	s_nop 0
	v_cndmask_b32_e64 v5, 0, 1, s[0:1]
	v_cndmask_b32_e32 v5, v50, v5, vcc
	v_and_b32_e32 v4, 1, v5
	v_cmp_ne_u32_e32 vcc, 0, v4
	v_readlane_b32 s0, v255, 1
	v_readlane_b32 s1, v255, 2
	v_mov_b32_e32 v4, vcc_lo
	s_nop 0
	v_cndmask_b32_e64 v2, v2, v4, s[0:1]
	v_mov_b32_e32 v4, vcc_hi
	v_cmp_eq_u32_e32 vcc, v30, v10
	v_cndmask_b32_e64 v3, v3, v4, s[0:1]
	s_nop 0
	v_mov_b32_e32 v4, vcc_hi
	v_mov_b32_e32 v5, vcc_lo
	v_cndmask_b32_e64 v4, v4, v5, s[6:7]
	v_and_b32_e32 v5, v4, v87
	v_bcnt_u32_b32 v5, v5, v0
	v_cmp_lt_u32_e64 s[0:1], v5, v23
	v_bcnt_u32_b32 v0, v4, v0
	s_nop 0
	v_cndmask_b32_e64 v5, 0, 1, s[0:1]
	v_cndmask_b32_e32 v5, v6, v5, vcc
	v_and_b32_e32 v4, 1, v5
	v_cmp_ne_u32_e32 vcc, 0, v4
	v_readlane_b32 s0, v255, 3
	v_readlane_b32 s1, v255, 4
	v_mov_b32_e32 v4, vcc_lo
	v_cndmask_b32_e64 v6, 0, 1, s[58:59]
	v_cndmask_b32_e64 v2, v2, v4, s[0:1]
	v_mov_b32_e32 v4, vcc_hi
	v_cmp_eq_u32_e32 vcc, v29, v10
	v_cndmask_b32_e64 v3, v3, v4, s[0:1]
	s_nop 0
	v_mov_b32_e32 v4, vcc_hi
	v_mov_b32_e32 v5, vcc_lo
	v_cndmask_b32_e64 v4, v4, v5, s[6:7]
	v_and_b32_e32 v5, v4, v87
	v_bcnt_u32_b32 v5, v5, v0
	v_cmp_lt_u32_e64 s[0:1], v5, v23
	v_bcnt_u32_b32 v0, v4, v0
	s_nop 0
	v_cndmask_b32_e64 v5, 0, 1, s[0:1]
	v_cndmask_b32_e32 v5, v47, v5, vcc
	v_and_b32_e32 v4, 1, v5
	v_cmp_ne_u32_e32 vcc, 0, v4
	v_readlane_b32 s0, v255, 5
	v_readlane_b32 s1, v255, 6
	v_mov_b32_e32 v4, vcc_lo
	s_nop 0
	v_cndmask_b32_e64 v2, v2, v4, s[0:1]
	v_mov_b32_e32 v4, vcc_hi
	v_cmp_eq_u32_e32 vcc, v27, v10
	v_cndmask_b32_e64 v3, v3, v4, s[0:1]
	s_nop 0
	v_mov_b32_e32 v4, vcc_hi
	v_mov_b32_e32 v5, vcc_lo
	v_cndmask_b32_e64 v4, v4, v5, s[6:7]
	v_and_b32_e32 v5, v4, v87
	v_bcnt_u32_b32 v5, v5, v0
	v_cmp_lt_u32_e64 s[0:1], v5, v23
	v_bcnt_u32_b32 v0, v4, v0
	s_nop 0
	v_cndmask_b32_e64 v5, 0, 1, s[0:1]
	v_cndmask_b32_e32 v5, v6, v5, vcc
	v_and_b32_e32 v4, 1, v5
	v_cmp_ne_u32_e32 vcc, 0, v4
	v_readlane_b32 s0, v255, 7
	v_readlane_b32 s1, v255, 8
	v_mov_b32_e32 v4, vcc_lo
	v_cndmask_b32_e64 v6, 0, 1, s[56:57]
	v_cndmask_b32_e64 v2, v2, v4, s[0:1]
	v_mov_b32_e32 v4, vcc_hi
	v_cmp_eq_u32_e32 vcc, v26, v10
	v_cndmask_b32_e64 v3, v3, v4, s[0:1]
	s_nop 0
	v_mov_b32_e32 v4, vcc_hi
	v_mov_b32_e32 v5, vcc_lo
	v_cndmask_b32_e64 v4, v4, v5, s[6:7]
	v_and_b32_e32 v5, v4, v87
	v_bcnt_u32_b32 v5, v5, v0
	v_cmp_lt_u32_e64 s[0:1], v5, v23
	v_bcnt_u32_b32 v0, v4, v0
	s_nop 0
	v_cndmask_b32_e64 v5, 0, 1, s[0:1]
	v_cndmask_b32_e32 v5, v44, v5, vcc
	v_and_b32_e32 v4, 1, v5
	v_cmp_ne_u32_e32 vcc, 0, v4
	v_readlane_b32 s0, v255, 9
	v_readlane_b32 s1, v255, 10
	v_mov_b32_e32 v4, vcc_lo
	s_nop 0
	v_cndmask_b32_e64 v2, v2, v4, s[0:1]
	v_mov_b32_e32 v4, vcc_hi
	v_cmp_eq_u32_e32 vcc, v24, v10
	v_cndmask_b32_e64 v3, v3, v4, s[0:1]
	s_nop 0
	v_mov_b32_e32 v4, vcc_hi
	v_mov_b32_e32 v5, vcc_lo
	v_cndmask_b32_e64 v4, v4, v5, s[6:7]
	v_and_b32_e32 v5, v4, v87
	v_bcnt_u32_b32 v5, v5, v0
	v_cmp_lt_u32_e64 s[0:1], v5, v23
	v_bcnt_u32_b32 v0, v4, v0
	s_nop 0
	v_cndmask_b32_e64 v5, 0, 1, s[0:1]
	v_cndmask_b32_e32 v5, v6, v5, vcc
	v_and_b32_e32 v4, 1, v5
; __device__ __forceinline__ void dsa_index_unit(const Ctx& c, int l, int b, int qb) {
;     ...
; #pragma unroll
;         for (int kt = 0; kt < 64; ++kt) {
;             const bool gt = key[kt] > T, eq = key[kt] == T;
;             const unsigned long long em = __ballot(eq);
;             const unsigned eh = hf ? (unsigned)(em >> 32) : (unsigned)em;
;             const bool take = gt || (eq && (eqbase + __popc(eh & below) < need));
;             eqbase += __popc(eh);
;             const unsigned long long sm = __ballot(take);
;             if (lane == kt) { mw0 = (unsigned)sm; mw1 = (unsigned)(sm >> 32); }
;         }
	v_cmp_ne_u32_e32 vcc, 0, v4
	v_readlane_b32 s0, v255, 11
	v_readlane_b32 s1, v255, 12
	v_mov_b32_e32 v4, vcc_lo
	v_cndmask_b32_e64 v6, 0, 1, s[54:55]
	v_cndmask_b32_e64 v2, v2, v4, s[0:1]
	v_mov_b32_e32 v4, vcc_hi
	v_cmp_eq_u32_e32 vcc, v22, v10
	v_cndmask_b32_e64 v3, v3, v4, s[0:1]
	s_nop 0
	v_mov_b32_e32 v4, vcc_hi
	v_mov_b32_e32 v5, vcc_lo
	v_cndmask_b32_e64 v4, v4, v5, s[6:7]
	v_and_b32_e32 v5, v4, v87
	v_bcnt_u32_b32 v5, v5, v0
	v_cmp_lt_u32_e64 s[0:1], v5, v23
	v_bcnt_u32_b32 v0, v4, v0
	s_nop 0
	v_cndmask_b32_e64 v5, 0, 1, s[0:1]
	v_cndmask_b32_e32 v5, v41, v5, vcc
	v_and_b32_e32 v4, 1, v5
	v_cmp_ne_u32_e32 vcc, 0, v4
	v_readlane_b32 s0, v255, 13
	v_readlane_b32 s1, v255, 14
	v_mov_b32_e32 v4, vcc_lo
	s_nop 0
	v_cndmask_b32_e64 v2, v2, v4, s[0:1]
	v_mov_b32_e32 v4, vcc_hi
	v_cmp_eq_u32_e32 vcc, v21, v10
	v_cndmask_b32_e64 v3, v3, v4, s[0:1]
	s_nop 0
	v_mov_b32_e32 v4, vcc_hi
	v_mov_b32_e32 v5, vcc_lo
	v_cndmask_b32_e64 v4, v4, v5, s[6:7]
	v_and_b32_e32 v5, v4, v87
	v_bcnt_u32_b32 v5, v5, v0
	v_cmp_lt_u32_e64 s[0:1], v5, v23
	v_bcnt_u32_b32 v0, v4, v0
	s_nop 0
	v_cndmask_b32_e64 v5, 0, 1, s[0:1]
	v_cndmask_b32_e32 v5, v6, v5, vcc
	v_and_b32_e32 v4, 1, v5
	v_cmp_ne_u32_e32 vcc, 0, v4
	v_readlane_b32 s0, v255, 15
	v_readlane_b32 s1, v255, 16
	v_mov_b32_e32 v4, vcc_lo
	v_cndmask_b32_e64 v6, 0, 1, s[52:53]
	v_cndmask_b32_e64 v2, v2, v4, s[0:1]
	v_mov_b32_e32 v4, vcc_hi
	v_cmp_eq_u32_e32 vcc, v20, v10
	v_cndmask_b32_e64 v3, v3, v4, s[0:1]
	s_nop 0
	v_mov_b32_e32 v4, vcc_hi
	v_mov_b32_e32 v5, vcc_lo
	v_cndmask_b32_e64 v4, v4, v5, s[6:7]
	v_and_b32_e32 v5, v4, v87
	v_bcnt_u32_b32 v5, v5, v0
	v_cmp_lt_u32_e64 s[0:1], v5, v23
	v_bcnt_u32_b32 v0, v4, v0
	s_nop 0
	v_cndmask_b32_e64 v5, 0, 1, s[0:1]
	v_cndmask_b32_e32 v5, v37, v5, vcc
	v_and_b32_e32 v4, 1, v5
	v_cmp_ne_u32_e32 vcc, 0, v4
	v_readlane_b32 s0, v255, 17
	v_readlane_b32 s1, v255, 18
	v_mov_b32_e32 v4, vcc_lo
	s_nop 0
	v_cndmask_b32_e64 v2, v2, v4, s[0:1]
	v_mov_b32_e32 v4, vcc_hi
	v_cmp_eq_u32_e32 vcc, v19, v10
	v_cndmask_b32_e64 v3, v3, v4, s[0:1]
	s_nop 0
	v_mov_b32_e32 v4, vcc_hi
	v_mov_b32_e32 v5, vcc_lo
	v_cndmask_b32_e64 v4, v4, v5, s[6:7]
	v_and_b32_e32 v5, v4, v87
	v_bcnt_u32_b32 v5, v5, v0
	v_cmp_lt_u32_e64 s[0:1], v5, v23
	v_bcnt_u32_b32 v0, v4, v0
	s_nop 0
	v_cndmask_b32_e64 v5, 0, 1, s[0:1]
	v_cndmask_b32_e32 v5, v6, v5, vcc
	v_and_b32_e32 v4, 1, v5
	v_cmp_ne_u32_e32 vcc, 0, v4
	v_cndmask_b32_e64 v6, 0, 1, s[50:51]
	s_nop 0
	v_mov_b32_e32 v4, vcc_lo
	v_cndmask_b32_e64 v2, v2, v4, s[24:25]
	v_mov_b32_e32 v4, vcc_hi
	v_cmp_eq_u32_e32 vcc, v18, v10
	v_cndmask_b32_e64 v3, v3, v4, s[24:25]
	s_nop 0
	v_mov_b32_e32 v4, vcc_hi
	v_mov_b32_e32 v5, vcc_lo
	v_cndmask_b32_e64 v4, v4, v5, s[6:7]
	v_and_b32_e32 v5, v4, v87
	v_bcnt_u32_b32 v5, v5, v0
	v_cmp_lt_u32_e64 s[0:1], v5, v23
	v_bcnt_u32_b32 v0, v4, v0
	s_nop 0
	v_cndmask_b32_e64 v5, 0, 1, s[0:1]
	v_cndmask_b32_e32 v5, v34, v5, vcc
	v_and_b32_e32 v4, 1, v5
	v_cmp_ne_u32_e32 vcc, 0, v4
	s_nop 1
	v_mov_b32_e32 v4, vcc_lo
	v_cndmask_b32_e64 v2, v2, v4, s[26:27]
	v_mov_b32_e32 v4, vcc_hi
	v_cmp_eq_u32_e32 vcc, v16, v10
	v_cndmask_b32_e64 v3, v3, v4, s[26:27]
	s_nop 0
	v_mov_b32_e32 v4, vcc_hi
	v_mov_b32_e32 v5, vcc_lo
	v_cndmask_b32_e64 v4, v4, v5, s[6:7]
	v_and_b32_e32 v5, v4, v87
	v_bcnt_u32_b32 v5, v5, v0
	v_cmp_lt_u32_e64 s[0:1], v5, v23
	v_bcnt_u32_b32 v0, v4, v0
	s_nop 0
	v_cndmask_b32_e64 v5, 0, 1, s[0:1]
	v_cndmask_b32_e32 v5, v6, v5, vcc
	v_and_b32_e32 v4, 1, v5
	v_cmp_ne_u32_e32 vcc, 0, v4
	v_cndmask_b32_e64 v6, 0, 1, s[48:49]
	s_nop 0
	v_mov_b32_e32 v4, vcc_lo
	v_cndmask_b32_e64 v2, v2, v4, s[28:29]
	v_mov_b32_e32 v4, vcc_hi
	v_cmp_eq_u32_e32 vcc, v15, v10
	v_cndmask_b32_e64 v3, v3, v4, s[28:29]
	s_nop 0
	v_mov_b32_e32 v4, vcc_hi
	v_mov_b32_e32 v5, vcc_lo
	v_cndmask_b32_e64 v4, v4, v5, s[6:7]
	v_and_b32_e32 v5, v4, v87
	v_bcnt_u32_b32 v5, v5, v0
	v_cmp_lt_u32_e64 s[0:1], v5, v23
	v_bcnt_u32_b32 v0, v4, v0
	s_nop 0
	v_cndmask_b32_e64 v5, 0, 1, s[0:1]
; __device__ __forceinline__ void dsa_index_unit(const Ctx& c, int l, int b, int qb) {
;     ...
; #pragma unroll
;         for (int kt = 0; kt < 64; ++kt) {
;             const bool gt = key[kt] > T, eq = key[kt] == T;
;             const unsigned long long em = __ballot(eq);
;             const unsigned eh = hf ? (unsigned)(em >> 32) : (unsigned)em;
;             const bool take = gt || (eq && (eqbase + __popc(eh & below) < need));
;             eqbase += __popc(eh);
;             const unsigned long long sm = __ballot(take);
;             if (lane == kt) { mw0 = (unsigned)sm; mw1 = (unsigned)(sm >> 32); }
;         }
;         MASKW[(size_t)(r0 + 2 * p) * 64 + lane] = mw0;
;         MASKW[(size_t)(r0 + 2 * p + 1) * 64 + lane] = mw1;
	v_cndmask_b32_e32 v5, v31, v5, vcc
	v_and_b32_e32 v4, 1, v5
	v_cmp_ne_u32_e32 vcc, 0, v4
	s_nop 1
	v_mov_b32_e32 v4, vcc_lo
	v_cndmask_b32_e64 v2, v2, v4, s[30:31]
	v_mov_b32_e32 v4, vcc_hi
	v_cmp_eq_u32_e32 vcc, v14, v10
	v_cndmask_b32_e64 v3, v3, v4, s[30:31]
	s_nop 0
	v_mov_b32_e32 v4, vcc_hi
	v_mov_b32_e32 v5, vcc_lo
	v_cndmask_b32_e64 v4, v4, v5, s[6:7]
	v_and_b32_e32 v5, v4, v87
	v_bcnt_u32_b32 v5, v5, v0
	v_cmp_lt_u32_e64 s[0:1], v5, v23
	v_bcnt_u32_b32 v0, v4, v0
	s_nop 0
	v_cndmask_b32_e64 v5, 0, 1, s[0:1]
	v_cndmask_b32_e32 v5, v6, v5, vcc
	v_and_b32_e32 v4, 1, v5
	v_cmp_ne_u32_e32 vcc, 0, v4
	v_cndmask_b32_e64 v6, 0, 1, s[46:47]
	s_nop 0
	v_mov_b32_e32 v4, vcc_lo
	v_cndmask_b32_e64 v2, v2, v4, s[34:35]
	v_mov_b32_e32 v4, vcc_hi
	v_cmp_eq_u32_e32 vcc, v13, v10
	v_cndmask_b32_e64 v3, v3, v4, s[34:35]
	s_nop 0
	v_mov_b32_e32 v4, vcc_hi
	v_mov_b32_e32 v5, vcc_lo
	v_cndmask_b32_e64 v4, v4, v5, s[6:7]
	v_and_b32_e32 v5, v4, v87
	v_bcnt_u32_b32 v5, v5, v0
	v_cmp_lt_u32_e64 s[0:1], v5, v23
	v_bcnt_u32_b32 v0, v4, v0
	s_nop 0
	v_cndmask_b32_e64 v5, 0, 1, s[0:1]
	v_cndmask_b32_e32 v5, v28, v5, vcc
	v_and_b32_e32 v4, 1, v5
	v_cmp_ne_u32_e32 vcc, 0, v4
	s_nop 1
	v_mov_b32_e32 v4, vcc_lo
	v_cndmask_b32_e64 v2, v2, v4, s[36:37]
	v_mov_b32_e32 v4, vcc_hi
	v_cmp_eq_u32_e32 vcc, v12, v10
	v_cndmask_b32_e64 v3, v3, v4, s[36:37]
	s_nop 0
	v_mov_b32_e32 v4, vcc_hi
	v_mov_b32_e32 v5, vcc_lo
	v_cndmask_b32_e64 v4, v4, v5, s[6:7]
	v_and_b32_e32 v5, v4, v87
	v_bcnt_u32_b32 v5, v5, v0
	v_cmp_lt_u32_e64 s[0:1], v5, v23
	v_bcnt_u32_b32 v0, v4, v0
	s_nop 0
	v_cndmask_b32_e64 v5, 0, 1, s[0:1]
	v_cndmask_b32_e32 v5, v6, v5, vcc
	v_and_b32_e32 v4, 1, v5
	v_cmp_ne_u32_e32 vcc, 0, v4
	s_nop 1
	v_mov_b32_e32 v4, vcc_lo
	v_cndmask_b32_e64 v2, v2, v4, s[38:39]
	v_mov_b32_e32 v4, vcc_hi
	v_cmp_eq_u32_e32 vcc, v11, v10
	v_cndmask_b32_e64 v3, v3, v4, s[38:39]
	s_nop 0
	v_mov_b32_e32 v4, vcc_hi
	v_mov_b32_e32 v5, vcc_lo
	v_cndmask_b32_e64 v4, v4, v5, s[6:7]
	v_and_b32_e32 v5, v4, v87
	v_bcnt_u32_b32 v5, v5, v0
	v_cmp_lt_u32_e64 s[0:1], v5, v23
	v_bcnt_u32_b32 v4, v4, 0
	s_nop 0
	v_cndmask_b32_e64 v5, 0, 1, s[0:1]
	v_cndmask_b32_e32 v5, v25, v5, vcc
	v_and_b32_e32 v5, 1, v5
	v_cmp_ne_u32_e32 vcc, 0, v5
	s_nop 1
	v_mov_b32_e32 v5, vcc_lo
	v_cndmask_b32_e64 v2, v2, v5, s[40:41]
	v_mov_b32_e32 v5, vcc_hi
	v_cmp_eq_u32_e32 vcc, v1, v10
	v_cndmask_b32_e64 v3, v3, v5, s[40:41]
	s_nop 0
	v_mov_b32_e32 v1, vcc_hi
	v_mov_b32_e32 v5, vcc_lo
	v_cndmask_b32_e64 v1, v1, v5, s[6:7]
	v_and_b32_e32 v1, v1, v87
	v_bcnt_u32_b32 v1, v1, 0
	v_add3_u32 v0, v4, v0, v1
	v_cmp_lt_u32_e64 s[0:1], v0, v23
	v_cndmask_b32_e64 v1, 0, 1, s[44:45]
	s_nop 0
	v_cndmask_b32_e64 v0, 0, 1, s[0:1]
	v_cndmask_b32_e32 v0, v1, v0, vcc
	v_and_b32_e32 v0, 1, v0
	v_cmp_ne_u32_e32 vcc, 0, v0
	s_lshl_b64 s[0:1], s[16:17], 8
	s_nop 0
	v_mov_b32_e32 v0, vcc_lo
	v_cndmask_b32_e64 v4, v2, v0, s[42:43]
	v_mov_b32_e32 v0, vcc_hi
	v_cndmask_b32_e64 v2, v3, v0, s[42:43]
	v_lshl_add_u64 v[0:1], v[74:75], 0, s[0:1]
	s_or_b32 s0, s16, 1
	s_ashr_i32 s1, s0, 31
	s_lshl_b64 s[0:1], s[0:1], 8
	global_store_dword v[0:1], v4, off
	v_lshl_add_u64 v[0:1], v[74:75], 0, s[0:1]
	s_mov_b64 s[0:1], 0
	s_and_b64 vcc, exec, s[2:3]
	global_store_dword v[0:1], v2, off
	s_cbranch_vccz .LBB0_2629
	v_readlane_b32 s28, v250, 12
	v_readlane_b32 s29, v250, 13
	v_readlane_b32 s30, v252, 9
	v_readlane_b32 s8, v252, 15
	s_mov_b64 s[2:3], 0
	v_readlane_b32 s39, v250, 7
	v_readlane_b32 s26, v252, 8
	v_readlane_b32 s31, v252, 10
	v_readlane_b32 s27, v252, 11
	v_readlane_b32 s34, v252, 12
	s_mov_b32 s35, 0x12000
	s_mov_b32 s40, 0x800000
	s_mov_b32 s37, 0x41a00000
	s_mov_b32 s38, 0x3fb8aa3b
	s_mov_b32 s42, 0xc2ce8ed0
	s_mov_b32 s43, 0x42b17218
	s_mov_b32 s36, 0xbfb8aa3b
	s_mov_b32 s41, 0x42ce8ed0
	s_mov_b32 s29, 0xc2b17218
	s_mov_b32 s19, 0x10100
	s_mov_b64 s[22:23], 0x1000
	v_readlane_b32 s18, v252, 13
	v_readlane_b32 s10, v252, 14
	v_readlane_b32 s9, v252, 16
